# BM selected attention with K and V double-buffered across union blocks, list entry prefetch, larger free-register map
# speedup vs baseline: 1.0621x; 1.0073x over previous
.LBB0_1549:
.LBB0_1550:
	v_readfirstlane_b32 s46, v70
	v_readfirstlane_b32 s47, v71
	v_readfirstlane_b32 s62, v72
	v_readfirstlane_b32 s63, v73
	v_and_b32_e32 v248, 15, v181
	v_lshrrev_b32_e32 v249, 4, v181
	v_lshrrev_b32_e32 v248, 2, v248
	v_lshlrev_b32_e32 v249, 2, v249
	v_readlane_b32 s23, v243, 32
	v_mov_b32_e32 v244, 1
	v_lshlrev_b32_e32 v244, v248, v244
	s_mov_b32 s16, 0x3e38aa3b
	s_mov_b32 s17, 0x3e38aa3b
	v_lshlrev_b32_e32 v79, 4, v181
	s_add_i32 s23, s23, s97
	v_add_u32_e32 v247, s23, v248
	v_mad_u64_u32 v[250:251], s[50:51], v247, v212, v[68:69]
	global_load_dwordx4 v[100:103], v[250:251], off
	global_load_dwordx4 v[104:107], v[250:251], off offset:64
	v_add_u32_e32 v249, 4, v247
	v_mad_u64_u32 v[250:251], s[50:51], v249, v212, v[68:69]
	global_load_dwordx4 v[108:111], v[250:251], off
	global_load_dwordx4 v[112:115], v[250:251], off offset:64
	v_add_u32_e32 v249, 8, v247
	v_mad_u64_u32 v[250:251], s[50:51], v249, v212, v[68:69]
	global_load_dwordx4 v[116:119], v[250:251], off
	global_load_dwordx4 v[120:123], v[250:251], off offset:64
	v_add_u32_e32 v249, 12, v247
	v_mad_u64_u32 v[250:251], s[50:51], v249, v212, v[68:69]
	global_load_dwordx4 v[124:127], v[250:251], off
	global_load_dwordx4 v[128:131], v[250:251], off offset:64
	v_and_b32_e32 v248, 15, v181
	v_lshrrev_b32_e32 v249, 4, v181
	v_lshlrev_b32_e32 v198, 6, v248
	v_lshl_add_u32 v198, v249, 2, v198
	v_add_u32_e32 v198, s96, v198
	v_lshl_add_u32 v199, v248, 2, s96
	ds_read_b32 v12, v198 offset:16384
	ds_read_b32 v13, v198 offset:16400
	ds_read_b32 v14, v198 offset:16416
	ds_read_b32 v15, v198 offset:16432
	ds_read_b32 v16, v199 offset:17408
	v_lshl_add_u32 v199, v181, 2, s96
	v_mov_b32_e32 v17, 1
	v_lshlrev_b32_e32 v17, v248, v17
	s_waitcnt lgkmcnt(0)
	v_mul_f32_e32 v81, 0x3fb8aa3b, v81
	ds_write_b32 v199, v11 offset:16384
	ds_write_b32 v199, v11 offset:16640
	ds_write_b32 v199, v11 offset:16896
	ds_write_b32 v199, v11 offset:17152
	v_cmp_lt_i32_e32 vcc, v249, v16
	v_and_b32_e32 v12, 0xff, v12
	v_lshl_add_u32 v12, v12, 2, s96
	v_cndmask_b32_e32 v18, 0, v17, vcc
	ds_or_b32 v12, v18 offset:16384
	v_add_u32_e32 v18, 4, v249
	v_cmp_lt_i32_e32 vcc, v18, v16
	v_and_b32_e32 v13, 0xff, v13
	v_lshl_add_u32 v13, v13, 2, s96
	v_cndmask_b32_e32 v18, 0, v17, vcc
	ds_or_b32 v13, v18 offset:16384
	v_add_u32_e32 v18, 8, v249
	v_cmp_lt_i32_e32 vcc, v18, v16
	v_and_b32_e32 v14, 0xff, v14
	v_lshl_add_u32 v14, v14, 2, s96
	v_cndmask_b32_e32 v18, 0, v17, vcc
	ds_or_b32 v14, v18 offset:16384
	v_add_u32_e32 v18, 12, v249
	v_cmp_lt_i32_e32 vcc, v18, v16
	v_and_b32_e32 v15, 0xff, v15
	v_lshl_add_u32 v15, v15, 2, s96
	v_cndmask_b32_e32 v18, 0, v17, vcc
	ds_or_b32 v15, v18 offset:16384
	s_waitcnt lgkmcnt(0)
	ds_read_b32 v12, v199 offset:16384
	ds_read_b32 v13, v199 offset:16640
	ds_read_b32 v14, v199 offset:16896
	ds_read_b32 v15, v199 offset:17152
	s_mov_b32 s25, 0
	s_waitcnt lgkmcnt(0)
	v_cmp_ne_u32_e64 s[4:5], 0, v12
	v_lshlrev_b32_e32 v16, 16, v12
	v_add_u32_e32 v17, 0, v181
	v_or_b32_e32 v16, v16, v17
	v_mbcnt_lo_u32_b32 v17, s4, 0
	v_mbcnt_hi_u32_b32 v17, s5, v17
	v_add_u32_e32 v17, s25, v17
	v_lshl_add_u32 v17, v17, 2, s96
	v_add_u32_e32 v17, 0x4000, v17
	v_add_u32_e32 v18, 0x4400, v199
	s_bcnt1_i32_b64 s13, s[4:5]
	v_cndmask_b32_e64 v17, v18, v17, s[4:5]
	s_add_i32 s25, s25, s13
	ds_write_b32 v17, v16
	v_cmp_ne_u32_e64 s[4:5], 0, v13
	v_lshlrev_b32_e32 v16, 16, v13
	v_add_u32_e32 v17, 64, v181
	v_or_b32_e32 v16, v16, v17
	v_mbcnt_lo_u32_b32 v17, s4, 0
	v_mbcnt_hi_u32_b32 v17, s5, v17
	v_add_u32_e32 v17, s25, v17
	v_lshl_add_u32 v17, v17, 2, s96
	v_add_u32_e32 v17, 0x4000, v17
	v_add_u32_e32 v18, 0x4400, v199
	s_bcnt1_i32_b64 s13, s[4:5]
	v_cndmask_b32_e64 v17, v18, v17, s[4:5]
	s_add_i32 s25, s25, s13
	ds_write_b32 v17, v16
	v_cmp_ne_u32_e64 s[4:5], 0, v14
	v_lshlrev_b32_e32 v16, 16, v14
	v_add_u32_e32 v17, 128, v181
	v_or_b32_e32 v16, v16, v17
	v_mbcnt_lo_u32_b32 v17, s4, 0
	v_mbcnt_hi_u32_b32 v17, s5, v17
	v_add_u32_e32 v17, s25, v17
	v_lshl_add_u32 v17, v17, 2, s96
	v_add_u32_e32 v17, 0x4000, v17
	v_add_u32_e32 v18, 0x4400, v199
	s_bcnt1_i32_b64 s13, s[4:5]
	v_cndmask_b32_e64 v17, v18, v17, s[4:5]
	s_add_i32 s25, s25, s13
	ds_write_b32 v17, v16
	v_cmp_ne_u32_e64 s[4:5], 0, v15
	v_lshlrev_b32_e32 v16, 16, v15
	v_add_u32_e32 v17, 192, v181
	v_or_b32_e32 v16, v16, v17
	v_mbcnt_lo_u32_b32 v17, s4, 0
	v_mbcnt_hi_u32_b32 v17, s5, v17
	v_add_u32_e32 v17, s25, v17
	v_lshl_add_u32 v17, v17, 2, s96
	v_add_u32_e32 v17, 0x4000, v17
	v_add_u32_e32 v18, 0x4400, v199
	s_bcnt1_i32_b64 s13, s[4:5]
	v_cndmask_b32_e64 v17, v18, v17, s[4:5]
	s_add_i32 s25, s25, s13
	ds_write_b32 v17, v16
	s_waitcnt vmcnt(0)
	v_lshlrev_b32_e32 v245, 16, v100
	v_and_b32_e32 v246, 0xffff0000, v100
	v_mul_f32_e32 v245, 0x41000000, v245
	v_mul_f32_e32 v246, 0x41000000, v246
	v_lshlrev_b32_e32 v248, 16, v101
	v_and_b32_e32 v249, 0xffff0000, v101
	v_cvt_pk_fp8_f32 v164, v245, v246
	v_mul_f32_e32 v248, 0x41000000, v248
	v_mul_f32_e32 v249, 0x41000000, v249
	s_nop 0
	v_cvt_pk_fp8_f32 v164, v248, v249 op_sel:[0,0,1]
	v_lshlrev_b32_e32 v245, 16, v102
	v_and_b32_e32 v246, 0xffff0000, v102
	v_mul_f32_e32 v245, 0x41000000, v245
	v_mul_f32_e32 v246, 0x41000000, v246
	v_lshlrev_b32_e32 v248, 16, v103
	v_and_b32_e32 v249, 0xffff0000, v103
	v_cvt_pk_fp8_f32 v165, v245, v246
	v_mul_f32_e32 v248, 0x41000000, v248
	v_mul_f32_e32 v249, 0x41000000, v249
	s_nop 0
	v_cvt_pk_fp8_f32 v165, v248, v249 op_sel:[0,0,1]
	v_lshlrev_b32_e32 v245, 16, v104
	v_and_b32_e32 v246, 0xffff0000, v104
	v_mul_f32_e32 v245, 0x41000000, v245
	v_mul_f32_e32 v246, 0x41000000, v246
	v_lshlrev_b32_e32 v248, 16, v105
	v_and_b32_e32 v249, 0xffff0000, v105
	v_cvt_pk_fp8_f32 v166, v245, v246
	v_mul_f32_e32 v248, 0x41000000, v248
	v_mul_f32_e32 v249, 0x41000000, v249
	s_nop 0
	v_cvt_pk_fp8_f32 v166, v248, v249 op_sel:[0,0,1]
	v_lshlrev_b32_e32 v245, 16, v106
	v_and_b32_e32 v246, 0xffff0000, v106
	v_mul_f32_e32 v245, 0x41000000, v245
	v_mul_f32_e32 v246, 0x41000000, v246
	v_lshlrev_b32_e32 v248, 16, v107
	v_and_b32_e32 v249, 0xffff0000, v107
	v_cvt_pk_fp8_f32 v167, v245, v246
	v_mul_f32_e32 v248, 0x41000000, v248
	v_mul_f32_e32 v249, 0x41000000, v249
	s_nop 0
	v_cvt_pk_fp8_f32 v167, v248, v249 op_sel:[0,0,1]
	v_lshlrev_b32_e32 v245, 16, v108
	v_and_b32_e32 v246, 0xffff0000, v108
	v_mul_f32_e32 v245, 0x41000000, v245
	v_mul_f32_e32 v246, 0x41000000, v246
	v_lshlrev_b32_e32 v248, 16, v109
	v_and_b32_e32 v249, 0xffff0000, v109
	v_cvt_pk_fp8_f32 v168, v245, v246
	v_mul_f32_e32 v248, 0x41000000, v248
	v_mul_f32_e32 v249, 0x41000000, v249
	s_nop 0
	v_cvt_pk_fp8_f32 v168, v248, v249 op_sel:[0,0,1]
	v_lshlrev_b32_e32 v245, 16, v110
	v_and_b32_e32 v246, 0xffff0000, v110
	v_mul_f32_e32 v245, 0x41000000, v245
	v_mul_f32_e32 v246, 0x41000000, v246
	v_lshlrev_b32_e32 v248, 16, v111
	v_and_b32_e32 v249, 0xffff0000, v111
	v_cvt_pk_fp8_f32 v169, v245, v246
	v_mul_f32_e32 v248, 0x41000000, v248
	v_mul_f32_e32 v249, 0x41000000, v249
	s_nop 0
	v_cvt_pk_fp8_f32 v169, v248, v249 op_sel:[0,0,1]
	v_lshlrev_b32_e32 v245, 16, v112
	v_and_b32_e32 v246, 0xffff0000, v112
	v_mul_f32_e32 v245, 0x41000000, v245
	v_mul_f32_e32 v246, 0x41000000, v246
	v_lshlrev_b32_e32 v248, 16, v113
	v_and_b32_e32 v249, 0xffff0000, v113
	v_cvt_pk_fp8_f32 v170, v245, v246
	v_mul_f32_e32 v248, 0x41000000, v248
	v_mul_f32_e32 v249, 0x41000000, v249
	s_nop 0
	v_cvt_pk_fp8_f32 v170, v248, v249 op_sel:[0,0,1]
	v_lshlrev_b32_e32 v245, 16, v114
	v_and_b32_e32 v246, 0xffff0000, v114
	v_mul_f32_e32 v245, 0x41000000, v245
	v_mul_f32_e32 v246, 0x41000000, v246
	v_lshlrev_b32_e32 v248, 16, v115
	v_and_b32_e32 v249, 0xffff0000, v115
	v_cvt_pk_fp8_f32 v171, v245, v246
	v_mul_f32_e32 v248, 0x41000000, v248
	v_mul_f32_e32 v249, 0x41000000, v249
	s_nop 0
	v_cvt_pk_fp8_f32 v171, v248, v249 op_sel:[0,0,1]
	v_lshlrev_b32_e32 v245, 16, v116
	v_and_b32_e32 v246, 0xffff0000, v116
	v_mul_f32_e32 v245, 0x41000000, v245
	v_mul_f32_e32 v246, 0x41000000, v246
	v_lshlrev_b32_e32 v248, 16, v117
	v_and_b32_e32 v249, 0xffff0000, v117
	v_cvt_pk_fp8_f32 v182, v245, v246
	v_mul_f32_e32 v248, 0x41000000, v248
	v_mul_f32_e32 v249, 0x41000000, v249
	s_nop 0
	v_cvt_pk_fp8_f32 v182, v248, v249 op_sel:[0,0,1]
	v_lshlrev_b32_e32 v245, 16, v118
	v_and_b32_e32 v246, 0xffff0000, v118
	v_mul_f32_e32 v245, 0x41000000, v245
	v_mul_f32_e32 v246, 0x41000000, v246
	v_lshlrev_b32_e32 v248, 16, v119
	v_and_b32_e32 v249, 0xffff0000, v119
	v_cvt_pk_fp8_f32 v183, v245, v246
	v_mul_f32_e32 v248, 0x41000000, v248
	v_mul_f32_e32 v249, 0x41000000, v249
	s_nop 0
	v_cvt_pk_fp8_f32 v183, v248, v249 op_sel:[0,0,1]
	v_lshlrev_b32_e32 v245, 16, v120
	v_and_b32_e32 v246, 0xffff0000, v120
	v_mul_f32_e32 v245, 0x41000000, v245
	v_mul_f32_e32 v246, 0x41000000, v246
	v_lshlrev_b32_e32 v248, 16, v121
	v_and_b32_e32 v249, 0xffff0000, v121
	v_cvt_pk_fp8_f32 v184, v245, v246
	v_mul_f32_e32 v248, 0x41000000, v248
	v_mul_f32_e32 v249, 0x41000000, v249
	s_nop 0
	v_cvt_pk_fp8_f32 v184, v248, v249 op_sel:[0,0,1]
	v_lshlrev_b32_e32 v245, 16, v122
	v_and_b32_e32 v246, 0xffff0000, v122
	v_mul_f32_e32 v245, 0x41000000, v245
	v_mul_f32_e32 v246, 0x41000000, v246
	v_lshlrev_b32_e32 v248, 16, v123
	v_and_b32_e32 v249, 0xffff0000, v123
	v_cvt_pk_fp8_f32 v185, v245, v246
	v_mul_f32_e32 v248, 0x41000000, v248
	v_mul_f32_e32 v249, 0x41000000, v249
	s_nop 0
	v_cvt_pk_fp8_f32 v185, v248, v249 op_sel:[0,0,1]
	v_lshlrev_b32_e32 v245, 16, v124
	v_and_b32_e32 v246, 0xffff0000, v124
	v_mul_f32_e32 v245, 0x41000000, v245
	v_mul_f32_e32 v246, 0x41000000, v246
	v_lshlrev_b32_e32 v248, 16, v125
	v_and_b32_e32 v249, 0xffff0000, v125
	v_cvt_pk_fp8_f32 v186, v245, v246
	v_mul_f32_e32 v248, 0x41000000, v248
	v_mul_f32_e32 v249, 0x41000000, v249
	s_nop 0
	v_cvt_pk_fp8_f32 v186, v248, v249 op_sel:[0,0,1]
	v_lshlrev_b32_e32 v245, 16, v126
	v_and_b32_e32 v246, 0xffff0000, v126
	v_mul_f32_e32 v245, 0x41000000, v245
	v_mul_f32_e32 v246, 0x41000000, v246
	v_lshlrev_b32_e32 v248, 16, v127
	v_and_b32_e32 v249, 0xffff0000, v127
	v_cvt_pk_fp8_f32 v187, v245, v246
	v_mul_f32_e32 v248, 0x41000000, v248
	v_mul_f32_e32 v249, 0x41000000, v249
	s_nop 0
	v_cvt_pk_fp8_f32 v187, v248, v249 op_sel:[0,0,1]
	v_lshlrev_b32_e32 v245, 16, v128
	v_and_b32_e32 v246, 0xffff0000, v128
	v_mul_f32_e32 v245, 0x41000000, v245
	v_mul_f32_e32 v246, 0x41000000, v246
	v_lshlrev_b32_e32 v248, 16, v129
	v_and_b32_e32 v249, 0xffff0000, v129
	v_cvt_pk_fp8_f32 v188, v245, v246
	v_mul_f32_e32 v248, 0x41000000, v248
	v_mul_f32_e32 v249, 0x41000000, v249
	s_nop 0
	v_cvt_pk_fp8_f32 v188, v248, v249 op_sel:[0,0,1]
	v_lshlrev_b32_e32 v245, 16, v130
	v_and_b32_e32 v246, 0xffff0000, v130
	v_mul_f32_e32 v245, 0x41000000, v245
	v_mul_f32_e32 v246, 0x41000000, v246
	v_lshlrev_b32_e32 v248, 16, v131
	v_and_b32_e32 v249, 0xffff0000, v131
	v_cvt_pk_fp8_f32 v189, v245, v246
	v_mul_f32_e32 v248, 0x41000000, v248
	v_mul_f32_e32 v249, 0x41000000, v249
	s_nop 0
	v_cvt_pk_fp8_f32 v189, v248, v249 op_sel:[0,0,1]
	v_mov_b64_e32 v[100:101], 0
	v_mov_b64_e32 v[102:103], 0
	v_mov_b64_e32 v[104:105], 0
	v_mov_b64_e32 v[106:107], 0
	v_mov_b64_e32 v[108:109], 0
	v_mov_b64_e32 v[110:111], 0
	v_mov_b64_e32 v[112:113], 0
	v_mov_b64_e32 v[114:115], 0
	v_mov_b32_e32 v190, 0
	v_mov_b32_e32 v194, 0
	v_mov_b64_e32 v[116:117], 0
	v_mov_b64_e32 v[118:119], 0
	v_mov_b64_e32 v[120:121], 0
	v_mov_b64_e32 v[122:123], 0
	v_mov_b64_e32 v[124:125], 0
	v_mov_b64_e32 v[126:127], 0
	v_mov_b64_e32 v[128:129], 0
	v_mov_b64_e32 v[130:131], 0
	v_mov_b32_e32 v191, 0
	v_mov_b32_e32 v195, 0
	v_mov_b64_e32 v[132:133], 0
	v_mov_b64_e32 v[134:135], 0
	v_mov_b64_e32 v[136:137], 0
	v_mov_b64_e32 v[138:139], 0
	v_mov_b64_e32 v[140:141], 0
	v_mov_b64_e32 v[142:143], 0
	v_mov_b64_e32 v[144:145], 0
	v_mov_b64_e32 v[146:147], 0
	v_mov_b32_e32 v192, 0
	v_mov_b32_e32 v196, 0
	v_mov_b64_e32 v[148:149], 0
	v_mov_b64_e32 v[150:151], 0
	v_mov_b64_e32 v[152:153], 0
	v_mov_b64_e32 v[154:155], 0
	v_mov_b64_e32 v[156:157], 0
	v_mov_b64_e32 v[158:159], 0
	v_mov_b64_e32 v[160:161], 0
	v_mov_b64_e32 v[162:163], 0
	v_mov_b32_e32 v193, 0
	v_mov_b32_e32 v197, 0
	v_mov_b32_e32 v77, 0xff800000
	v_mov_b32_e32 v78, 0xff800000
	s_waitcnt lgkmcnt(0)
	s_mov_b32 s35, 0
	s_lshl_b32 s13, s35, 2
	s_add_i32 s13, s13, s96
	v_mov_b32_e32 v76, s13
	ds_read_b32 v76, v76 offset:16384
	s_add_i32 s14, s25, -1
	s_min_i32 s14, s14, 1
	s_waitcnt lgkmcnt(0)
	v_readfirstlane_b32 s13, v76
	s_and_b32 s54, s13, 0xffff
	s_lshr_b32 s48, s13, 16
	s_lshl_b32 s13, s14, 2
	s_add_i32 s13, s13, s96
	v_mov_b32_e32 v76, s13
	ds_read_b32 v76, v76 offset:16384
	s_lshl_b32 s12, s54, 12
	s_add_u32 s30, s46, s12
	s_addc_u32 s31, s47, 0
	global_load_dwordx4 v[2:5], v79, s[30:31]
	global_load_dwordx4 v[6:9], v79, s[30:31] offset:1024
	global_load_dwordx4 v[12:15], v79, s[30:31] offset:2048
	global_load_dwordx4 v[16:19], v79, s[30:31] offset:3072
	s_lshl_b32 s12, s54, 12
	s_add_u32 s30, s62, s12
	s_addc_u32 s31, s63, 0
	global_load_dwordx4 v[36:39], v79, s[30:31]
	global_load_dwordx4 v[40:43], v79, s[30:31] offset:1024
	global_load_dwordx4 v[44:47], v79, s[30:31] offset:2048
	global_load_dwordx4 v[48:51], v79, s[30:31] offset:3072
	s_waitcnt lgkmcnt(0)
	v_readfirstlane_b32 s13, v76
	s_and_b32 s15, s13, 0xffff
	s_lshr_b32 s27, s13, 16
.Lbm2_blkA:
	s_lshl_b32 s12, s15, 12
	s_add_u32 s30, s46, s12
	s_addc_u32 s31, s47, 0
	global_load_dwordx4 v[20:23], v79, s[30:31]
	global_load_dwordx4 v[24:27], v79, s[30:31] offset:1024
	global_load_dwordx4 v[28:31], v79, s[30:31] offset:2048
	global_load_dwordx4 v[32:35], v79, s[30:31] offset:3072
	s_lshl_b32 s12, s15, 12
	s_add_u32 s30, s62, s12
	s_addc_u32 s31, s63, 0
	global_load_dwordx4 v[52:55], v79, s[30:31]
	global_load_dwordx4 v[56:59], v79, s[30:31] offset:1024
	global_load_dwordx4 v[60:63], v79, s[30:31] offset:2048
	global_load_dwordx4 v[64:67], v79, s[30:31] offset:3072
	s_add_i32 s14, s35, 2
	s_add_i32 s13, s25, -1
	s_min_i32 s14, s14, s13
	s_lshl_b32 s13, s14, 2
	s_add_i32 s13, s13, s96
	v_mov_b32_e32 v76, s13
	ds_read_b32 v76, v76 offset:16384
	s_cmp_ge_i32 s54, s21
	s_cselect_b32 s14, 1, 0
	s_bfe_u32 s29, s48, 0x40000
	s_cmp_eq_u32 s29, 0
	s_cbranch_scc1 .Lbm2_Ag0_skip
	s_waitcnt vmcnt(12)
	v_mfma_f32_16x16x32_fp8_fp8 v[84:87], v[2:3], v[164:165], 0
	v_mfma_f32_16x16x32_fp8_fp8 v[88:91], v[6:7], v[164:165], 0
	v_mfma_f32_16x16x32_fp8_fp8 v[92:95], v[12:13], v[164:165], 0
	v_mfma_f32_16x16x32_fp8_fp8 v[96:99], v[16:17], v[164:165], 0
	v_mfma_f32_16x16x32_fp8_fp8 v[84:87], v[4:5], v[166:167], v[84:87]
	v_mfma_f32_16x16x32_fp8_fp8 v[88:91], v[8:9], v[166:167], v[88:91]
	v_mfma_f32_16x16x32_fp8_fp8 v[92:95], v[14:15], v[166:167], v[92:95]
	v_mfma_f32_16x16x32_fp8_fp8 v[96:99], v[18:19], v[166:167], v[96:99]
	v_and_b32_e32 v199, s29, v244
	s_cmp_eq_u32 s14, 1
	v_cmp_ne_u32_e32 vcc, 0, v199
	s_cbranch_scc1 .Lbm2_Ag0_near
	v_add_f32_e32 v200, v81, v190
	v_cndmask_b32_e32 v200, v77, v200, vcc
	v_pk_fma_f32 v[84:85], v[84:85], s[16:17], v[200:201] op_sel_hi:[1,1,0]
	v_pk_fma_f32 v[86:87], v[86:87], s[16:17], v[200:201] op_sel_hi:[1,1,0]
	v_pk_fma_f32 v[88:89], v[88:89], s[16:17], v[200:201] op_sel_hi:[1,1,0]
	v_pk_fma_f32 v[90:91], v[90:91], s[16:17], v[200:201] op_sel_hi:[1,1,0]
	v_pk_fma_f32 v[92:93], v[92:93], s[16:17], v[200:201] op_sel_hi:[1,1,0]
	v_pk_fma_f32 v[94:95], v[94:95], s[16:17], v[200:201] op_sel_hi:[1,1,0]
	v_pk_fma_f32 v[96:97], v[96:97], s[16:17], v[200:201] op_sel_hi:[1,1,0]
	v_pk_fma_f32 v[98:99], v[98:99], s[16:17], v[200:201] op_sel_hi:[1,1,0]
.Lbm2_Ag0_max:
	v_max3_f32 v198, v84, v85, v86
	v_max3_f32 v199, v87, v88, v89
	v_max3_f32 v198, v198, v90, v91
	v_max3_f32 v199, v199, v92, v93
	v_max3_f32 v198, v198, v94, v95
	v_max3_f32 v199, v199, v96, v97
	v_max3_f32 v198, v198, v98, v99
	v_max_f32_e32 v198, v198, v199
	v_mov_b32_e32 v199, v198
	s_nop 1
	v_permlane16_swap_b32_e32 v198, v199
	s_nop 0
	v_max_f32_e32 v198, v198, v199
	v_mov_b32_e32 v199, v198
	s_nop 1
	v_permlane32_swap_b32_e32 v198, v199
	s_nop 0
	v_max_f32_e32 v198, v198, v199
	v_cmp_gt_f32_e32 vcc, v198, v78
	s_cbranch_vccnz .Lbm2_Ag0_resc
.Lbm2_Ag0_exp:
	v_exp_f32_e32 v84, v84
	v_exp_f32_e32 v85, v85
	v_exp_f32_e32 v86, v86
	v_exp_f32_e32 v87, v87
	v_exp_f32_e32 v88, v88
	v_exp_f32_e32 v89, v89
	v_exp_f32_e32 v90, v90
	v_exp_f32_e32 v91, v91
	v_exp_f32_e32 v92, v92
	v_exp_f32_e32 v93, v93
	v_exp_f32_e32 v94, v94
	v_exp_f32_e32 v95, v95
	v_exp_f32_e32 v96, v96
	v_exp_f32_e32 v97, v97
	v_exp_f32_e32 v98, v98
	v_exp_f32_e32 v99, v99
	s_nop 0
	v_pk_add_f32 v[248:249], v[84:85], v[86:87]
	v_pk_add_f32 v[248:249], v[248:249], v[88:89]
	v_pk_add_f32 v[248:249], v[248:249], v[90:91]
	v_pk_add_f32 v[248:249], v[248:249], v[92:93]
	v_pk_add_f32 v[248:249], v[248:249], v[94:95]
	v_pk_add_f32 v[248:249], v[248:249], v[96:97]
	v_pk_add_f32 v[248:249], v[248:249], v[98:99]
	v_add_f32_e32 v248, v248, v249
	v_add_f32_e32 v194, v194, v248
	v_cvt_pk_fp8_f32 v84, v84, v85
	s_nop 0
	v_cvt_pk_fp8_f32 v84, v86, v87 op_sel:[0,0,1]
	v_cvt_pk_fp8_f32 v85, v88, v89
	s_nop 0
	v_cvt_pk_fp8_f32 v85, v90, v91 op_sel:[0,0,1]
	v_cvt_pk_fp8_f32 v86, v92, v93
	s_nop 0
	v_cvt_pk_fp8_f32 v86, v94, v95 op_sel:[0,0,1]
	v_cvt_pk_fp8_f32 v87, v96, v97
	s_nop 0
	v_cvt_pk_fp8_f32 v87, v98, v99 op_sel:[0,0,1]
	s_waitcnt vmcnt(8)
	s_nop 1
	v_mfma_f32_16x16x32_fp8_fp8 v[100:103], v[36:37], v[84:85], v[100:103]
	v_mfma_f32_16x16x32_fp8_fp8 v[104:107], v[38:39], v[84:85], v[104:107]
	v_mfma_f32_16x16x32_fp8_fp8 v[108:111], v[40:41], v[84:85], v[108:111]
	v_mfma_f32_16x16x32_fp8_fp8 v[112:115], v[42:43], v[84:85], v[112:115]
	v_mfma_f32_16x16x32_fp8_fp8 v[100:103], v[44:45], v[86:87], v[100:103]
	v_mfma_f32_16x16x32_fp8_fp8 v[104:107], v[46:47], v[86:87], v[104:107]
	v_mfma_f32_16x16x32_fp8_fp8 v[108:111], v[48:49], v[86:87], v[108:111]
	v_mfma_f32_16x16x32_fp8_fp8 v[112:115], v[50:51], v[86:87], v[112:115]
	s_branch .Lbm2_Ag0_skip
.Lbm2_Ag0_resc:
	v_max_f32_e32 v248, 0, v198
	v_max_f32_e32 v249, v198, v78
	v_exp_f32_e64 v248, -v248
	v_sub_f32_e32 v190, v190, v249
	v_sub_f32_e32 v84, v84, v249
	v_sub_f32_e32 v85, v85, v249
	v_sub_f32_e32 v86, v86, v249
	v_sub_f32_e32 v87, v87, v249
	v_sub_f32_e32 v88, v88, v249
	v_sub_f32_e32 v89, v89, v249
	v_sub_f32_e32 v90, v90, v249
	v_sub_f32_e32 v91, v91, v249
	v_sub_f32_e32 v92, v92, v249
	v_sub_f32_e32 v93, v93, v249
	v_sub_f32_e32 v94, v94, v249
	v_sub_f32_e32 v95, v95, v249
	v_sub_f32_e32 v96, v96, v249
	v_sub_f32_e32 v97, v97, v249
	v_sub_f32_e32 v98, v98, v249
	v_sub_f32_e32 v99, v99, v249
	v_mul_f32_e32 v194, v194, v248
	v_pk_mul_f32 v[100:101], v[100:101], v[248:249] op_sel_hi:[1,0]
	v_pk_mul_f32 v[102:103], v[102:103], v[248:249] op_sel_hi:[1,0]
	v_pk_mul_f32 v[104:105], v[104:105], v[248:249] op_sel_hi:[1,0]
	v_pk_mul_f32 v[106:107], v[106:107], v[248:249] op_sel_hi:[1,0]
	v_pk_mul_f32 v[108:109], v[108:109], v[248:249] op_sel_hi:[1,0]
	v_pk_mul_f32 v[110:111], v[110:111], v[248:249] op_sel_hi:[1,0]
	v_pk_mul_f32 v[112:113], v[112:113], v[248:249] op_sel_hi:[1,0]
	v_pk_mul_f32 v[114:115], v[114:115], v[248:249] op_sel_hi:[1,0]
	s_branch .Lbm2_Ag0_exp
.Lbm2_Ag0_near:
	s_lshl_b32 s13, s54, 6
	s_sub_i32 s13, s97, s13
	v_and_b32_e32 v245, 15, v181
	v_lshrrev_b32_e32 v246, 4, v181
	v_lshrrev_b32_e32 v245, 2, v245
	v_lshlrev_b32_e32 v246, 2, v246
	v_cndmask_b32_e32 v200, v77, v190, vcc
	v_sub_u32_e32 v245, v245, v246
	v_add_u32_e32 v198, s13, v245
	v_mov_b32_e32 v245, v198
	v_min_u32_e32 v248, 0x7f, v245
	v_lshl_add_u32 v248, v248, 2, v80
	ds_read_b32 v248, v248
	v_subrev_u32_e32 v246, 1, v198
	v_min_u32_e32 v249, 0x7f, v246
	v_lshl_add_u32 v249, v249, 2, v80
	ds_read_b32 v249, v249
	s_waitcnt lgkmcnt(0)
	v_fmamk_f32 v248, v248, 0x3fb8aa3b, v200
	v_cmp_le_i32_e32 vcc, 0, v245
	v_fmamk_f32 v84, v84, 0x3e38aa3b, v248
	s_nop 0
	v_cndmask_b32_e32 v84, v77, v84, vcc
	v_fmamk_f32 v249, v249, 0x3fb8aa3b, v200
	v_cmp_le_i32_e32 vcc, 0, v246
	v_fmamk_f32 v85, v85, 0x3e38aa3b, v249
	s_nop 0
	v_cndmask_b32_e32 v85, v77, v85, vcc
	v_subrev_u32_e32 v245, 2, v198
	v_min_u32_e32 v248, 0x7f, v245
	v_lshl_add_u32 v248, v248, 2, v80
	ds_read_b32 v248, v248
	v_subrev_u32_e32 v246, 3, v198
	v_min_u32_e32 v249, 0x7f, v246
	v_lshl_add_u32 v249, v249, 2, v80
	ds_read_b32 v249, v249
	s_waitcnt lgkmcnt(0)
	v_fmamk_f32 v248, v248, 0x3fb8aa3b, v200
	v_cmp_le_i32_e32 vcc, 0, v245
	v_fmamk_f32 v86, v86, 0x3e38aa3b, v248
	s_nop 0
	v_cndmask_b32_e32 v86, v77, v86, vcc
	v_fmamk_f32 v249, v249, 0x3fb8aa3b, v200
	v_cmp_le_i32_e32 vcc, 0, v246
	v_fmamk_f32 v87, v87, 0x3e38aa3b, v249
	s_nop 0
	v_cndmask_b32_e32 v87, v77, v87, vcc
	v_subrev_u32_e32 v245, 16, v198
	v_min_u32_e32 v248, 0x7f, v245
	v_lshl_add_u32 v248, v248, 2, v80
	ds_read_b32 v248, v248
	v_subrev_u32_e32 v246, 17, v198
	v_min_u32_e32 v249, 0x7f, v246
	v_lshl_add_u32 v249, v249, 2, v80
	ds_read_b32 v249, v249
	s_waitcnt lgkmcnt(0)
	v_fmamk_f32 v248, v248, 0x3fb8aa3b, v200
	v_cmp_le_i32_e32 vcc, 0, v245
	v_fmamk_f32 v88, v88, 0x3e38aa3b, v248
	s_nop 0
	v_cndmask_b32_e32 v88, v77, v88, vcc
	v_fmamk_f32 v249, v249, 0x3fb8aa3b, v200
	v_cmp_le_i32_e32 vcc, 0, v246
	v_fmamk_f32 v89, v89, 0x3e38aa3b, v249
	s_nop 0
	v_cndmask_b32_e32 v89, v77, v89, vcc
	v_subrev_u32_e32 v245, 18, v198
	v_min_u32_e32 v248, 0x7f, v245
	v_lshl_add_u32 v248, v248, 2, v80
	ds_read_b32 v248, v248
	v_subrev_u32_e32 v246, 19, v198
	v_min_u32_e32 v249, 0x7f, v246
	v_lshl_add_u32 v249, v249, 2, v80
	ds_read_b32 v249, v249
	s_waitcnt lgkmcnt(0)
	v_fmamk_f32 v248, v248, 0x3fb8aa3b, v200
	v_cmp_le_i32_e32 vcc, 0, v245
	v_fmamk_f32 v90, v90, 0x3e38aa3b, v248
	s_nop 0
	v_cndmask_b32_e32 v90, v77, v90, vcc
	v_fmamk_f32 v249, v249, 0x3fb8aa3b, v200
	v_cmp_le_i32_e32 vcc, 0, v246
	v_fmamk_f32 v91, v91, 0x3e38aa3b, v249
	s_nop 0
	v_cndmask_b32_e32 v91, v77, v91, vcc
	v_subrev_u32_e32 v245, 32, v198
	v_min_u32_e32 v248, 0x7f, v245
	v_lshl_add_u32 v248, v248, 2, v80
	ds_read_b32 v248, v248
	v_subrev_u32_e32 v246, 33, v198
	v_min_u32_e32 v249, 0x7f, v246
	v_lshl_add_u32 v249, v249, 2, v80
	ds_read_b32 v249, v249
	s_waitcnt lgkmcnt(0)
	v_fmamk_f32 v248, v248, 0x3fb8aa3b, v200
	v_cmp_le_i32_e32 vcc, 0, v245
	v_fmamk_f32 v92, v92, 0x3e38aa3b, v248
	s_nop 0
	v_cndmask_b32_e32 v92, v77, v92, vcc
	v_fmamk_f32 v249, v249, 0x3fb8aa3b, v200
	v_cmp_le_i32_e32 vcc, 0, v246
	v_fmamk_f32 v93, v93, 0x3e38aa3b, v249
	s_nop 0
	v_cndmask_b32_e32 v93, v77, v93, vcc
	v_subrev_u32_e32 v245, 34, v198
	v_min_u32_e32 v248, 0x7f, v245
	v_lshl_add_u32 v248, v248, 2, v80
	ds_read_b32 v248, v248
	v_subrev_u32_e32 v246, 35, v198
	v_min_u32_e32 v249, 0x7f, v246
	v_lshl_add_u32 v249, v249, 2, v80
	ds_read_b32 v249, v249
	s_waitcnt lgkmcnt(0)
	v_fmamk_f32 v248, v248, 0x3fb8aa3b, v200
	v_cmp_le_i32_e32 vcc, 0, v245
	v_fmamk_f32 v94, v94, 0x3e38aa3b, v248
	s_nop 0
	v_cndmask_b32_e32 v94, v77, v94, vcc
	v_fmamk_f32 v249, v249, 0x3fb8aa3b, v200
	v_cmp_le_i32_e32 vcc, 0, v246
	v_fmamk_f32 v95, v95, 0x3e38aa3b, v249
	s_nop 0
	v_cndmask_b32_e32 v95, v77, v95, vcc
	v_subrev_u32_e32 v245, 48, v198
	v_min_u32_e32 v248, 0x7f, v245
	v_lshl_add_u32 v248, v248, 2, v80
	ds_read_b32 v248, v248
	v_subrev_u32_e32 v246, 49, v198
	v_min_u32_e32 v249, 0x7f, v246
	v_lshl_add_u32 v249, v249, 2, v80
	ds_read_b32 v249, v249
	s_waitcnt lgkmcnt(0)
	v_fmamk_f32 v248, v248, 0x3fb8aa3b, v200
	v_cmp_le_i32_e32 vcc, 0, v245
	v_fmamk_f32 v96, v96, 0x3e38aa3b, v248
	s_nop 0
	v_cndmask_b32_e32 v96, v77, v96, vcc
	v_fmamk_f32 v249, v249, 0x3fb8aa3b, v200
	v_cmp_le_i32_e32 vcc, 0, v246
	v_fmamk_f32 v97, v97, 0x3e38aa3b, v249
	s_nop 0
	v_cndmask_b32_e32 v97, v77, v97, vcc
	v_subrev_u32_e32 v245, 50, v198
	v_min_u32_e32 v248, 0x7f, v245
	v_lshl_add_u32 v248, v248, 2, v80
	ds_read_b32 v248, v248
	v_subrev_u32_e32 v246, 51, v198
	v_min_u32_e32 v249, 0x7f, v246
	v_lshl_add_u32 v249, v249, 2, v80
	ds_read_b32 v249, v249
	s_waitcnt lgkmcnt(0)
	v_fmamk_f32 v248, v248, 0x3fb8aa3b, v200
	v_cmp_le_i32_e32 vcc, 0, v245
	v_fmamk_f32 v98, v98, 0x3e38aa3b, v248
	s_nop 0
	v_cndmask_b32_e32 v98, v77, v98, vcc
	v_fmamk_f32 v249, v249, 0x3fb8aa3b, v200
	v_cmp_le_i32_e32 vcc, 0, v246
	v_fmamk_f32 v99, v99, 0x3e38aa3b, v249
	s_nop 0
	v_cndmask_b32_e32 v99, v77, v99, vcc
	s_branch .Lbm2_Ag0_max
.Lbm2_Ag0_skip:
	s_bfe_u32 s29, s48, 0x40004
	s_cmp_eq_u32 s29, 0
	s_cbranch_scc1 .Lbm2_Ag1_skip
	s_waitcnt vmcnt(12)
	v_mfma_f32_16x16x32_fp8_fp8 v[84:87], v[2:3], v[168:169], 0
	v_mfma_f32_16x16x32_fp8_fp8 v[88:91], v[6:7], v[168:169], 0
	v_mfma_f32_16x16x32_fp8_fp8 v[92:95], v[12:13], v[168:169], 0
	v_mfma_f32_16x16x32_fp8_fp8 v[96:99], v[16:17], v[168:169], 0
	v_mfma_f32_16x16x32_fp8_fp8 v[84:87], v[4:5], v[170:171], v[84:87]
	v_mfma_f32_16x16x32_fp8_fp8 v[88:91], v[8:9], v[170:171], v[88:91]
	v_mfma_f32_16x16x32_fp8_fp8 v[92:95], v[14:15], v[170:171], v[92:95]
	v_mfma_f32_16x16x32_fp8_fp8 v[96:99], v[18:19], v[170:171], v[96:99]
	v_and_b32_e32 v199, s29, v244
	s_cmp_eq_u32 s14, 1
	v_cmp_ne_u32_e32 vcc, 0, v199
	s_cbranch_scc1 .Lbm2_Ag1_near
	v_add_f32_e32 v200, v81, v191
	v_cndmask_b32_e32 v200, v77, v200, vcc
	v_pk_fma_f32 v[84:85], v[84:85], s[16:17], v[200:201] op_sel_hi:[1,1,0]
	v_pk_fma_f32 v[86:87], v[86:87], s[16:17], v[200:201] op_sel_hi:[1,1,0]
	v_pk_fma_f32 v[88:89], v[88:89], s[16:17], v[200:201] op_sel_hi:[1,1,0]
	v_pk_fma_f32 v[90:91], v[90:91], s[16:17], v[200:201] op_sel_hi:[1,1,0]
	v_pk_fma_f32 v[92:93], v[92:93], s[16:17], v[200:201] op_sel_hi:[1,1,0]
	v_pk_fma_f32 v[94:95], v[94:95], s[16:17], v[200:201] op_sel_hi:[1,1,0]
	v_pk_fma_f32 v[96:97], v[96:97], s[16:17], v[200:201] op_sel_hi:[1,1,0]
	v_pk_fma_f32 v[98:99], v[98:99], s[16:17], v[200:201] op_sel_hi:[1,1,0]

.Lbm2_Ag1_exp:
	v_exp_f32_e32 v84, v84
	v_exp_f32_e32 v85, v85
	v_exp_f32_e32 v86, v86
	v_exp_f32_e32 v87, v87
	v_exp_f32_e32 v88, v88
	v_exp_f32_e32 v89, v89
	v_exp_f32_e32 v90, v90
	v_exp_f32_e32 v91, v91
	v_exp_f32_e32 v92, v92
	v_exp_f32_e32 v93, v93
	v_exp_f32_e32 v94, v94
	v_exp_f32_e32 v95, v95
	v_exp_f32_e32 v96, v96
	v_exp_f32_e32 v97, v97
	v_exp_f32_e32 v98, v98
	v_exp_f32_e32 v99, v99
	s_nop 0
	v_pk_add_f32 v[248:249], v[84:85], v[86:87]
	v_pk_add_f32 v[248:249], v[248:249], v[88:89]
	v_pk_add_f32 v[248:249], v[248:249], v[90:91]
	v_pk_add_f32 v[248:249], v[248:249], v[92:93]
	v_pk_add_f32 v[248:249], v[248:249], v[94:95]
	v_pk_add_f32 v[248:249], v[248:249], v[96:97]
	v_pk_add_f32 v[248:249], v[248:249], v[98:99]
	v_add_f32_e32 v248, v248, v249
	v_add_f32_e32 v195, v195, v248
	v_cvt_pk_fp8_f32 v84, v84, v85
	s_nop 0
	v_cvt_pk_fp8_f32 v84, v86, v87 op_sel:[0,0,1]
	v_cvt_pk_fp8_f32 v85, v88, v89
	s_nop 0
	v_cvt_pk_fp8_f32 v85, v90, v91 op_sel:[0,0,1]
	v_cvt_pk_fp8_f32 v86, v92, v93
	s_nop 0
	v_cvt_pk_fp8_f32 v86, v94, v95 op_sel:[0,0,1]
	v_cvt_pk_fp8_f32 v87, v96, v97
	s_nop 0
	v_cvt_pk_fp8_f32 v87, v98, v99 op_sel:[0,0,1]
	s_waitcnt vmcnt(8)
	s_nop 1
	v_mfma_f32_16x16x32_fp8_fp8 v[116:119], v[36:37], v[84:85], v[116:119]
	v_mfma_f32_16x16x32_fp8_fp8 v[120:123], v[38:39], v[84:85], v[120:123]
	v_mfma_f32_16x16x32_fp8_fp8 v[124:127], v[40:41], v[84:85], v[124:127]
	v_mfma_f32_16x16x32_fp8_fp8 v[128:131], v[42:43], v[84:85], v[128:131]
	v_mfma_f32_16x16x32_fp8_fp8 v[116:119], v[44:45], v[86:87], v[116:119]
	v_mfma_f32_16x16x32_fp8_fp8 v[120:123], v[46:47], v[86:87], v[120:123]
	v_mfma_f32_16x16x32_fp8_fp8 v[124:127], v[48:49], v[86:87], v[124:127]
	v_mfma_f32_16x16x32_fp8_fp8 v[128:131], v[50:51], v[86:87], v[128:131]
	s_branch .Lbm2_Ag1_skip
.Lbm2_Ag1_resc:
	v_max_f32_e32 v248, 0, v198
	v_max_f32_e32 v249, v198, v78
	v_exp_f32_e64 v248, -v248
	v_sub_f32_e32 v191, v191, v249
	v_sub_f32_e32 v84, v84, v249
	v_sub_f32_e32 v85, v85, v249
	v_sub_f32_e32 v86, v86, v249
	v_sub_f32_e32 v87, v87, v249
	v_sub_f32_e32 v88, v88, v249
	v_sub_f32_e32 v89, v89, v249
	v_sub_f32_e32 v90, v90, v249
	v_sub_f32_e32 v91, v91, v249
	v_sub_f32_e32 v92, v92, v249
	v_sub_f32_e32 v93, v93, v249
	v_sub_f32_e32 v94, v94, v249
	v_sub_f32_e32 v95, v95, v249
	v_sub_f32_e32 v96, v96, v249
	v_sub_f32_e32 v97, v97, v249
	v_sub_f32_e32 v98, v98, v249
	v_sub_f32_e32 v99, v99, v249
	v_mul_f32_e32 v195, v195, v248
	v_pk_mul_f32 v[116:117], v[116:117], v[248:249] op_sel_hi:[1,0]
	v_pk_mul_f32 v[118:119], v[118:119], v[248:249] op_sel_hi:[1,0]
	v_pk_mul_f32 v[120:121], v[120:121], v[248:249] op_sel_hi:[1,0]
	v_pk_mul_f32 v[122:123], v[122:123], v[248:249] op_sel_hi:[1,0]
	v_pk_mul_f32 v[124:125], v[124:125], v[248:249] op_sel_hi:[1,0]
	v_pk_mul_f32 v[126:127], v[126:127], v[248:249] op_sel_hi:[1,0]
	v_pk_mul_f32 v[128:129], v[128:129], v[248:249] op_sel_hi:[1,0]
	v_pk_mul_f32 v[130:131], v[130:131], v[248:249] op_sel_hi:[1,0]
	s_branch .Lbm2_Ag1_exp
.Lbm2_Ag1_near:
	s_lshl_b32 s13, s54, 6
	s_sub_i32 s13, s97, s13
	s_add_i32 s13, s13, 4
	v_and_b32_e32 v245, 15, v181
	v_lshrrev_b32_e32 v246, 4, v181
	v_lshrrev_b32_e32 v245, 2, v245
	v_lshlrev_b32_e32 v246, 2, v246
	v_cndmask_b32_e32 v200, v77, v191, vcc
	v_sub_u32_e32 v245, v245, v246
	v_add_u32_e32 v198, s13, v245
	v_mov_b32_e32 v245, v198
	v_min_u32_e32 v248, 0x7f, v245
	v_lshl_add_u32 v248, v248, 2, v80
	ds_read_b32 v248, v248
	v_subrev_u32_e32 v246, 1, v198
	v_min_u32_e32 v249, 0x7f, v246
	v_lshl_add_u32 v249, v249, 2, v80
	ds_read_b32 v249, v249
	s_waitcnt lgkmcnt(0)
	v_fmamk_f32 v248, v248, 0x3fb8aa3b, v200
	v_cmp_le_i32_e32 vcc, 0, v245
	v_fmamk_f32 v84, v84, 0x3e38aa3b, v248
	s_nop 0
	v_cndmask_b32_e32 v84, v77, v84, vcc
	v_fmamk_f32 v249, v249, 0x3fb8aa3b, v200
	v_cmp_le_i32_e32 vcc, 0, v246
	v_fmamk_f32 v85, v85, 0x3e38aa3b, v249
	s_nop 0
	v_cndmask_b32_e32 v85, v77, v85, vcc
	v_subrev_u32_e32 v245, 2, v198
	v_min_u32_e32 v248, 0x7f, v245
	v_lshl_add_u32 v248, v248, 2, v80
	ds_read_b32 v248, v248
	v_subrev_u32_e32 v246, 3, v198
	v_min_u32_e32 v249, 0x7f, v246
	v_lshl_add_u32 v249, v249, 2, v80
	ds_read_b32 v249, v249
	s_waitcnt lgkmcnt(0)
	v_fmamk_f32 v248, v248, 0x3fb8aa3b, v200
	v_cmp_le_i32_e32 vcc, 0, v245
	v_fmamk_f32 v86, v86, 0x3e38aa3b, v248
	s_nop 0
	v_cndmask_b32_e32 v86, v77, v86, vcc
	v_fmamk_f32 v249, v249, 0x3fb8aa3b, v200
	v_cmp_le_i32_e32 vcc, 0, v246
	v_fmamk_f32 v87, v87, 0x3e38aa3b, v249
	s_nop 0
	v_cndmask_b32_e32 v87, v77, v87, vcc
	v_subrev_u32_e32 v245, 16, v198
	v_min_u32_e32 v248, 0x7f, v245
	v_lshl_add_u32 v248, v248, 2, v80
	ds_read_b32 v248, v248
	v_subrev_u32_e32 v246, 17, v198
	v_min_u32_e32 v249, 0x7f, v246
	v_lshl_add_u32 v249, v249, 2, v80
	ds_read_b32 v249, v249
	s_waitcnt lgkmcnt(0)
	v_fmamk_f32 v248, v248, 0x3fb8aa3b, v200
	v_cmp_le_i32_e32 vcc, 0, v245
	v_fmamk_f32 v88, v88, 0x3e38aa3b, v248
	s_nop 0
	v_cndmask_b32_e32 v88, v77, v88, vcc
	v_fmamk_f32 v249, v249, 0x3fb8aa3b, v200
	v_cmp_le_i32_e32 vcc, 0, v246
	v_fmamk_f32 v89, v89, 0x3e38aa3b, v249
	s_nop 0
	v_cndmask_b32_e32 v89, v77, v89, vcc
	v_subrev_u32_e32 v245, 18, v198
	v_min_u32_e32 v248, 0x7f, v245
	v_lshl_add_u32 v248, v248, 2, v80
	ds_read_b32 v248, v248
	v_subrev_u32_e32 v246, 19, v198
	v_min_u32_e32 v249, 0x7f, v246
	v_lshl_add_u32 v249, v249, 2, v80
	ds_read_b32 v249, v249
	s_waitcnt lgkmcnt(0)
	v_fmamk_f32 v248, v248, 0x3fb8aa3b, v200
	v_cmp_le_i32_e32 vcc, 0, v245
	v_fmamk_f32 v90, v90, 0x3e38aa3b, v248
	s_nop 0
	v_cndmask_b32_e32 v90, v77, v90, vcc
	v_fmamk_f32 v249, v249, 0x3fb8aa3b, v200
	v_cmp_le_i32_e32 vcc, 0, v246
	v_fmamk_f32 v91, v91, 0x3e38aa3b, v249
	s_nop 0
	v_cndmask_b32_e32 v91, v77, v91, vcc
	v_subrev_u32_e32 v245, 32, v198
	v_min_u32_e32 v248, 0x7f, v245
	v_lshl_add_u32 v248, v248, 2, v80
	ds_read_b32 v248, v248
	v_subrev_u32_e32 v246, 33, v198
	v_min_u32_e32 v249, 0x7f, v246
	v_lshl_add_u32 v249, v249, 2, v80
	ds_read_b32 v249, v249
	s_waitcnt lgkmcnt(0)
	v_fmamk_f32 v248, v248, 0x3fb8aa3b, v200
	v_cmp_le_i32_e32 vcc, 0, v245
	v_fmamk_f32 v92, v92, 0x3e38aa3b, v248
	s_nop 0
	v_cndmask_b32_e32 v92, v77, v92, vcc
	v_fmamk_f32 v249, v249, 0x3fb8aa3b, v200
	v_cmp_le_i32_e32 vcc, 0, v246
	v_fmamk_f32 v93, v93, 0x3e38aa3b, v249
	s_nop 0
	v_cndmask_b32_e32 v93, v77, v93, vcc
	v_subrev_u32_e32 v245, 34, v198
	v_min_u32_e32 v248, 0x7f, v245
	v_lshl_add_u32 v248, v248, 2, v80
	ds_read_b32 v248, v248
	v_subrev_u32_e32 v246, 35, v198
	v_min_u32_e32 v249, 0x7f, v246
	v_lshl_add_u32 v249, v249, 2, v80
	ds_read_b32 v249, v249
	s_waitcnt lgkmcnt(0)
	v_fmamk_f32 v248, v248, 0x3fb8aa3b, v200
	v_cmp_le_i32_e32 vcc, 0, v245
	v_fmamk_f32 v94, v94, 0x3e38aa3b, v248
	s_nop 0
	v_cndmask_b32_e32 v94, v77, v94, vcc
	v_fmamk_f32 v249, v249, 0x3fb8aa3b, v200
	v_cmp_le_i32_e32 vcc, 0, v246
	v_fmamk_f32 v95, v95, 0x3e38aa3b, v249
	s_nop 0
	v_cndmask_b32_e32 v95, v77, v95, vcc
	v_subrev_u32_e32 v245, 48, v198
	v_min_u32_e32 v248, 0x7f, v245
	v_lshl_add_u32 v248, v248, 2, v80
	ds_read_b32 v248, v248
	v_subrev_u32_e32 v246, 49, v198
	v_min_u32_e32 v249, 0x7f, v246
	v_lshl_add_u32 v249, v249, 2, v80
	ds_read_b32 v249, v249
	s_waitcnt lgkmcnt(0)
	v_fmamk_f32 v248, v248, 0x3fb8aa3b, v200
	v_cmp_le_i32_e32 vcc, 0, v245
	v_fmamk_f32 v96, v96, 0x3e38aa3b, v248
	s_nop 0
	v_cndmask_b32_e32 v96, v77, v96, vcc
	v_fmamk_f32 v249, v249, 0x3fb8aa3b, v200
	v_cmp_le_i32_e32 vcc, 0, v246
	v_fmamk_f32 v97, v97, 0x3e38aa3b, v249
	s_nop 0
	v_cndmask_b32_e32 v97, v77, v97, vcc
	v_subrev_u32_e32 v245, 50, v198
	v_min_u32_e32 v248, 0x7f, v245
	v_lshl_add_u32 v248, v248, 2, v80
	ds_read_b32 v248, v248
	v_subrev_u32_e32 v246, 51, v198
	v_min_u32_e32 v249, 0x7f, v246
	v_lshl_add_u32 v249, v249, 2, v80
	ds_read_b32 v249, v249
	s_waitcnt lgkmcnt(0)
	v_fmamk_f32 v248, v248, 0x3fb8aa3b, v200
	v_cmp_le_i32_e32 vcc, 0, v245
	v_fmamk_f32 v98, v98, 0x3e38aa3b, v248
	s_nop 0
	v_cndmask_b32_e32 v98, v77, v98, vcc
	v_fmamk_f32 v249, v249, 0x3fb8aa3b, v200
	v_cmp_le_i32_e32 vcc, 0, v246
	v_fmamk_f32 v99, v99, 0x3e38aa3b, v249
	s_nop 0
	v_cndmask_b32_e32 v99, v77, v99, vcc
	s_branch .Lbm2_Ag1_max
.Lbm2_Ag1_skip:
	s_bfe_u32 s29, s48, 0x40008
	s_cmp_eq_u32 s29, 0
	s_cbranch_scc1 .Lbm2_Ag2_skip
	s_waitcnt vmcnt(12)
	v_mfma_f32_16x16x32_fp8_fp8 v[84:87], v[2:3], v[182:183], 0
	v_mfma_f32_16x16x32_fp8_fp8 v[88:91], v[6:7], v[182:183], 0
	v_mfma_f32_16x16x32_fp8_fp8 v[92:95], v[12:13], v[182:183], 0
	v_mfma_f32_16x16x32_fp8_fp8 v[96:99], v[16:17], v[182:183], 0
	v_mfma_f32_16x16x32_fp8_fp8 v[84:87], v[4:5], v[184:185], v[84:87]
	v_mfma_f32_16x16x32_fp8_fp8 v[88:91], v[8:9], v[184:185], v[88:91]
	v_mfma_f32_16x16x32_fp8_fp8 v[92:95], v[14:15], v[184:185], v[92:95]
	v_mfma_f32_16x16x32_fp8_fp8 v[96:99], v[18:19], v[184:185], v[96:99]
	v_and_b32_e32 v199, s29, v244
	s_cmp_eq_u32 s14, 1
	v_cmp_ne_u32_e32 vcc, 0, v199
	s_cbranch_scc1 .Lbm2_Ag2_near
	v_add_f32_e32 v200, v81, v192
	v_cndmask_b32_e32 v200, v77, v200, vcc
	v_pk_fma_f32 v[84:85], v[84:85], s[16:17], v[200:201] op_sel_hi:[1,1,0]
	v_pk_fma_f32 v[86:87], v[86:87], s[16:17], v[200:201] op_sel_hi:[1,1,0]
	v_pk_fma_f32 v[88:89], v[88:89], s[16:17], v[200:201] op_sel_hi:[1,1,0]
	v_pk_fma_f32 v[90:91], v[90:91], s[16:17], v[200:201] op_sel_hi:[1,1,0]
	v_pk_fma_f32 v[92:93], v[92:93], s[16:17], v[200:201] op_sel_hi:[1,1,0]
	v_pk_fma_f32 v[94:95], v[94:95], s[16:17], v[200:201] op_sel_hi:[1,1,0]
	v_pk_fma_f32 v[96:97], v[96:97], s[16:17], v[200:201] op_sel_hi:[1,1,0]
	v_pk_fma_f32 v[98:99], v[98:99], s[16:17], v[200:201] op_sel_hi:[1,1,0]

.Lbm2_Ag2_exp:
	v_exp_f32_e32 v84, v84
	v_exp_f32_e32 v85, v85
	v_exp_f32_e32 v86, v86
	v_exp_f32_e32 v87, v87
	v_exp_f32_e32 v88, v88
	v_exp_f32_e32 v89, v89
	v_exp_f32_e32 v90, v90
	v_exp_f32_e32 v91, v91
	v_exp_f32_e32 v92, v92
	v_exp_f32_e32 v93, v93
	v_exp_f32_e32 v94, v94
	v_exp_f32_e32 v95, v95
	v_exp_f32_e32 v96, v96
	v_exp_f32_e32 v97, v97
	v_exp_f32_e32 v98, v98
	v_exp_f32_e32 v99, v99
	s_nop 0
	v_pk_add_f32 v[248:249], v[84:85], v[86:87]
	v_pk_add_f32 v[248:249], v[248:249], v[88:89]
	v_pk_add_f32 v[248:249], v[248:249], v[90:91]
	v_pk_add_f32 v[248:249], v[248:249], v[92:93]
	v_pk_add_f32 v[248:249], v[248:249], v[94:95]
	v_pk_add_f32 v[248:249], v[248:249], v[96:97]
	v_pk_add_f32 v[248:249], v[248:249], v[98:99]
	v_add_f32_e32 v248, v248, v249
	v_add_f32_e32 v196, v196, v248
	v_cvt_pk_fp8_f32 v84, v84, v85
	s_nop 0
	v_cvt_pk_fp8_f32 v84, v86, v87 op_sel:[0,0,1]
	v_cvt_pk_fp8_f32 v85, v88, v89
	s_nop 0
	v_cvt_pk_fp8_f32 v85, v90, v91 op_sel:[0,0,1]
	v_cvt_pk_fp8_f32 v86, v92, v93
	s_nop 0
	v_cvt_pk_fp8_f32 v86, v94, v95 op_sel:[0,0,1]
	v_cvt_pk_fp8_f32 v87, v96, v97
	s_nop 0
	v_cvt_pk_fp8_f32 v87, v98, v99 op_sel:[0,0,1]
	s_waitcnt vmcnt(8)
	s_nop 1
	v_mfma_f32_16x16x32_fp8_fp8 v[132:135], v[36:37], v[84:85], v[132:135]
	v_mfma_f32_16x16x32_fp8_fp8 v[136:139], v[38:39], v[84:85], v[136:139]
	v_mfma_f32_16x16x32_fp8_fp8 v[140:143], v[40:41], v[84:85], v[140:143]
	v_mfma_f32_16x16x32_fp8_fp8 v[144:147], v[42:43], v[84:85], v[144:147]
	v_mfma_f32_16x16x32_fp8_fp8 v[132:135], v[44:45], v[86:87], v[132:135]
	v_mfma_f32_16x16x32_fp8_fp8 v[136:139], v[46:47], v[86:87], v[136:139]
	v_mfma_f32_16x16x32_fp8_fp8 v[140:143], v[48:49], v[86:87], v[140:143]
	v_mfma_f32_16x16x32_fp8_fp8 v[144:147], v[50:51], v[86:87], v[144:147]
	s_branch .Lbm2_Ag2_skip
.Lbm2_Ag2_resc:
	v_max_f32_e32 v248, 0, v198
	v_max_f32_e32 v249, v198, v78
	v_exp_f32_e64 v248, -v248
	v_sub_f32_e32 v192, v192, v249
	v_sub_f32_e32 v84, v84, v249
	v_sub_f32_e32 v85, v85, v249
	v_sub_f32_e32 v86, v86, v249
	v_sub_f32_e32 v87, v87, v249
	v_sub_f32_e32 v88, v88, v249
	v_sub_f32_e32 v89, v89, v249
	v_sub_f32_e32 v90, v90, v249
	v_sub_f32_e32 v91, v91, v249
	v_sub_f32_e32 v92, v92, v249
	v_sub_f32_e32 v93, v93, v249
	v_sub_f32_e32 v94, v94, v249
	v_sub_f32_e32 v95, v95, v249
	v_sub_f32_e32 v96, v96, v249
	v_sub_f32_e32 v97, v97, v249
	v_sub_f32_e32 v98, v98, v249
	v_sub_f32_e32 v99, v99, v249
	v_mul_f32_e32 v196, v196, v248
	v_pk_mul_f32 v[132:133], v[132:133], v[248:249] op_sel_hi:[1,0]
	v_pk_mul_f32 v[134:135], v[134:135], v[248:249] op_sel_hi:[1,0]
	v_pk_mul_f32 v[136:137], v[136:137], v[248:249] op_sel_hi:[1,0]
	v_pk_mul_f32 v[138:139], v[138:139], v[248:249] op_sel_hi:[1,0]
	v_pk_mul_f32 v[140:141], v[140:141], v[248:249] op_sel_hi:[1,0]
	v_pk_mul_f32 v[142:143], v[142:143], v[248:249] op_sel_hi:[1,0]
	v_pk_mul_f32 v[144:145], v[144:145], v[248:249] op_sel_hi:[1,0]
	v_pk_mul_f32 v[146:147], v[146:147], v[248:249] op_sel_hi:[1,0]
	s_branch .Lbm2_Ag2_exp
.Lbm2_Ag2_near:
	s_lshl_b32 s13, s54, 6
	s_sub_i32 s13, s97, s13
	s_add_i32 s13, s13, 8
	v_and_b32_e32 v245, 15, v181
	v_lshrrev_b32_e32 v246, 4, v181
	v_lshrrev_b32_e32 v245, 2, v245
	v_lshlrev_b32_e32 v246, 2, v246
	v_cndmask_b32_e32 v200, v77, v192, vcc
	v_sub_u32_e32 v245, v245, v246
	v_add_u32_e32 v198, s13, v245
	v_mov_b32_e32 v245, v198
	v_min_u32_e32 v248, 0x7f, v245
	v_lshl_add_u32 v248, v248, 2, v80
	ds_read_b32 v248, v248
	v_subrev_u32_e32 v246, 1, v198
	v_min_u32_e32 v249, 0x7f, v246
	v_lshl_add_u32 v249, v249, 2, v80
	ds_read_b32 v249, v249
	s_waitcnt lgkmcnt(0)
	v_fmamk_f32 v248, v248, 0x3fb8aa3b, v200
	v_cmp_le_i32_e32 vcc, 0, v245
	v_fmamk_f32 v84, v84, 0x3e38aa3b, v248
	s_nop 0
	v_cndmask_b32_e32 v84, v77, v84, vcc
	v_fmamk_f32 v249, v249, 0x3fb8aa3b, v200
	v_cmp_le_i32_e32 vcc, 0, v246
	v_fmamk_f32 v85, v85, 0x3e38aa3b, v249
	s_nop 0
	v_cndmask_b32_e32 v85, v77, v85, vcc
	v_subrev_u32_e32 v245, 2, v198
	v_min_u32_e32 v248, 0x7f, v245
	v_lshl_add_u32 v248, v248, 2, v80
	ds_read_b32 v248, v248
	v_subrev_u32_e32 v246, 3, v198
	v_min_u32_e32 v249, 0x7f, v246
	v_lshl_add_u32 v249, v249, 2, v80
	ds_read_b32 v249, v249
	s_waitcnt lgkmcnt(0)
	v_fmamk_f32 v248, v248, 0x3fb8aa3b, v200
	v_cmp_le_i32_e32 vcc, 0, v245
	v_fmamk_f32 v86, v86, 0x3e38aa3b, v248
	s_nop 0
	v_cndmask_b32_e32 v86, v77, v86, vcc
	v_fmamk_f32 v249, v249, 0x3fb8aa3b, v200
	v_cmp_le_i32_e32 vcc, 0, v246
	v_fmamk_f32 v87, v87, 0x3e38aa3b, v249
	s_nop 0
	v_cndmask_b32_e32 v87, v77, v87, vcc
	v_subrev_u32_e32 v245, 16, v198
	v_min_u32_e32 v248, 0x7f, v245
	v_lshl_add_u32 v248, v248, 2, v80
	ds_read_b32 v248, v248
	v_subrev_u32_e32 v246, 17, v198
	v_min_u32_e32 v249, 0x7f, v246
	v_lshl_add_u32 v249, v249, 2, v80
	ds_read_b32 v249, v249
	s_waitcnt lgkmcnt(0)
	v_fmamk_f32 v248, v248, 0x3fb8aa3b, v200
	v_cmp_le_i32_e32 vcc, 0, v245
	v_fmamk_f32 v88, v88, 0x3e38aa3b, v248
	s_nop 0
	v_cndmask_b32_e32 v88, v77, v88, vcc
	v_fmamk_f32 v249, v249, 0x3fb8aa3b, v200
	v_cmp_le_i32_e32 vcc, 0, v246
	v_fmamk_f32 v89, v89, 0x3e38aa3b, v249
	s_nop 0
	v_cndmask_b32_e32 v89, v77, v89, vcc
	v_subrev_u32_e32 v245, 18, v198
	v_min_u32_e32 v248, 0x7f, v245
	v_lshl_add_u32 v248, v248, 2, v80
	ds_read_b32 v248, v248
	v_subrev_u32_e32 v246, 19, v198
	v_min_u32_e32 v249, 0x7f, v246
	v_lshl_add_u32 v249, v249, 2, v80
	ds_read_b32 v249, v249
	s_waitcnt lgkmcnt(0)
	v_fmamk_f32 v248, v248, 0x3fb8aa3b, v200
	v_cmp_le_i32_e32 vcc, 0, v245
	v_fmamk_f32 v90, v90, 0x3e38aa3b, v248
	s_nop 0
	v_cndmask_b32_e32 v90, v77, v90, vcc
	v_fmamk_f32 v249, v249, 0x3fb8aa3b, v200
	v_cmp_le_i32_e32 vcc, 0, v246
	v_fmamk_f32 v91, v91, 0x3e38aa3b, v249
	s_nop 0
	v_cndmask_b32_e32 v91, v77, v91, vcc
	v_subrev_u32_e32 v245, 32, v198
	v_min_u32_e32 v248, 0x7f, v245
	v_lshl_add_u32 v248, v248, 2, v80
	ds_read_b32 v248, v248
	v_subrev_u32_e32 v246, 33, v198
	v_min_u32_e32 v249, 0x7f, v246
	v_lshl_add_u32 v249, v249, 2, v80
	ds_read_b32 v249, v249
	s_waitcnt lgkmcnt(0)
	v_fmamk_f32 v248, v248, 0x3fb8aa3b, v200
	v_cmp_le_i32_e32 vcc, 0, v245
	v_fmamk_f32 v92, v92, 0x3e38aa3b, v248
	s_nop 0
	v_cndmask_b32_e32 v92, v77, v92, vcc
	v_fmamk_f32 v249, v249, 0x3fb8aa3b, v200
	v_cmp_le_i32_e32 vcc, 0, v246
	v_fmamk_f32 v93, v93, 0x3e38aa3b, v249
	s_nop 0
	v_cndmask_b32_e32 v93, v77, v93, vcc
	v_subrev_u32_e32 v245, 34, v198
	v_min_u32_e32 v248, 0x7f, v245
	v_lshl_add_u32 v248, v248, 2, v80
	ds_read_b32 v248, v248
	v_subrev_u32_e32 v246, 35, v198
	v_min_u32_e32 v249, 0x7f, v246
	v_lshl_add_u32 v249, v249, 2, v80
	ds_read_b32 v249, v249
	s_waitcnt lgkmcnt(0)
	v_fmamk_f32 v248, v248, 0x3fb8aa3b, v200
	v_cmp_le_i32_e32 vcc, 0, v245
	v_fmamk_f32 v94, v94, 0x3e38aa3b, v248
	s_nop 0
	v_cndmask_b32_e32 v94, v77, v94, vcc
	v_fmamk_f32 v249, v249, 0x3fb8aa3b, v200
	v_cmp_le_i32_e32 vcc, 0, v246
	v_fmamk_f32 v95, v95, 0x3e38aa3b, v249
	s_nop 0
	v_cndmask_b32_e32 v95, v77, v95, vcc
	v_subrev_u32_e32 v245, 48, v198
	v_min_u32_e32 v248, 0x7f, v245
	v_lshl_add_u32 v248, v248, 2, v80
	ds_read_b32 v248, v248
	v_subrev_u32_e32 v246, 49, v198
	v_min_u32_e32 v249, 0x7f, v246
	v_lshl_add_u32 v249, v249, 2, v80
	ds_read_b32 v249, v249
	s_waitcnt lgkmcnt(0)
	v_fmamk_f32 v248, v248, 0x3fb8aa3b, v200
	v_cmp_le_i32_e32 vcc, 0, v245
	v_fmamk_f32 v96, v96, 0x3e38aa3b, v248
	s_nop 0
	v_cndmask_b32_e32 v96, v77, v96, vcc
	v_fmamk_f32 v249, v249, 0x3fb8aa3b, v200
	v_cmp_le_i32_e32 vcc, 0, v246
	v_fmamk_f32 v97, v97, 0x3e38aa3b, v249
	s_nop 0
	v_cndmask_b32_e32 v97, v77, v97, vcc
	v_subrev_u32_e32 v245, 50, v198
	v_min_u32_e32 v248, 0x7f, v245
	v_lshl_add_u32 v248, v248, 2, v80
	ds_read_b32 v248, v248
	v_subrev_u32_e32 v246, 51, v198
	v_min_u32_e32 v249, 0x7f, v246
	v_lshl_add_u32 v249, v249, 2, v80
	ds_read_b32 v249, v249
	s_waitcnt lgkmcnt(0)
	v_fmamk_f32 v248, v248, 0x3fb8aa3b, v200
	v_cmp_le_i32_e32 vcc, 0, v245
	v_fmamk_f32 v98, v98, 0x3e38aa3b, v248
	s_nop 0
	v_cndmask_b32_e32 v98, v77, v98, vcc
	v_fmamk_f32 v249, v249, 0x3fb8aa3b, v200
	v_cmp_le_i32_e32 vcc, 0, v246
	v_fmamk_f32 v99, v99, 0x3e38aa3b, v249
	s_nop 0
	v_cndmask_b32_e32 v99, v77, v99, vcc
	s_branch .Lbm2_Ag2_max
.Lbm2_Ag2_skip:
	s_bfe_u32 s29, s48, 0x4000c
	s_cmp_eq_u32 s29, 0
	s_cbranch_scc1 .Lbm2_Ag3_skip
	s_waitcnt vmcnt(12)
	v_mfma_f32_16x16x32_fp8_fp8 v[84:87], v[2:3], v[186:187], 0
	v_mfma_f32_16x16x32_fp8_fp8 v[88:91], v[6:7], v[186:187], 0
	v_mfma_f32_16x16x32_fp8_fp8 v[92:95], v[12:13], v[186:187], 0
	v_mfma_f32_16x16x32_fp8_fp8 v[96:99], v[16:17], v[186:187], 0
	v_mfma_f32_16x16x32_fp8_fp8 v[84:87], v[4:5], v[188:189], v[84:87]
	v_mfma_f32_16x16x32_fp8_fp8 v[88:91], v[8:9], v[188:189], v[88:91]
	v_mfma_f32_16x16x32_fp8_fp8 v[92:95], v[14:15], v[188:189], v[92:95]
	v_mfma_f32_16x16x32_fp8_fp8 v[96:99], v[18:19], v[188:189], v[96:99]
	v_and_b32_e32 v199, s29, v244
	s_cmp_eq_u32 s14, 1
	v_cmp_ne_u32_e32 vcc, 0, v199
	s_cbranch_scc1 .Lbm2_Ag3_near
	v_add_f32_e32 v200, v81, v193
	v_cndmask_b32_e32 v200, v77, v200, vcc
	v_pk_fma_f32 v[84:85], v[84:85], s[16:17], v[200:201] op_sel_hi:[1,1,0]
	v_pk_fma_f32 v[86:87], v[86:87], s[16:17], v[200:201] op_sel_hi:[1,1,0]
	v_pk_fma_f32 v[88:89], v[88:89], s[16:17], v[200:201] op_sel_hi:[1,1,0]
	v_pk_fma_f32 v[90:91], v[90:91], s[16:17], v[200:201] op_sel_hi:[1,1,0]
	v_pk_fma_f32 v[92:93], v[92:93], s[16:17], v[200:201] op_sel_hi:[1,1,0]
	v_pk_fma_f32 v[94:95], v[94:95], s[16:17], v[200:201] op_sel_hi:[1,1,0]
	v_pk_fma_f32 v[96:97], v[96:97], s[16:17], v[200:201] op_sel_hi:[1,1,0]
	v_pk_fma_f32 v[98:99], v[98:99], s[16:17], v[200:201] op_sel_hi:[1,1,0]

.Lbm2_Ag3_exp:
	v_exp_f32_e32 v84, v84
	v_exp_f32_e32 v85, v85
	v_exp_f32_e32 v86, v86
	v_exp_f32_e32 v87, v87
	v_exp_f32_e32 v88, v88
	v_exp_f32_e32 v89, v89
	v_exp_f32_e32 v90, v90
	v_exp_f32_e32 v91, v91
	v_exp_f32_e32 v92, v92
	v_exp_f32_e32 v93, v93
	v_exp_f32_e32 v94, v94
	v_exp_f32_e32 v95, v95
	v_exp_f32_e32 v96, v96
	v_exp_f32_e32 v97, v97
	v_exp_f32_e32 v98, v98
	v_exp_f32_e32 v99, v99
	s_nop 0
	v_pk_add_f32 v[248:249], v[84:85], v[86:87]
	v_pk_add_f32 v[248:249], v[248:249], v[88:89]
	v_pk_add_f32 v[248:249], v[248:249], v[90:91]
	v_pk_add_f32 v[248:249], v[248:249], v[92:93]
	v_pk_add_f32 v[248:249], v[248:249], v[94:95]
	v_pk_add_f32 v[248:249], v[248:249], v[96:97]
	v_pk_add_f32 v[248:249], v[248:249], v[98:99]
	v_add_f32_e32 v248, v248, v249
	v_add_f32_e32 v197, v197, v248
	v_cvt_pk_fp8_f32 v84, v84, v85
	s_nop 0
	v_cvt_pk_fp8_f32 v84, v86, v87 op_sel:[0,0,1]
	v_cvt_pk_fp8_f32 v85, v88, v89
	s_nop 0
	v_cvt_pk_fp8_f32 v85, v90, v91 op_sel:[0,0,1]
	v_cvt_pk_fp8_f32 v86, v92, v93
	s_nop 0
	v_cvt_pk_fp8_f32 v86, v94, v95 op_sel:[0,0,1]
	v_cvt_pk_fp8_f32 v87, v96, v97
	s_nop 0
	v_cvt_pk_fp8_f32 v87, v98, v99 op_sel:[0,0,1]
	s_waitcnt vmcnt(8)
	s_nop 1
	v_mfma_f32_16x16x32_fp8_fp8 v[148:151], v[36:37], v[84:85], v[148:151]
	v_mfma_f32_16x16x32_fp8_fp8 v[152:155], v[38:39], v[84:85], v[152:155]
	v_mfma_f32_16x16x32_fp8_fp8 v[156:159], v[40:41], v[84:85], v[156:159]
	v_mfma_f32_16x16x32_fp8_fp8 v[160:163], v[42:43], v[84:85], v[160:163]
	v_mfma_f32_16x16x32_fp8_fp8 v[148:151], v[44:45], v[86:87], v[148:151]
	v_mfma_f32_16x16x32_fp8_fp8 v[152:155], v[46:47], v[86:87], v[152:155]
	v_mfma_f32_16x16x32_fp8_fp8 v[156:159], v[48:49], v[86:87], v[156:159]
	v_mfma_f32_16x16x32_fp8_fp8 v[160:163], v[50:51], v[86:87], v[160:163]
	s_branch .Lbm2_Ag3_skip
.Lbm2_Ag3_resc:
	v_max_f32_e32 v248, 0, v198
	v_max_f32_e32 v249, v198, v78
	v_exp_f32_e64 v248, -v248
	v_sub_f32_e32 v193, v193, v249
	v_sub_f32_e32 v84, v84, v249
	v_sub_f32_e32 v85, v85, v249
	v_sub_f32_e32 v86, v86, v249
	v_sub_f32_e32 v87, v87, v249
	v_sub_f32_e32 v88, v88, v249
	v_sub_f32_e32 v89, v89, v249
	v_sub_f32_e32 v90, v90, v249
	v_sub_f32_e32 v91, v91, v249
	v_sub_f32_e32 v92, v92, v249
	v_sub_f32_e32 v93, v93, v249
	v_sub_f32_e32 v94, v94, v249
	v_sub_f32_e32 v95, v95, v249
	v_sub_f32_e32 v96, v96, v249
	v_sub_f32_e32 v97, v97, v249
	v_sub_f32_e32 v98, v98, v249
	v_sub_f32_e32 v99, v99, v249
	v_mul_f32_e32 v197, v197, v248
	v_pk_mul_f32 v[148:149], v[148:149], v[248:249] op_sel_hi:[1,0]
	v_pk_mul_f32 v[150:151], v[150:151], v[248:249] op_sel_hi:[1,0]
	v_pk_mul_f32 v[152:153], v[152:153], v[248:249] op_sel_hi:[1,0]
	v_pk_mul_f32 v[154:155], v[154:155], v[248:249] op_sel_hi:[1,0]
	v_pk_mul_f32 v[156:157], v[156:157], v[248:249] op_sel_hi:[1,0]
	v_pk_mul_f32 v[158:159], v[158:159], v[248:249] op_sel_hi:[1,0]
	v_pk_mul_f32 v[160:161], v[160:161], v[248:249] op_sel_hi:[1,0]
	v_pk_mul_f32 v[162:163], v[162:163], v[248:249] op_sel_hi:[1,0]
	s_branch .Lbm2_Ag3_exp
.Lbm2_Ag3_near:
	s_lshl_b32 s13, s54, 6
	s_sub_i32 s13, s97, s13
	s_add_i32 s13, s13, 12
	v_and_b32_e32 v245, 15, v181
	v_lshrrev_b32_e32 v246, 4, v181
	v_lshrrev_b32_e32 v245, 2, v245
	v_lshlrev_b32_e32 v246, 2, v246
	v_cndmask_b32_e32 v200, v77, v193, vcc
	v_sub_u32_e32 v245, v245, v246
	v_add_u32_e32 v198, s13, v245
	v_mov_b32_e32 v245, v198
	v_min_u32_e32 v248, 0x7f, v245
	v_lshl_add_u32 v248, v248, 2, v80
	ds_read_b32 v248, v248
	v_subrev_u32_e32 v246, 1, v198
	v_min_u32_e32 v249, 0x7f, v246
	v_lshl_add_u32 v249, v249, 2, v80
	ds_read_b32 v249, v249
	s_waitcnt lgkmcnt(0)
	v_fmamk_f32 v248, v248, 0x3fb8aa3b, v200
	v_cmp_le_i32_e32 vcc, 0, v245
	v_fmamk_f32 v84, v84, 0x3e38aa3b, v248
	s_nop 0
	v_cndmask_b32_e32 v84, v77, v84, vcc
	v_fmamk_f32 v249, v249, 0x3fb8aa3b, v200
	v_cmp_le_i32_e32 vcc, 0, v246
	v_fmamk_f32 v85, v85, 0x3e38aa3b, v249
	s_nop 0
	v_cndmask_b32_e32 v85, v77, v85, vcc
	v_subrev_u32_e32 v245, 2, v198
	v_min_u32_e32 v248, 0x7f, v245
	v_lshl_add_u32 v248, v248, 2, v80
	ds_read_b32 v248, v248
	v_subrev_u32_e32 v246, 3, v198
	v_min_u32_e32 v249, 0x7f, v246
	v_lshl_add_u32 v249, v249, 2, v80
	ds_read_b32 v249, v249
	s_waitcnt lgkmcnt(0)
	v_fmamk_f32 v248, v248, 0x3fb8aa3b, v200
	v_cmp_le_i32_e32 vcc, 0, v245
	v_fmamk_f32 v86, v86, 0x3e38aa3b, v248
	s_nop 0
	v_cndmask_b32_e32 v86, v77, v86, vcc
	v_fmamk_f32 v249, v249, 0x3fb8aa3b, v200
	v_cmp_le_i32_e32 vcc, 0, v246
	v_fmamk_f32 v87, v87, 0x3e38aa3b, v249
	s_nop 0
	v_cndmask_b32_e32 v87, v77, v87, vcc
	v_subrev_u32_e32 v245, 16, v198
	v_min_u32_e32 v248, 0x7f, v245
	v_lshl_add_u32 v248, v248, 2, v80
	ds_read_b32 v248, v248
	v_subrev_u32_e32 v246, 17, v198
	v_min_u32_e32 v249, 0x7f, v246
	v_lshl_add_u32 v249, v249, 2, v80
	ds_read_b32 v249, v249
	s_waitcnt lgkmcnt(0)
	v_fmamk_f32 v248, v248, 0x3fb8aa3b, v200
	v_cmp_le_i32_e32 vcc, 0, v245
	v_fmamk_f32 v88, v88, 0x3e38aa3b, v248
	s_nop 0
	v_cndmask_b32_e32 v88, v77, v88, vcc
	v_fmamk_f32 v249, v249, 0x3fb8aa3b, v200
	v_cmp_le_i32_e32 vcc, 0, v246
	v_fmamk_f32 v89, v89, 0x3e38aa3b, v249
	s_nop 0
	v_cndmask_b32_e32 v89, v77, v89, vcc
	v_subrev_u32_e32 v245, 18, v198
	v_min_u32_e32 v248, 0x7f, v245
	v_lshl_add_u32 v248, v248, 2, v80
	ds_read_b32 v248, v248
	v_subrev_u32_e32 v246, 19, v198
	v_min_u32_e32 v249, 0x7f, v246
	v_lshl_add_u32 v249, v249, 2, v80
	ds_read_b32 v249, v249
	s_waitcnt lgkmcnt(0)
	v_fmamk_f32 v248, v248, 0x3fb8aa3b, v200
	v_cmp_le_i32_e32 vcc, 0, v245
	v_fmamk_f32 v90, v90, 0x3e38aa3b, v248
	s_nop 0
	v_cndmask_b32_e32 v90, v77, v90, vcc
	v_fmamk_f32 v249, v249, 0x3fb8aa3b, v200
	v_cmp_le_i32_e32 vcc, 0, v246
	v_fmamk_f32 v91, v91, 0x3e38aa3b, v249
	s_nop 0
	v_cndmask_b32_e32 v91, v77, v91, vcc
	v_subrev_u32_e32 v245, 32, v198
	v_min_u32_e32 v248, 0x7f, v245
	v_lshl_add_u32 v248, v248, 2, v80
	ds_read_b32 v248, v248
	v_subrev_u32_e32 v246, 33, v198
	v_min_u32_e32 v249, 0x7f, v246
	v_lshl_add_u32 v249, v249, 2, v80
	ds_read_b32 v249, v249
	s_waitcnt lgkmcnt(0)
	v_fmamk_f32 v248, v248, 0x3fb8aa3b, v200
	v_cmp_le_i32_e32 vcc, 0, v245
	v_fmamk_f32 v92, v92, 0x3e38aa3b, v248
	s_nop 0
	v_cndmask_b32_e32 v92, v77, v92, vcc
	v_fmamk_f32 v249, v249, 0x3fb8aa3b, v200
	v_cmp_le_i32_e32 vcc, 0, v246
	v_fmamk_f32 v93, v93, 0x3e38aa3b, v249
	s_nop 0
	v_cndmask_b32_e32 v93, v77, v93, vcc
	v_subrev_u32_e32 v245, 34, v198
	v_min_u32_e32 v248, 0x7f, v245
	v_lshl_add_u32 v248, v248, 2, v80
	ds_read_b32 v248, v248
	v_subrev_u32_e32 v246, 35, v198
	v_min_u32_e32 v249, 0x7f, v246
	v_lshl_add_u32 v249, v249, 2, v80
	ds_read_b32 v249, v249
	s_waitcnt lgkmcnt(0)
	v_fmamk_f32 v248, v248, 0x3fb8aa3b, v200
	v_cmp_le_i32_e32 vcc, 0, v245
	v_fmamk_f32 v94, v94, 0x3e38aa3b, v248
	s_nop 0
	v_cndmask_b32_e32 v94, v77, v94, vcc
	v_fmamk_f32 v249, v249, 0x3fb8aa3b, v200
	v_cmp_le_i32_e32 vcc, 0, v246
	v_fmamk_f32 v95, v95, 0x3e38aa3b, v249
	s_nop 0
	v_cndmask_b32_e32 v95, v77, v95, vcc
	v_subrev_u32_e32 v245, 48, v198
	v_min_u32_e32 v248, 0x7f, v245
	v_lshl_add_u32 v248, v248, 2, v80
	ds_read_b32 v248, v248
	v_subrev_u32_e32 v246, 49, v198
	v_min_u32_e32 v249, 0x7f, v246
	v_lshl_add_u32 v249, v249, 2, v80
	ds_read_b32 v249, v249
	s_waitcnt lgkmcnt(0)
	v_fmamk_f32 v248, v248, 0x3fb8aa3b, v200
	v_cmp_le_i32_e32 vcc, 0, v245
	v_fmamk_f32 v96, v96, 0x3e38aa3b, v248
	s_nop 0
	v_cndmask_b32_e32 v96, v77, v96, vcc
	v_fmamk_f32 v249, v249, 0x3fb8aa3b, v200
	v_cmp_le_i32_e32 vcc, 0, v246
	v_fmamk_f32 v97, v97, 0x3e38aa3b, v249
	s_nop 0
	v_cndmask_b32_e32 v97, v77, v97, vcc
	v_subrev_u32_e32 v245, 50, v198
	v_min_u32_e32 v248, 0x7f, v245
	v_lshl_add_u32 v248, v248, 2, v80
	ds_read_b32 v248, v248
	v_subrev_u32_e32 v246, 51, v198
	v_min_u32_e32 v249, 0x7f, v246
	v_lshl_add_u32 v249, v249, 2, v80
	ds_read_b32 v249, v249
	s_waitcnt lgkmcnt(0)
	v_fmamk_f32 v248, v248, 0x3fb8aa3b, v200
	v_cmp_le_i32_e32 vcc, 0, v245
	v_fmamk_f32 v98, v98, 0x3e38aa3b, v248
	s_nop 0
	v_cndmask_b32_e32 v98, v77, v98, vcc
	v_fmamk_f32 v249, v249, 0x3fb8aa3b, v200
	v_cmp_le_i32_e32 vcc, 0, v246
	v_fmamk_f32 v99, v99, 0x3e38aa3b, v249
	s_nop 0
	v_cndmask_b32_e32 v99, v77, v99, vcc
	s_branch .Lbm2_Ag3_max
.Lbm2_Ag3_skip:
	v_mov_b32_e32 v78, 0
	s_mov_b32 s54, s15
	s_mov_b32 s48, s27
	s_waitcnt lgkmcnt(0)
	v_readfirstlane_b32 s13, v76
	s_add_i32 s35, s35, 1
	s_and_b32 s15, s13, 0xffff
	s_lshr_b32 s27, s13, 16
	s_cmp_lt_i32 s35, s25
	s_cbranch_scc1 .Lbm2_blkB
	s_branch .Lbm2_done
.Lbm2_blkB:
	s_lshl_b32 s12, s15, 12
	s_add_u32 s30, s46, s12
	s_addc_u32 s31, s47, 0
	global_load_dwordx4 v[2:5], v79, s[30:31]
	global_load_dwordx4 v[6:9], v79, s[30:31] offset:1024
	global_load_dwordx4 v[12:15], v79, s[30:31] offset:2048
	global_load_dwordx4 v[16:19], v79, s[30:31] offset:3072
	s_lshl_b32 s12, s15, 12
	s_add_u32 s30, s62, s12
	s_addc_u32 s31, s63, 0
	global_load_dwordx4 v[36:39], v79, s[30:31]
	global_load_dwordx4 v[40:43], v79, s[30:31] offset:1024
	global_load_dwordx4 v[44:47], v79, s[30:31] offset:2048
	global_load_dwordx4 v[48:51], v79, s[30:31] offset:3072
	s_add_i32 s14, s35, 2
	s_add_i32 s13, s25, -1
	s_min_i32 s14, s14, s13
	s_lshl_b32 s13, s14, 2
	s_add_i32 s13, s13, s96
	v_mov_b32_e32 v76, s13
	ds_read_b32 v76, v76 offset:16384
	s_cmp_ge_i32 s54, s21
	s_cselect_b32 s14, 1, 0
	s_bfe_u32 s29, s48, 0x40000
	s_cmp_eq_u32 s29, 0
	s_cbranch_scc1 .Lbm2_Bg0_skip
	s_waitcnt vmcnt(12)
	v_mfma_f32_16x16x32_fp8_fp8 v[84:87], v[20:21], v[164:165], 0
	v_mfma_f32_16x16x32_fp8_fp8 v[88:91], v[24:25], v[164:165], 0
	v_mfma_f32_16x16x32_fp8_fp8 v[92:95], v[28:29], v[164:165], 0
	v_mfma_f32_16x16x32_fp8_fp8 v[96:99], v[32:33], v[164:165], 0
	v_mfma_f32_16x16x32_fp8_fp8 v[84:87], v[22:23], v[166:167], v[84:87]
	v_mfma_f32_16x16x32_fp8_fp8 v[88:91], v[26:27], v[166:167], v[88:91]
	v_mfma_f32_16x16x32_fp8_fp8 v[92:95], v[30:31], v[166:167], v[92:95]
	v_mfma_f32_16x16x32_fp8_fp8 v[96:99], v[34:35], v[166:167], v[96:99]
	v_and_b32_e32 v199, s29, v244
	s_cmp_eq_u32 s14, 1
	v_cmp_ne_u32_e32 vcc, 0, v199
	s_cbranch_scc1 .Lbm2_Bg0_near
	v_add_f32_e32 v200, v81, v190
	v_cndmask_b32_e32 v200, v77, v200, vcc
	v_pk_fma_f32 v[84:85], v[84:85], s[16:17], v[200:201] op_sel_hi:[1,1,0]
	v_pk_fma_f32 v[86:87], v[86:87], s[16:17], v[200:201] op_sel_hi:[1,1,0]
	v_pk_fma_f32 v[88:89], v[88:89], s[16:17], v[200:201] op_sel_hi:[1,1,0]
	v_pk_fma_f32 v[90:91], v[90:91], s[16:17], v[200:201] op_sel_hi:[1,1,0]
	v_pk_fma_f32 v[92:93], v[92:93], s[16:17], v[200:201] op_sel_hi:[1,1,0]
	v_pk_fma_f32 v[94:95], v[94:95], s[16:17], v[200:201] op_sel_hi:[1,1,0]
	v_pk_fma_f32 v[96:97], v[96:97], s[16:17], v[200:201] op_sel_hi:[1,1,0]
	v_pk_fma_f32 v[98:99], v[98:99], s[16:17], v[200:201] op_sel_hi:[1,1,0]

.Lbm2_Bg0_exp:
	v_exp_f32_e32 v84, v84
	v_exp_f32_e32 v85, v85
	v_exp_f32_e32 v86, v86
	v_exp_f32_e32 v87, v87
	v_exp_f32_e32 v88, v88
	v_exp_f32_e32 v89, v89
	v_exp_f32_e32 v90, v90
	v_exp_f32_e32 v91, v91
	v_exp_f32_e32 v92, v92
	v_exp_f32_e32 v93, v93
	v_exp_f32_e32 v94, v94
	v_exp_f32_e32 v95, v95
	v_exp_f32_e32 v96, v96
	v_exp_f32_e32 v97, v97
	v_exp_f32_e32 v98, v98
	v_exp_f32_e32 v99, v99
	s_nop 0
	v_pk_add_f32 v[248:249], v[84:85], v[86:87]
	v_pk_add_f32 v[248:249], v[248:249], v[88:89]
	v_pk_add_f32 v[248:249], v[248:249], v[90:91]
	v_pk_add_f32 v[248:249], v[248:249], v[92:93]
	v_pk_add_f32 v[248:249], v[248:249], v[94:95]
	v_pk_add_f32 v[248:249], v[248:249], v[96:97]
	v_pk_add_f32 v[248:249], v[248:249], v[98:99]
	v_add_f32_e32 v248, v248, v249
	v_add_f32_e32 v194, v194, v248
	v_cvt_pk_fp8_f32 v84, v84, v85
	s_nop 0
	v_cvt_pk_fp8_f32 v84, v86, v87 op_sel:[0,0,1]
	v_cvt_pk_fp8_f32 v85, v88, v89
	s_nop 0
	v_cvt_pk_fp8_f32 v85, v90, v91 op_sel:[0,0,1]
	v_cvt_pk_fp8_f32 v86, v92, v93
	s_nop 0
	v_cvt_pk_fp8_f32 v86, v94, v95 op_sel:[0,0,1]
	v_cvt_pk_fp8_f32 v87, v96, v97
	s_nop 0
	v_cvt_pk_fp8_f32 v87, v98, v99 op_sel:[0,0,1]
	s_waitcnt vmcnt(8)
	s_nop 1
	v_mfma_f32_16x16x32_fp8_fp8 v[100:103], v[52:53], v[84:85], v[100:103]
	v_mfma_f32_16x16x32_fp8_fp8 v[104:107], v[54:55], v[84:85], v[104:107]
	v_mfma_f32_16x16x32_fp8_fp8 v[108:111], v[56:57], v[84:85], v[108:111]
	v_mfma_f32_16x16x32_fp8_fp8 v[112:115], v[58:59], v[84:85], v[112:115]
	v_mfma_f32_16x16x32_fp8_fp8 v[100:103], v[60:61], v[86:87], v[100:103]
	v_mfma_f32_16x16x32_fp8_fp8 v[104:107], v[62:63], v[86:87], v[104:107]
	v_mfma_f32_16x16x32_fp8_fp8 v[108:111], v[64:65], v[86:87], v[108:111]
	v_mfma_f32_16x16x32_fp8_fp8 v[112:115], v[66:67], v[86:87], v[112:115]
	s_branch .Lbm2_Bg0_skip

.Lbm2_Bg0_skip:
	s_bfe_u32 s29, s48, 0x40004
	s_cmp_eq_u32 s29, 0
	s_cbranch_scc1 .Lbm2_Bg1_skip
	s_waitcnt vmcnt(12)
	v_mfma_f32_16x16x32_fp8_fp8 v[84:87], v[20:21], v[168:169], 0
	v_mfma_f32_16x16x32_fp8_fp8 v[88:91], v[24:25], v[168:169], 0
	v_mfma_f32_16x16x32_fp8_fp8 v[92:95], v[28:29], v[168:169], 0
	v_mfma_f32_16x16x32_fp8_fp8 v[96:99], v[32:33], v[168:169], 0
	v_mfma_f32_16x16x32_fp8_fp8 v[84:87], v[22:23], v[170:171], v[84:87]
	v_mfma_f32_16x16x32_fp8_fp8 v[88:91], v[26:27], v[170:171], v[88:91]
	v_mfma_f32_16x16x32_fp8_fp8 v[92:95], v[30:31], v[170:171], v[92:95]
	v_mfma_f32_16x16x32_fp8_fp8 v[96:99], v[34:35], v[170:171], v[96:99]
	v_and_b32_e32 v199, s29, v244
	s_cmp_eq_u32 s14, 1
	v_cmp_ne_u32_e32 vcc, 0, v199
	s_cbranch_scc1 .Lbm2_Bg1_near
	v_add_f32_e32 v200, v81, v191
	v_cndmask_b32_e32 v200, v77, v200, vcc
	v_pk_fma_f32 v[84:85], v[84:85], s[16:17], v[200:201] op_sel_hi:[1,1,0]
	v_pk_fma_f32 v[86:87], v[86:87], s[16:17], v[200:201] op_sel_hi:[1,1,0]
	v_pk_fma_f32 v[88:89], v[88:89], s[16:17], v[200:201] op_sel_hi:[1,1,0]
	v_pk_fma_f32 v[90:91], v[90:91], s[16:17], v[200:201] op_sel_hi:[1,1,0]
	v_pk_fma_f32 v[92:93], v[92:93], s[16:17], v[200:201] op_sel_hi:[1,1,0]
	v_pk_fma_f32 v[94:95], v[94:95], s[16:17], v[200:201] op_sel_hi:[1,1,0]
	v_pk_fma_f32 v[96:97], v[96:97], s[16:17], v[200:201] op_sel_hi:[1,1,0]
	v_pk_fma_f32 v[98:99], v[98:99], s[16:17], v[200:201] op_sel_hi:[1,1,0]

.Lbm2_Bg1_exp:
	v_exp_f32_e32 v84, v84
	v_exp_f32_e32 v85, v85
	v_exp_f32_e32 v86, v86
	v_exp_f32_e32 v87, v87
	v_exp_f32_e32 v88, v88
	v_exp_f32_e32 v89, v89
	v_exp_f32_e32 v90, v90
	v_exp_f32_e32 v91, v91
	v_exp_f32_e32 v92, v92
	v_exp_f32_e32 v93, v93
	v_exp_f32_e32 v94, v94
	v_exp_f32_e32 v95, v95
	v_exp_f32_e32 v96, v96
	v_exp_f32_e32 v97, v97
	v_exp_f32_e32 v98, v98
	v_exp_f32_e32 v99, v99
	s_nop 0
	v_pk_add_f32 v[248:249], v[84:85], v[86:87]
	v_pk_add_f32 v[248:249], v[248:249], v[88:89]
	v_pk_add_f32 v[248:249], v[248:249], v[90:91]
	v_pk_add_f32 v[248:249], v[248:249], v[92:93]
	v_pk_add_f32 v[248:249], v[248:249], v[94:95]
	v_pk_add_f32 v[248:249], v[248:249], v[96:97]
	v_pk_add_f32 v[248:249], v[248:249], v[98:99]
	v_add_f32_e32 v248, v248, v249
	v_add_f32_e32 v195, v195, v248
	v_cvt_pk_fp8_f32 v84, v84, v85
	s_nop 0
	v_cvt_pk_fp8_f32 v84, v86, v87 op_sel:[0,0,1]
	v_cvt_pk_fp8_f32 v85, v88, v89
	s_nop 0
	v_cvt_pk_fp8_f32 v85, v90, v91 op_sel:[0,0,1]
	v_cvt_pk_fp8_f32 v86, v92, v93
	s_nop 0
	v_cvt_pk_fp8_f32 v86, v94, v95 op_sel:[0,0,1]
	v_cvt_pk_fp8_f32 v87, v96, v97
	s_nop 0
	v_cvt_pk_fp8_f32 v87, v98, v99 op_sel:[0,0,1]
	s_waitcnt vmcnt(8)
	s_nop 1
	v_mfma_f32_16x16x32_fp8_fp8 v[116:119], v[52:53], v[84:85], v[116:119]
	v_mfma_f32_16x16x32_fp8_fp8 v[120:123], v[54:55], v[84:85], v[120:123]
	v_mfma_f32_16x16x32_fp8_fp8 v[124:127], v[56:57], v[84:85], v[124:127]
	v_mfma_f32_16x16x32_fp8_fp8 v[128:131], v[58:59], v[84:85], v[128:131]
	v_mfma_f32_16x16x32_fp8_fp8 v[116:119], v[60:61], v[86:87], v[116:119]
	v_mfma_f32_16x16x32_fp8_fp8 v[120:123], v[62:63], v[86:87], v[120:123]
	v_mfma_f32_16x16x32_fp8_fp8 v[124:127], v[64:65], v[86:87], v[124:127]
	v_mfma_f32_16x16x32_fp8_fp8 v[128:131], v[66:67], v[86:87], v[128:131]
	s_branch .Lbm2_Bg1_skip

.Lbm2_Bg1_skip:
	s_bfe_u32 s29, s48, 0x40008
	s_cmp_eq_u32 s29, 0
	s_cbranch_scc1 .Lbm2_Bg2_skip
	s_waitcnt vmcnt(12)
	v_mfma_f32_16x16x32_fp8_fp8 v[84:87], v[20:21], v[182:183], 0
	v_mfma_f32_16x16x32_fp8_fp8 v[88:91], v[24:25], v[182:183], 0
	v_mfma_f32_16x16x32_fp8_fp8 v[92:95], v[28:29], v[182:183], 0
	v_mfma_f32_16x16x32_fp8_fp8 v[96:99], v[32:33], v[182:183], 0
	v_mfma_f32_16x16x32_fp8_fp8 v[84:87], v[22:23], v[184:185], v[84:87]
	v_mfma_f32_16x16x32_fp8_fp8 v[88:91], v[26:27], v[184:185], v[88:91]
	v_mfma_f32_16x16x32_fp8_fp8 v[92:95], v[30:31], v[184:185], v[92:95]
	v_mfma_f32_16x16x32_fp8_fp8 v[96:99], v[34:35], v[184:185], v[96:99]
	v_and_b32_e32 v199, s29, v244
	s_cmp_eq_u32 s14, 1
	v_cmp_ne_u32_e32 vcc, 0, v199
	s_cbranch_scc1 .Lbm2_Bg2_near
	v_add_f32_e32 v200, v81, v192
	v_cndmask_b32_e32 v200, v77, v200, vcc
	v_pk_fma_f32 v[84:85], v[84:85], s[16:17], v[200:201] op_sel_hi:[1,1,0]
	v_pk_fma_f32 v[86:87], v[86:87], s[16:17], v[200:201] op_sel_hi:[1,1,0]
	v_pk_fma_f32 v[88:89], v[88:89], s[16:17], v[200:201] op_sel_hi:[1,1,0]
	v_pk_fma_f32 v[90:91], v[90:91], s[16:17], v[200:201] op_sel_hi:[1,1,0]
	v_pk_fma_f32 v[92:93], v[92:93], s[16:17], v[200:201] op_sel_hi:[1,1,0]
	v_pk_fma_f32 v[94:95], v[94:95], s[16:17], v[200:201] op_sel_hi:[1,1,0]
	v_pk_fma_f32 v[96:97], v[96:97], s[16:17], v[200:201] op_sel_hi:[1,1,0]
	v_pk_fma_f32 v[98:99], v[98:99], s[16:17], v[200:201] op_sel_hi:[1,1,0]

.Lbm2_Bg2_exp:
	v_exp_f32_e32 v84, v84
	v_exp_f32_e32 v85, v85
	v_exp_f32_e32 v86, v86
	v_exp_f32_e32 v87, v87
	v_exp_f32_e32 v88, v88
	v_exp_f32_e32 v89, v89
	v_exp_f32_e32 v90, v90
	v_exp_f32_e32 v91, v91
	v_exp_f32_e32 v92, v92
	v_exp_f32_e32 v93, v93
	v_exp_f32_e32 v94, v94
	v_exp_f32_e32 v95, v95
	v_exp_f32_e32 v96, v96
	v_exp_f32_e32 v97, v97
	v_exp_f32_e32 v98, v98
	v_exp_f32_e32 v99, v99
	s_nop 0
	v_pk_add_f32 v[248:249], v[84:85], v[86:87]
	v_pk_add_f32 v[248:249], v[248:249], v[88:89]
	v_pk_add_f32 v[248:249], v[248:249], v[90:91]
	v_pk_add_f32 v[248:249], v[248:249], v[92:93]
	v_pk_add_f32 v[248:249], v[248:249], v[94:95]
	v_pk_add_f32 v[248:249], v[248:249], v[96:97]
	v_pk_add_f32 v[248:249], v[248:249], v[98:99]
	v_add_f32_e32 v248, v248, v249
	v_add_f32_e32 v196, v196, v248
	v_cvt_pk_fp8_f32 v84, v84, v85
	s_nop 0
	v_cvt_pk_fp8_f32 v84, v86, v87 op_sel:[0,0,1]
	v_cvt_pk_fp8_f32 v85, v88, v89
	s_nop 0
	v_cvt_pk_fp8_f32 v85, v90, v91 op_sel:[0,0,1]
	v_cvt_pk_fp8_f32 v86, v92, v93
	s_nop 0
	v_cvt_pk_fp8_f32 v86, v94, v95 op_sel:[0,0,1]
	v_cvt_pk_fp8_f32 v87, v96, v97
	s_nop 0
	v_cvt_pk_fp8_f32 v87, v98, v99 op_sel:[0,0,1]
	s_waitcnt vmcnt(8)
	s_nop 1
	v_mfma_f32_16x16x32_fp8_fp8 v[132:135], v[52:53], v[84:85], v[132:135]
	v_mfma_f32_16x16x32_fp8_fp8 v[136:139], v[54:55], v[84:85], v[136:139]
	v_mfma_f32_16x16x32_fp8_fp8 v[140:143], v[56:57], v[84:85], v[140:143]
	v_mfma_f32_16x16x32_fp8_fp8 v[144:147], v[58:59], v[84:85], v[144:147]
	v_mfma_f32_16x16x32_fp8_fp8 v[132:135], v[60:61], v[86:87], v[132:135]
	v_mfma_f32_16x16x32_fp8_fp8 v[136:139], v[62:63], v[86:87], v[136:139]
	v_mfma_f32_16x16x32_fp8_fp8 v[140:143], v[64:65], v[86:87], v[140:143]
	v_mfma_f32_16x16x32_fp8_fp8 v[144:147], v[66:67], v[86:87], v[144:147]
	s_branch .Lbm2_Bg2_skip

.Lbm2_Bg2_skip:
	s_bfe_u32 s29, s48, 0x4000c
	s_cmp_eq_u32 s29, 0
	s_cbranch_scc1 .Lbm2_Bg3_skip
	s_waitcnt vmcnt(12)
	v_mfma_f32_16x16x32_fp8_fp8 v[84:87], v[20:21], v[186:187], 0
	v_mfma_f32_16x16x32_fp8_fp8 v[88:91], v[24:25], v[186:187], 0
	v_mfma_f32_16x16x32_fp8_fp8 v[92:95], v[28:29], v[186:187], 0
	v_mfma_f32_16x16x32_fp8_fp8 v[96:99], v[32:33], v[186:187], 0
	v_mfma_f32_16x16x32_fp8_fp8 v[84:87], v[22:23], v[188:189], v[84:87]
	v_mfma_f32_16x16x32_fp8_fp8 v[88:91], v[26:27], v[188:189], v[88:91]
	v_mfma_f32_16x16x32_fp8_fp8 v[92:95], v[30:31], v[188:189], v[92:95]
	v_mfma_f32_16x16x32_fp8_fp8 v[96:99], v[34:35], v[188:189], v[96:99]
	v_and_b32_e32 v199, s29, v244
	s_cmp_eq_u32 s14, 1
	v_cmp_ne_u32_e32 vcc, 0, v199
	s_cbranch_scc1 .Lbm2_Bg3_near
	v_add_f32_e32 v200, v81, v193
	v_cndmask_b32_e32 v200, v77, v200, vcc
	v_pk_fma_f32 v[84:85], v[84:85], s[16:17], v[200:201] op_sel_hi:[1,1,0]
	v_pk_fma_f32 v[86:87], v[86:87], s[16:17], v[200:201] op_sel_hi:[1,1,0]
	v_pk_fma_f32 v[88:89], v[88:89], s[16:17], v[200:201] op_sel_hi:[1,1,0]
	v_pk_fma_f32 v[90:91], v[90:91], s[16:17], v[200:201] op_sel_hi:[1,1,0]
	v_pk_fma_f32 v[92:93], v[92:93], s[16:17], v[200:201] op_sel_hi:[1,1,0]
	v_pk_fma_f32 v[94:95], v[94:95], s[16:17], v[200:201] op_sel_hi:[1,1,0]
	v_pk_fma_f32 v[96:97], v[96:97], s[16:17], v[200:201] op_sel_hi:[1,1,0]
	v_pk_fma_f32 v[98:99], v[98:99], s[16:17], v[200:201] op_sel_hi:[1,1,0]

.Lbm2_Bg3_exp:
	v_exp_f32_e32 v84, v84
	v_exp_f32_e32 v85, v85
	v_exp_f32_e32 v86, v86
	v_exp_f32_e32 v87, v87
	v_exp_f32_e32 v88, v88
	v_exp_f32_e32 v89, v89
	v_exp_f32_e32 v90, v90
	v_exp_f32_e32 v91, v91
	v_exp_f32_e32 v92, v92
	v_exp_f32_e32 v93, v93
	v_exp_f32_e32 v94, v94
	v_exp_f32_e32 v95, v95
	v_exp_f32_e32 v96, v96
	v_exp_f32_e32 v97, v97
	v_exp_f32_e32 v98, v98
	v_exp_f32_e32 v99, v99
	s_nop 0
	v_pk_add_f32 v[248:249], v[84:85], v[86:87]
	v_pk_add_f32 v[248:249], v[248:249], v[88:89]
	v_pk_add_f32 v[248:249], v[248:249], v[90:91]
	v_pk_add_f32 v[248:249], v[248:249], v[92:93]
	v_pk_add_f32 v[248:249], v[248:249], v[94:95]
	v_pk_add_f32 v[248:249], v[248:249], v[96:97]
	v_pk_add_f32 v[248:249], v[248:249], v[98:99]
	v_add_f32_e32 v248, v248, v249
	v_add_f32_e32 v197, v197, v248
	v_cvt_pk_fp8_f32 v84, v84, v85
	s_nop 0
	v_cvt_pk_fp8_f32 v84, v86, v87 op_sel:[0,0,1]
	v_cvt_pk_fp8_f32 v85, v88, v89
	s_nop 0
	v_cvt_pk_fp8_f32 v85, v90, v91 op_sel:[0,0,1]
	v_cvt_pk_fp8_f32 v86, v92, v93
	s_nop 0
	v_cvt_pk_fp8_f32 v86, v94, v95 op_sel:[0,0,1]
	v_cvt_pk_fp8_f32 v87, v96, v97
	s_nop 0
	v_cvt_pk_fp8_f32 v87, v98, v99 op_sel:[0,0,1]
	s_waitcnt vmcnt(8)
	s_nop 1
	v_mfma_f32_16x16x32_fp8_fp8 v[148:151], v[52:53], v[84:85], v[148:151]
	v_mfma_f32_16x16x32_fp8_fp8 v[152:155], v[54:55], v[84:85], v[152:155]
	v_mfma_f32_16x16x32_fp8_fp8 v[156:159], v[56:57], v[84:85], v[156:159]
	v_mfma_f32_16x16x32_fp8_fp8 v[160:163], v[58:59], v[84:85], v[160:163]
	v_mfma_f32_16x16x32_fp8_fp8 v[148:151], v[60:61], v[86:87], v[148:151]
	v_mfma_f32_16x16x32_fp8_fp8 v[152:155], v[62:63], v[86:87], v[152:155]
	v_mfma_f32_16x16x32_fp8_fp8 v[156:159], v[64:65], v[86:87], v[156:159]
	v_mfma_f32_16x16x32_fp8_fp8 v[160:163], v[66:67], v[86:87], v[160:163]
	s_branch .Lbm2_Bg3_skip

.Lbm2_done:
	s_waitcnt vmcnt(0)
	v_and_b32_e32 v245, 15, v181
	v_lshrrev_b32_e32 v246, 4, v181
	v_lshrrev_b32_e32 v247, 2, v245
	v_add_u32_e32 v247, s23, v247
	v_lshlrev_b32_e32 v245, 8, v245
	v_lshl_add_u32 v245, v246, 4, v245
	v_add_u32_e32 v200, s96, v245
	v_mad_u64_u32 v[250:251], s[50:51], v247, v213, v[74:75]
	global_load_dword v252, v[250:251], off offset:4
	v_add_u32_e32 v246, 4, v247
	v_mad_u64_u32 v[250:251], s[50:51], v246, v213, v[74:75]
	global_load_dword v253, v[250:251], off offset:4
	v_add_u32_e32 v246, 8, v247
	v_mad_u64_u32 v[250:251], s[50:51], v246, v213, v[74:75]
	global_load_dword v254, v[250:251], off offset:4
	v_add_u32_e32 v246, 12, v247
	v_mad_u64_u32 v[250:251], s[50:51], v246, v213, v[74:75]
	global_load_dword v255, v[250:251], off offset:4
	v_mov_b32_e32 v199, v194
	s_nop 1
	v_permlane16_swap_b32_e32 v194, v199
	s_nop 0
	v_add_f32_e32 v194, v194, v199
	v_mov_b32_e32 v199, v194
	s_nop 1
	v_permlane32_swap_b32_e32 v194, v199
	s_nop 0
	v_add_f32_e32 v194, v194, v199
	v_max_f32_e32 v194, 0xda24260, v194
	v_mov_b32_e32 v199, v195
	s_nop 1
	v_permlane16_swap_b32_e32 v195, v199
	s_nop 0
	v_add_f32_e32 v195, v195, v199
	v_mov_b32_e32 v199, v195
	s_nop 1
	v_permlane32_swap_b32_e32 v195, v199
	s_nop 0
	v_add_f32_e32 v195, v195, v199
	v_max_f32_e32 v195, 0xda24260, v195
	v_mov_b32_e32 v199, v196
	s_nop 1
	v_permlane16_swap_b32_e32 v196, v199
	s_nop 0
	v_add_f32_e32 v196, v196, v199
	v_mov_b32_e32 v199, v196
	s_nop 1
	v_permlane32_swap_b32_e32 v196, v199
	s_nop 0
	v_add_f32_e32 v196, v196, v199
	v_max_f32_e32 v196, 0xda24260, v196
	v_mov_b32_e32 v199, v197
	s_nop 1
	v_permlane16_swap_b32_e32 v197, v199
	s_nop 0
	v_add_f32_e32 v197, v197, v199
	v_mov_b32_e32 v199, v197
	s_nop 1
	v_permlane32_swap_b32_e32 v197, v199
	s_nop 0
	v_add_f32_e32 v197, v197, v199
	v_max_f32_e32 v197, 0xda24260, v197
	s_waitcnt vmcnt(0)
	v_div_scale_f32 v2, s[50:51], v194, v194, v252
	v_rcp_f32_e32 v3, v2
	s_nop 0
	v_fma_f32 v4, -v2, v3, 1.0
	v_fmac_f32_e32 v3, v4, v3
	v_div_scale_f32 v4, vcc, v252, v194, v252
	v_mul_f32_e32 v5, v4, v3
	v_fma_f32 v6, -v2, v5, v4
	v_fmac_f32_e32 v5, v6, v3
	v_fma_f32 v2, -v2, v5, v4
	v_div_fmas_f32 v2, v2, v3, v5
	v_div_fixup_f32 v248, v2, v194, v252
	ds_read_b128 v[16:19], v200 offset:0
	s_waitcnt lgkmcnt(0)
	v_pk_fma_f32 v[100:101], v[100:101], v[248:249], v[16:17] op_sel_hi:[1,0,1]
	v_pk_fma_f32 v[102:103], v[102:103], v[248:249], v[18:19] op_sel_hi:[1,0,1]
	ds_write_b128 v200, v[100:103] offset:0
	ds_read_b128 v[16:19], v200 offset:64
	s_waitcnt lgkmcnt(0)
	v_pk_fma_f32 v[104:105], v[104:105], v[248:249], v[16:17] op_sel_hi:[1,0,1]
	v_pk_fma_f32 v[106:107], v[106:107], v[248:249], v[18:19] op_sel_hi:[1,0,1]
	ds_write_b128 v200, v[104:107] offset:64
	ds_read_b128 v[16:19], v200 offset:128
	s_waitcnt lgkmcnt(0)
	v_pk_fma_f32 v[108:109], v[108:109], v[248:249], v[16:17] op_sel_hi:[1,0,1]
	v_pk_fma_f32 v[110:111], v[110:111], v[248:249], v[18:19] op_sel_hi:[1,0,1]
	ds_write_b128 v200, v[108:111] offset:128
	ds_read_b128 v[16:19], v200 offset:192
	s_waitcnt lgkmcnt(0)
	v_pk_fma_f32 v[112:113], v[112:113], v[248:249], v[16:17] op_sel_hi:[1,0,1]
	v_pk_fma_f32 v[114:115], v[114:115], v[248:249], v[18:19] op_sel_hi:[1,0,1]
	ds_write_b128 v200, v[112:115] offset:192
	v_div_scale_f32 v2, s[50:51], v195, v195, v253
	v_rcp_f32_e32 v3, v2
	s_nop 0
	v_fma_f32 v4, -v2, v3, 1.0
	v_fmac_f32_e32 v3, v4, v3
	v_div_scale_f32 v4, vcc, v253, v195, v253
	v_mul_f32_e32 v5, v4, v3
	v_fma_f32 v6, -v2, v5, v4
	v_fmac_f32_e32 v5, v6, v3
	v_fma_f32 v2, -v2, v5, v4
	v_div_fmas_f32 v2, v2, v3, v5
	v_div_fixup_f32 v248, v2, v195, v253
	ds_read_b128 v[16:19], v200 offset:4096
	s_waitcnt lgkmcnt(0)
	v_pk_fma_f32 v[116:117], v[116:117], v[248:249], v[16:17] op_sel_hi:[1,0,1]
	v_pk_fma_f32 v[118:119], v[118:119], v[248:249], v[18:19] op_sel_hi:[1,0,1]
	ds_write_b128 v200, v[116:119] offset:4096
	ds_read_b128 v[16:19], v200 offset:4160
	s_waitcnt lgkmcnt(0)
	v_pk_fma_f32 v[120:121], v[120:121], v[248:249], v[16:17] op_sel_hi:[1,0,1]
	v_pk_fma_f32 v[122:123], v[122:123], v[248:249], v[18:19] op_sel_hi:[1,0,1]
	ds_write_b128 v200, v[120:123] offset:4160
	ds_read_b128 v[16:19], v200 offset:4224
	s_waitcnt lgkmcnt(0)
	v_pk_fma_f32 v[124:125], v[124:125], v[248:249], v[16:17] op_sel_hi:[1,0,1]
	v_pk_fma_f32 v[126:127], v[126:127], v[248:249], v[18:19] op_sel_hi:[1,0,1]
	ds_write_b128 v200, v[124:127] offset:4224
	ds_read_b128 v[16:19], v200 offset:4288
	s_waitcnt lgkmcnt(0)
	v_pk_fma_f32 v[128:129], v[128:129], v[248:249], v[16:17] op_sel_hi:[1,0,1]
	v_pk_fma_f32 v[130:131], v[130:131], v[248:249], v[18:19] op_sel_hi:[1,0,1]
	ds_write_b128 v200, v[128:131] offset:4288
	v_div_scale_f32 v2, s[50:51], v196, v196, v254
	v_rcp_f32_e32 v3, v2
	s_nop 0
	v_fma_f32 v4, -v2, v3, 1.0
	v_fmac_f32_e32 v3, v4, v3
	v_div_scale_f32 v4, vcc, v254, v196, v254
	v_mul_f32_e32 v5, v4, v3
	v_fma_f32 v6, -v2, v5, v4
	v_fmac_f32_e32 v5, v6, v3
	v_fma_f32 v2, -v2, v5, v4
	v_div_fmas_f32 v2, v2, v3, v5
	v_div_fixup_f32 v248, v2, v196, v254
	ds_read_b128 v[16:19], v200 offset:8192
	s_waitcnt lgkmcnt(0)
	v_pk_fma_f32 v[132:133], v[132:133], v[248:249], v[16:17] op_sel_hi:[1,0,1]
	v_pk_fma_f32 v[134:135], v[134:135], v[248:249], v[18:19] op_sel_hi:[1,0,1]
	ds_write_b128 v200, v[132:135] offset:8192
	ds_read_b128 v[16:19], v200 offset:8256
	s_waitcnt lgkmcnt(0)
	v_pk_fma_f32 v[136:137], v[136:137], v[248:249], v[16:17] op_sel_hi:[1,0,1]
	v_pk_fma_f32 v[138:139], v[138:139], v[248:249], v[18:19] op_sel_hi:[1,0,1]
	ds_write_b128 v200, v[136:139] offset:8256
	ds_read_b128 v[16:19], v200 offset:8320
	s_waitcnt lgkmcnt(0)
	v_pk_fma_f32 v[140:141], v[140:141], v[248:249], v[16:17] op_sel_hi:[1,0,1]
	v_pk_fma_f32 v[142:143], v[142:143], v[248:249], v[18:19] op_sel_hi:[1,0,1]
	ds_write_b128 v200, v[140:143] offset:8320
	ds_read_b128 v[16:19], v200 offset:8384
	s_waitcnt lgkmcnt(0)
	v_pk_fma_f32 v[144:145], v[144:145], v[248:249], v[16:17] op_sel_hi:[1,0,1]
	v_pk_fma_f32 v[146:147], v[146:147], v[248:249], v[18:19] op_sel_hi:[1,0,1]
	ds_write_b128 v200, v[144:147] offset:8384
	v_div_scale_f32 v2, s[50:51], v197, v197, v255
	v_rcp_f32_e32 v3, v2
	s_nop 0
	v_fma_f32 v4, -v2, v3, 1.0
	v_fmac_f32_e32 v3, v4, v3
	v_div_scale_f32 v4, vcc, v255, v197, v255
	v_mul_f32_e32 v5, v4, v3
	v_fma_f32 v6, -v2, v5, v4
	v_fmac_f32_e32 v5, v6, v3
	v_fma_f32 v2, -v2, v5, v4
	v_div_fmas_f32 v2, v2, v3, v5
	v_div_fixup_f32 v248, v2, v197, v255
	ds_read_b128 v[16:19], v200 offset:12288
	s_waitcnt lgkmcnt(0)
	v_pk_fma_f32 v[148:149], v[148:149], v[248:249], v[16:17] op_sel_hi:[1,0,1]
	v_pk_fma_f32 v[150:151], v[150:151], v[248:249], v[18:19] op_sel_hi:[1,0,1]
	ds_write_b128 v200, v[148:151] offset:12288
	ds_read_b128 v[16:19], v200 offset:12352
	s_waitcnt lgkmcnt(0)
	v_pk_fma_f32 v[152:153], v[152:153], v[248:249], v[16:17] op_sel_hi:[1,0,1]
	v_pk_fma_f32 v[154:155], v[154:155], v[248:249], v[18:19] op_sel_hi:[1,0,1]
	ds_write_b128 v200, v[152:155] offset:12352
	ds_read_b128 v[16:19], v200 offset:12416
	s_waitcnt lgkmcnt(0)
	v_pk_fma_f32 v[156:157], v[156:157], v[248:249], v[16:17] op_sel_hi:[1,0,1]
	v_pk_fma_f32 v[158:159], v[158:159], v[248:249], v[18:19] op_sel_hi:[1,0,1]
	ds_write_b128 v200, v[156:159] offset:12416
	ds_read_b128 v[16:19], v200 offset:12480
	s_waitcnt lgkmcnt(0)
	v_pk_fma_f32 v[160:161], v[160:161], v[248:249], v[16:17] op_sel_hi:[1,0,1]
	v_pk_fma_f32 v[162:163], v[162:163], v[248:249], v[18:19] op_sel_hi:[1,0,1]
	ds_write_b128 v200, v[160:163] offset:12480
	s_waitcnt lgkmcnt(0)
	s_branch .LBB0_1588

.LBB0_2049:
.LBB0_2050:
	v_readfirstlane_b32 s40, v70
	v_readfirstlane_b32 s41, v71
	v_readfirstlane_b32 s62, v72
	v_readfirstlane_b32 s63, v73
	v_and_b32_e32 v248, 15, v181
	v_lshrrev_b32_e32 v249, 4, v181
	v_lshrrev_b32_e32 v248, 2, v248
	v_lshlrev_b32_e32 v249, 2, v249
	v_readlane_b32 s23, v243, 32
	v_mov_b32_e32 v244, 1
	v_lshlrev_b32_e32 v244, v248, v244
	s_mov_b32 s10, 0x3e38aa3b
	s_mov_b32 s11, 0x3e38aa3b
	v_lshlrev_b32_e32 v79, 4, v181
	s_add_i32 s23, s23, s47
	v_add_u32_e32 v247, s23, v248
	v_mad_u64_u32 v[250:251], s[6:7], v247, v212, v[68:69]
	global_load_dwordx4 v[100:103], v[250:251], off
	global_load_dwordx4 v[104:107], v[250:251], off offset:64
	v_add_u32_e32 v249, 4, v247
	v_mad_u64_u32 v[250:251], s[6:7], v249, v212, v[68:69]
	global_load_dwordx4 v[108:111], v[250:251], off
	global_load_dwordx4 v[112:115], v[250:251], off offset:64
	v_add_u32_e32 v249, 8, v247
	v_mad_u64_u32 v[250:251], s[6:7], v249, v212, v[68:69]
	global_load_dwordx4 v[116:119], v[250:251], off
	global_load_dwordx4 v[120:123], v[250:251], off offset:64
	v_add_u32_e32 v249, 12, v247
	v_mad_u64_u32 v[250:251], s[6:7], v249, v212, v[68:69]
	global_load_dwordx4 v[124:127], v[250:251], off
	global_load_dwordx4 v[128:131], v[250:251], off offset:64
	v_and_b32_e32 v248, 15, v181
	v_lshrrev_b32_e32 v249, 4, v181
	v_lshlrev_b32_e32 v198, 6, v248
	v_lshl_add_u32 v198, v249, 2, v198
	v_add_u32_e32 v198, s46, v198
	v_lshl_add_u32 v199, v248, 2, s46
	ds_read_b32 v12, v198 offset:16384
	ds_read_b32 v13, v198 offset:16400
	ds_read_b32 v14, v198 offset:16416
	ds_read_b32 v15, v198 offset:16432
	ds_read_b32 v16, v199 offset:17408
	v_lshl_add_u32 v199, v181, 2, s46
	v_mov_b32_e32 v17, 1
	v_lshlrev_b32_e32 v17, v248, v17
	s_waitcnt lgkmcnt(0)
	v_mul_f32_e32 v81, 0x3fb8aa3b, v81
	ds_write_b32 v199, v11 offset:16384
	ds_write_b32 v199, v11 offset:16640
	ds_write_b32 v199, v11 offset:16896
	ds_write_b32 v199, v11 offset:17152
	v_cmp_lt_i32_e32 vcc, v249, v16
	v_and_b32_e32 v12, 0xff, v12
	v_lshl_add_u32 v12, v12, 2, s46
	v_cndmask_b32_e32 v18, 0, v17, vcc
	ds_or_b32 v12, v18 offset:16384
	v_add_u32_e32 v18, 4, v249
	v_cmp_lt_i32_e32 vcc, v18, v16
	v_and_b32_e32 v13, 0xff, v13
	v_lshl_add_u32 v13, v13, 2, s46
	v_cndmask_b32_e32 v18, 0, v17, vcc
	ds_or_b32 v13, v18 offset:16384
	v_add_u32_e32 v18, 8, v249
	v_cmp_lt_i32_e32 vcc, v18, v16
	v_and_b32_e32 v14, 0xff, v14
	v_lshl_add_u32 v14, v14, 2, s46
	v_cndmask_b32_e32 v18, 0, v17, vcc
	ds_or_b32 v14, v18 offset:16384
	v_add_u32_e32 v18, 12, v249
	v_cmp_lt_i32_e32 vcc, v18, v16
	v_and_b32_e32 v15, 0xff, v15
	v_lshl_add_u32 v15, v15, 2, s46
	v_cndmask_b32_e32 v18, 0, v17, vcc
	ds_or_b32 v15, v18 offset:16384
	s_waitcnt lgkmcnt(0)
	ds_read_b32 v12, v199 offset:16384
	ds_read_b32 v13, v199 offset:16640
	ds_read_b32 v14, v199 offset:16896
	ds_read_b32 v15, v199 offset:17152
	s_mov_b32 s25, 0
	s_waitcnt lgkmcnt(0)
	v_cmp_ne_u32_e64 s[4:5], 0, v12
	v_lshlrev_b32_e32 v16, 16, v12
	v_add_u32_e32 v17, 0, v181
	v_or_b32_e32 v16, v16, v17
	v_mbcnt_lo_u32_b32 v17, s4, 0
	v_mbcnt_hi_u32_b32 v17, s5, v17
	v_add_u32_e32 v17, s25, v17
	v_lshl_add_u32 v17, v17, 2, s46
	v_add_u32_e32 v17, 0x4000, v17
	v_add_u32_e32 v18, 0x4400, v199
	s_bcnt1_i32_b64 s9, s[4:5]
	v_cndmask_b32_e64 v17, v18, v17, s[4:5]
	s_add_i32 s25, s25, s9
	ds_write_b32 v17, v16
	v_cmp_ne_u32_e64 s[4:5], 0, v13
	v_lshlrev_b32_e32 v16, 16, v13
	v_add_u32_e32 v17, 64, v181
	v_or_b32_e32 v16, v16, v17
	v_mbcnt_lo_u32_b32 v17, s4, 0
	v_mbcnt_hi_u32_b32 v17, s5, v17
	v_add_u32_e32 v17, s25, v17
	v_lshl_add_u32 v17, v17, 2, s46
	v_add_u32_e32 v17, 0x4000, v17
	v_add_u32_e32 v18, 0x4400, v199
	s_bcnt1_i32_b64 s9, s[4:5]
	v_cndmask_b32_e64 v17, v18, v17, s[4:5]
	s_add_i32 s25, s25, s9
	ds_write_b32 v17, v16
	v_cmp_ne_u32_e64 s[4:5], 0, v14
	v_lshlrev_b32_e32 v16, 16, v14
	v_add_u32_e32 v17, 128, v181
	v_or_b32_e32 v16, v16, v17
	v_mbcnt_lo_u32_b32 v17, s4, 0
	v_mbcnt_hi_u32_b32 v17, s5, v17
	v_add_u32_e32 v17, s25, v17
	v_lshl_add_u32 v17, v17, 2, s46
	v_add_u32_e32 v17, 0x4000, v17
	v_add_u32_e32 v18, 0x4400, v199
	s_bcnt1_i32_b64 s9, s[4:5]
	v_cndmask_b32_e64 v17, v18, v17, s[4:5]
	s_add_i32 s25, s25, s9
	ds_write_b32 v17, v16
	v_cmp_ne_u32_e64 s[4:5], 0, v15
	v_lshlrev_b32_e32 v16, 16, v15
	v_add_u32_e32 v17, 192, v181
	v_or_b32_e32 v16, v16, v17
	v_mbcnt_lo_u32_b32 v17, s4, 0
	v_mbcnt_hi_u32_b32 v17, s5, v17
	v_add_u32_e32 v17, s25, v17
	v_lshl_add_u32 v17, v17, 2, s46
	v_add_u32_e32 v17, 0x4000, v17
	v_add_u32_e32 v18, 0x4400, v199
	s_bcnt1_i32_b64 s9, s[4:5]
	v_cndmask_b32_e64 v17, v18, v17, s[4:5]
	s_add_i32 s25, s25, s9
	ds_write_b32 v17, v16
	s_waitcnt vmcnt(0)
	v_lshlrev_b32_e32 v245, 16, v100
	v_and_b32_e32 v246, 0xffff0000, v100
	v_mul_f32_e32 v245, 0x41000000, v245
	v_mul_f32_e32 v246, 0x41000000, v246
	v_lshlrev_b32_e32 v248, 16, v101
	v_and_b32_e32 v249, 0xffff0000, v101
	v_cvt_pk_fp8_f32 v164, v245, v246
	v_mul_f32_e32 v248, 0x41000000, v248
	v_mul_f32_e32 v249, 0x41000000, v249
	s_nop 0
	v_cvt_pk_fp8_f32 v164, v248, v249 op_sel:[0,0,1]
	v_lshlrev_b32_e32 v245, 16, v102
	v_and_b32_e32 v246, 0xffff0000, v102
	v_mul_f32_e32 v245, 0x41000000, v245
	v_mul_f32_e32 v246, 0x41000000, v246
	v_lshlrev_b32_e32 v248, 16, v103
	v_and_b32_e32 v249, 0xffff0000, v103
	v_cvt_pk_fp8_f32 v165, v245, v246
	v_mul_f32_e32 v248, 0x41000000, v248
	v_mul_f32_e32 v249, 0x41000000, v249
	s_nop 0
	v_cvt_pk_fp8_f32 v165, v248, v249 op_sel:[0,0,1]
	v_lshlrev_b32_e32 v245, 16, v104
	v_and_b32_e32 v246, 0xffff0000, v104
	v_mul_f32_e32 v245, 0x41000000, v245
	v_mul_f32_e32 v246, 0x41000000, v246
	v_lshlrev_b32_e32 v248, 16, v105
	v_and_b32_e32 v249, 0xffff0000, v105
	v_cvt_pk_fp8_f32 v166, v245, v246
	v_mul_f32_e32 v248, 0x41000000, v248
	v_mul_f32_e32 v249, 0x41000000, v249
	s_nop 0
	v_cvt_pk_fp8_f32 v166, v248, v249 op_sel:[0,0,1]
	v_lshlrev_b32_e32 v245, 16, v106
	v_and_b32_e32 v246, 0xffff0000, v106
	v_mul_f32_e32 v245, 0x41000000, v245
	v_mul_f32_e32 v246, 0x41000000, v246
	v_lshlrev_b32_e32 v248, 16, v107
	v_and_b32_e32 v249, 0xffff0000, v107
	v_cvt_pk_fp8_f32 v167, v245, v246
	v_mul_f32_e32 v248, 0x41000000, v248
	v_mul_f32_e32 v249, 0x41000000, v249
	s_nop 0
	v_cvt_pk_fp8_f32 v167, v248, v249 op_sel:[0,0,1]
	v_lshlrev_b32_e32 v245, 16, v108
	v_and_b32_e32 v246, 0xffff0000, v108
	v_mul_f32_e32 v245, 0x41000000, v245
	v_mul_f32_e32 v246, 0x41000000, v246
	v_lshlrev_b32_e32 v248, 16, v109
	v_and_b32_e32 v249, 0xffff0000, v109
	v_cvt_pk_fp8_f32 v168, v245, v246
	v_mul_f32_e32 v248, 0x41000000, v248
	v_mul_f32_e32 v249, 0x41000000, v249
	s_nop 0
	v_cvt_pk_fp8_f32 v168, v248, v249 op_sel:[0,0,1]
	v_lshlrev_b32_e32 v245, 16, v110
	v_and_b32_e32 v246, 0xffff0000, v110
	v_mul_f32_e32 v245, 0x41000000, v245
	v_mul_f32_e32 v246, 0x41000000, v246
	v_lshlrev_b32_e32 v248, 16, v111
	v_and_b32_e32 v249, 0xffff0000, v111
	v_cvt_pk_fp8_f32 v169, v245, v246
	v_mul_f32_e32 v248, 0x41000000, v248
	v_mul_f32_e32 v249, 0x41000000, v249
	s_nop 0
	v_cvt_pk_fp8_f32 v169, v248, v249 op_sel:[0,0,1]
	v_lshlrev_b32_e32 v245, 16, v112
	v_and_b32_e32 v246, 0xffff0000, v112
	v_mul_f32_e32 v245, 0x41000000, v245
	v_mul_f32_e32 v246, 0x41000000, v246
	v_lshlrev_b32_e32 v248, 16, v113
	v_and_b32_e32 v249, 0xffff0000, v113
	v_cvt_pk_fp8_f32 v170, v245, v246
	v_mul_f32_e32 v248, 0x41000000, v248
	v_mul_f32_e32 v249, 0x41000000, v249
	s_nop 0
	v_cvt_pk_fp8_f32 v170, v248, v249 op_sel:[0,0,1]
	v_lshlrev_b32_e32 v245, 16, v114
	v_and_b32_e32 v246, 0xffff0000, v114
	v_mul_f32_e32 v245, 0x41000000, v245
	v_mul_f32_e32 v246, 0x41000000, v246
	v_lshlrev_b32_e32 v248, 16, v115
	v_and_b32_e32 v249, 0xffff0000, v115
	v_cvt_pk_fp8_f32 v171, v245, v246
	v_mul_f32_e32 v248, 0x41000000, v248
	v_mul_f32_e32 v249, 0x41000000, v249
	s_nop 0
	v_cvt_pk_fp8_f32 v171, v248, v249 op_sel:[0,0,1]
	v_lshlrev_b32_e32 v245, 16, v116
	v_and_b32_e32 v246, 0xffff0000, v116
	v_mul_f32_e32 v245, 0x41000000, v245
	v_mul_f32_e32 v246, 0x41000000, v246
	v_lshlrev_b32_e32 v248, 16, v117
	v_and_b32_e32 v249, 0xffff0000, v117
	v_cvt_pk_fp8_f32 v182, v245, v246
	v_mul_f32_e32 v248, 0x41000000, v248
	v_mul_f32_e32 v249, 0x41000000, v249
	s_nop 0
	v_cvt_pk_fp8_f32 v182, v248, v249 op_sel:[0,0,1]
	v_lshlrev_b32_e32 v245, 16, v118
	v_and_b32_e32 v246, 0xffff0000, v118
	v_mul_f32_e32 v245, 0x41000000, v245
	v_mul_f32_e32 v246, 0x41000000, v246
	v_lshlrev_b32_e32 v248, 16, v119
	v_and_b32_e32 v249, 0xffff0000, v119
	v_cvt_pk_fp8_f32 v183, v245, v246
	v_mul_f32_e32 v248, 0x41000000, v248
	v_mul_f32_e32 v249, 0x41000000, v249
	s_nop 0
	v_cvt_pk_fp8_f32 v183, v248, v249 op_sel:[0,0,1]
	v_lshlrev_b32_e32 v245, 16, v120
	v_and_b32_e32 v246, 0xffff0000, v120
	v_mul_f32_e32 v245, 0x41000000, v245
	v_mul_f32_e32 v246, 0x41000000, v246
	v_lshlrev_b32_e32 v248, 16, v121
	v_and_b32_e32 v249, 0xffff0000, v121
	v_cvt_pk_fp8_f32 v184, v245, v246
	v_mul_f32_e32 v248, 0x41000000, v248
	v_mul_f32_e32 v249, 0x41000000, v249
	s_nop 0
	v_cvt_pk_fp8_f32 v184, v248, v249 op_sel:[0,0,1]
	v_lshlrev_b32_e32 v245, 16, v122
	v_and_b32_e32 v246, 0xffff0000, v122
	v_mul_f32_e32 v245, 0x41000000, v245
	v_mul_f32_e32 v246, 0x41000000, v246
	v_lshlrev_b32_e32 v248, 16, v123
	v_and_b32_e32 v249, 0xffff0000, v123
	v_cvt_pk_fp8_f32 v185, v245, v246
	v_mul_f32_e32 v248, 0x41000000, v248
	v_mul_f32_e32 v249, 0x41000000, v249
	s_nop 0
	v_cvt_pk_fp8_f32 v185, v248, v249 op_sel:[0,0,1]
	v_lshlrev_b32_e32 v245, 16, v124
	v_and_b32_e32 v246, 0xffff0000, v124
	v_mul_f32_e32 v245, 0x41000000, v245
	v_mul_f32_e32 v246, 0x41000000, v246
	v_lshlrev_b32_e32 v248, 16, v125
	v_and_b32_e32 v249, 0xffff0000, v125
	v_cvt_pk_fp8_f32 v186, v245, v246
	v_mul_f32_e32 v248, 0x41000000, v248
	v_mul_f32_e32 v249, 0x41000000, v249
	s_nop 0
	v_cvt_pk_fp8_f32 v186, v248, v249 op_sel:[0,0,1]
	v_lshlrev_b32_e32 v245, 16, v126
	v_and_b32_e32 v246, 0xffff0000, v126
	v_mul_f32_e32 v245, 0x41000000, v245
	v_mul_f32_e32 v246, 0x41000000, v246
	v_lshlrev_b32_e32 v248, 16, v127
	v_and_b32_e32 v249, 0xffff0000, v127
	v_cvt_pk_fp8_f32 v187, v245, v246
	v_mul_f32_e32 v248, 0x41000000, v248
	v_mul_f32_e32 v249, 0x41000000, v249
	s_nop 0
	v_cvt_pk_fp8_f32 v187, v248, v249 op_sel:[0,0,1]
	v_lshlrev_b32_e32 v245, 16, v128
	v_and_b32_e32 v246, 0xffff0000, v128
	v_mul_f32_e32 v245, 0x41000000, v245
	v_mul_f32_e32 v246, 0x41000000, v246
	v_lshlrev_b32_e32 v248, 16, v129
	v_and_b32_e32 v249, 0xffff0000, v129
	v_cvt_pk_fp8_f32 v188, v245, v246
	v_mul_f32_e32 v248, 0x41000000, v248
	v_mul_f32_e32 v249, 0x41000000, v249
	s_nop 0
	v_cvt_pk_fp8_f32 v188, v248, v249 op_sel:[0,0,1]
	v_lshlrev_b32_e32 v245, 16, v130
	v_and_b32_e32 v246, 0xffff0000, v130
	v_mul_f32_e32 v245, 0x41000000, v245
	v_mul_f32_e32 v246, 0x41000000, v246
	v_lshlrev_b32_e32 v248, 16, v131
	v_and_b32_e32 v249, 0xffff0000, v131
	v_cvt_pk_fp8_f32 v189, v245, v246
	v_mul_f32_e32 v248, 0x41000000, v248
	v_mul_f32_e32 v249, 0x41000000, v249
	s_nop 0
	v_cvt_pk_fp8_f32 v189, v248, v249 op_sel:[0,0,1]
	v_mov_b64_e32 v[100:101], 0
	v_mov_b64_e32 v[102:103], 0
	v_mov_b64_e32 v[104:105], 0
	v_mov_b64_e32 v[106:107], 0
	v_mov_b64_e32 v[108:109], 0
	v_mov_b64_e32 v[110:111], 0
	v_mov_b64_e32 v[112:113], 0
	v_mov_b64_e32 v[114:115], 0
	v_mov_b32_e32 v190, 0
	v_mov_b32_e32 v194, 0
	v_mov_b64_e32 v[116:117], 0
	v_mov_b64_e32 v[118:119], 0
	v_mov_b64_e32 v[120:121], 0
	v_mov_b64_e32 v[122:123], 0
	v_mov_b64_e32 v[124:125], 0
	v_mov_b64_e32 v[126:127], 0
	v_mov_b64_e32 v[128:129], 0
	v_mov_b64_e32 v[130:131], 0
	v_mov_b32_e32 v191, 0
	v_mov_b32_e32 v195, 0
	v_mov_b64_e32 v[132:133], 0
	v_mov_b64_e32 v[134:135], 0
	v_mov_b64_e32 v[136:137], 0
	v_mov_b64_e32 v[138:139], 0
	v_mov_b64_e32 v[140:141], 0
	v_mov_b64_e32 v[142:143], 0
	v_mov_b64_e32 v[144:145], 0
	v_mov_b64_e32 v[146:147], 0
	v_mov_b32_e32 v192, 0
	v_mov_b32_e32 v196, 0
	v_mov_b64_e32 v[148:149], 0
	v_mov_b64_e32 v[150:151], 0
	v_mov_b64_e32 v[152:153], 0
	v_mov_b64_e32 v[154:155], 0
	v_mov_b64_e32 v[156:157], 0
	v_mov_b64_e32 v[158:159], 0
	v_mov_b64_e32 v[160:161], 0
	v_mov_b64_e32 v[162:163], 0
	v_mov_b32_e32 v193, 0
	v_mov_b32_e32 v197, 0
	v_mov_b32_e32 v77, 0xff800000
	v_mov_b32_e32 v78, 0xff800000
	s_waitcnt lgkmcnt(0)
	s_mov_b32 s35, 0
	s_lshl_b32 s9, s35, 2
	s_add_i32 s9, s9, s46
	v_mov_b32_e32 v76, s9
	ds_read_b32 v76, v76 offset:16384
	s_add_i32 s50, s25, -1
	s_min_i32 s50, s50, 1
	s_waitcnt lgkmcnt(0)
	v_readfirstlane_b32 s9, v76
	s_and_b32 s38, s9, 0xffff
	s_lshr_b32 s48, s9, 16
	s_lshl_b32 s9, s50, 2
	s_add_i32 s9, s9, s46
	v_mov_b32_e32 v76, s9
	ds_read_b32 v76, v76 offset:16384
	s_lshl_b32 s29, s38, 12
	s_add_u32 s30, s40, s29
	s_addc_u32 s31, s41, 0
	global_load_dwordx4 v[2:5], v79, s[30:31]
	global_load_dwordx4 v[6:9], v79, s[30:31] offset:1024
	global_load_dwordx4 v[12:15], v79, s[30:31] offset:2048
	global_load_dwordx4 v[16:19], v79, s[30:31] offset:3072
	s_lshl_b32 s29, s38, 12
	s_add_u32 s30, s62, s29
	s_addc_u32 s31, s63, 0
	global_load_dwordx4 v[36:39], v79, s[30:31]
	global_load_dwordx4 v[40:43], v79, s[30:31] offset:1024
	global_load_dwordx4 v[44:47], v79, s[30:31] offset:2048
	global_load_dwordx4 v[48:51], v79, s[30:31] offset:3072
	s_waitcnt lgkmcnt(0)
	v_readfirstlane_b32 s9, v76
	s_and_b32 s27, s9, 0xffff
	s_lshr_b32 s8, s9, 16
.Lbm3_blkA:
	s_lshl_b32 s29, s27, 12
	s_add_u32 s30, s40, s29
	s_addc_u32 s31, s41, 0
	global_load_dwordx4 v[20:23], v79, s[30:31]
	global_load_dwordx4 v[24:27], v79, s[30:31] offset:1024
	global_load_dwordx4 v[28:31], v79, s[30:31] offset:2048
	global_load_dwordx4 v[32:35], v79, s[30:31] offset:3072
	s_lshl_b32 s29, s27, 12
	s_add_u32 s30, s62, s29
	s_addc_u32 s31, s63, 0
	global_load_dwordx4 v[52:55], v79, s[30:31]
	global_load_dwordx4 v[56:59], v79, s[30:31] offset:1024
	global_load_dwordx4 v[60:63], v79, s[30:31] offset:2048
	global_load_dwordx4 v[64:67], v79, s[30:31] offset:3072
	s_add_i32 s50, s35, 2
	s_add_i32 s9, s25, -1
	s_min_i32 s50, s50, s9
	s_lshl_b32 s9, s50, 2
	s_add_i32 s9, s9, s46
	v_mov_b32_e32 v76, s9
	ds_read_b32 v76, v76 offset:16384
	s_cmp_ge_i32 s38, s21
	s_cselect_b32 s50, 1, 0
	s_bfe_u32 s29, s48, 0x40000
	s_cmp_eq_u32 s29, 0
	s_cbranch_scc1 .Lbm3_Ag0_skip
	s_waitcnt vmcnt(12)
	v_mfma_f32_16x16x32_fp8_fp8 v[84:87], v[2:3], v[164:165], 0
	v_mfma_f32_16x16x32_fp8_fp8 v[88:91], v[6:7], v[164:165], 0
	v_mfma_f32_16x16x32_fp8_fp8 v[92:95], v[12:13], v[164:165], 0
	v_mfma_f32_16x16x32_fp8_fp8 v[96:99], v[16:17], v[164:165], 0
	v_mfma_f32_16x16x32_fp8_fp8 v[84:87], v[4:5], v[166:167], v[84:87]
	v_mfma_f32_16x16x32_fp8_fp8 v[88:91], v[8:9], v[166:167], v[88:91]
	v_mfma_f32_16x16x32_fp8_fp8 v[92:95], v[14:15], v[166:167], v[92:95]
	v_mfma_f32_16x16x32_fp8_fp8 v[96:99], v[18:19], v[166:167], v[96:99]
	v_and_b32_e32 v199, s29, v244
	s_cmp_eq_u32 s50, 1
	v_cmp_ne_u32_e32 vcc, 0, v199
	s_cbranch_scc1 .Lbm3_Ag0_near
	v_add_f32_e32 v200, v81, v190
	v_cndmask_b32_e32 v200, v77, v200, vcc
	v_pk_fma_f32 v[84:85], v[84:85], s[10:11], v[200:201] op_sel_hi:[1,1,0]
	v_pk_fma_f32 v[86:87], v[86:87], s[10:11], v[200:201] op_sel_hi:[1,1,0]
	v_pk_fma_f32 v[88:89], v[88:89], s[10:11], v[200:201] op_sel_hi:[1,1,0]
	v_pk_fma_f32 v[90:91], v[90:91], s[10:11], v[200:201] op_sel_hi:[1,1,0]
	v_pk_fma_f32 v[92:93], v[92:93], s[10:11], v[200:201] op_sel_hi:[1,1,0]
	v_pk_fma_f32 v[94:95], v[94:95], s[10:11], v[200:201] op_sel_hi:[1,1,0]
	v_pk_fma_f32 v[96:97], v[96:97], s[10:11], v[200:201] op_sel_hi:[1,1,0]
	v_pk_fma_f32 v[98:99], v[98:99], s[10:11], v[200:201] op_sel_hi:[1,1,0]

.Lbm3_Ag0_near:
	s_lshl_b32 s9, s38, 6
	s_sub_i32 s9, s47, s9
	v_and_b32_e32 v245, 15, v181
	v_lshrrev_b32_e32 v246, 4, v181
	v_lshrrev_b32_e32 v245, 2, v245
	v_lshlrev_b32_e32 v246, 2, v246
	v_cndmask_b32_e32 v200, v77, v190, vcc
	v_sub_u32_e32 v245, v245, v246
	v_add_u32_e32 v198, s9, v245
	v_mov_b32_e32 v245, v198
	v_min_u32_e32 v248, 0x7f, v245
	v_lshl_add_u32 v248, v248, 2, v80
	ds_read_b32 v248, v248
	v_subrev_u32_e32 v246, 1, v198
	v_min_u32_e32 v249, 0x7f, v246
	v_lshl_add_u32 v249, v249, 2, v80
	ds_read_b32 v249, v249
	s_waitcnt lgkmcnt(0)
	v_fmamk_f32 v248, v248, 0x3fb8aa3b, v200
	v_cmp_le_i32_e32 vcc, 0, v245
	v_fmamk_f32 v84, v84, 0x3e38aa3b, v248
	s_nop 0
	v_cndmask_b32_e32 v84, v77, v84, vcc
	v_fmamk_f32 v249, v249, 0x3fb8aa3b, v200
	v_cmp_le_i32_e32 vcc, 0, v246
	v_fmamk_f32 v85, v85, 0x3e38aa3b, v249
	s_nop 0
	v_cndmask_b32_e32 v85, v77, v85, vcc
	v_subrev_u32_e32 v245, 2, v198
	v_min_u32_e32 v248, 0x7f, v245
	v_lshl_add_u32 v248, v248, 2, v80
	ds_read_b32 v248, v248
	v_subrev_u32_e32 v246, 3, v198
	v_min_u32_e32 v249, 0x7f, v246
	v_lshl_add_u32 v249, v249, 2, v80
	ds_read_b32 v249, v249
	s_waitcnt lgkmcnt(0)
	v_fmamk_f32 v248, v248, 0x3fb8aa3b, v200
	v_cmp_le_i32_e32 vcc, 0, v245
	v_fmamk_f32 v86, v86, 0x3e38aa3b, v248
	s_nop 0
	v_cndmask_b32_e32 v86, v77, v86, vcc
	v_fmamk_f32 v249, v249, 0x3fb8aa3b, v200
	v_cmp_le_i32_e32 vcc, 0, v246
	v_fmamk_f32 v87, v87, 0x3e38aa3b, v249
	s_nop 0
	v_cndmask_b32_e32 v87, v77, v87, vcc
	v_subrev_u32_e32 v245, 16, v198
	v_min_u32_e32 v248, 0x7f, v245
	v_lshl_add_u32 v248, v248, 2, v80
	ds_read_b32 v248, v248
	v_subrev_u32_e32 v246, 17, v198
	v_min_u32_e32 v249, 0x7f, v246
	v_lshl_add_u32 v249, v249, 2, v80
	ds_read_b32 v249, v249
	s_waitcnt lgkmcnt(0)
	v_fmamk_f32 v248, v248, 0x3fb8aa3b, v200
	v_cmp_le_i32_e32 vcc, 0, v245
	v_fmamk_f32 v88, v88, 0x3e38aa3b, v248
	s_nop 0
	v_cndmask_b32_e32 v88, v77, v88, vcc
	v_fmamk_f32 v249, v249, 0x3fb8aa3b, v200
	v_cmp_le_i32_e32 vcc, 0, v246
	v_fmamk_f32 v89, v89, 0x3e38aa3b, v249
	s_nop 0
	v_cndmask_b32_e32 v89, v77, v89, vcc
	v_subrev_u32_e32 v245, 18, v198
	v_min_u32_e32 v248, 0x7f, v245
	v_lshl_add_u32 v248, v248, 2, v80
	ds_read_b32 v248, v248
	v_subrev_u32_e32 v246, 19, v198
	v_min_u32_e32 v249, 0x7f, v246
	v_lshl_add_u32 v249, v249, 2, v80
	ds_read_b32 v249, v249
	s_waitcnt lgkmcnt(0)
	v_fmamk_f32 v248, v248, 0x3fb8aa3b, v200
	v_cmp_le_i32_e32 vcc, 0, v245
	v_fmamk_f32 v90, v90, 0x3e38aa3b, v248
	s_nop 0
	v_cndmask_b32_e32 v90, v77, v90, vcc
	v_fmamk_f32 v249, v249, 0x3fb8aa3b, v200
	v_cmp_le_i32_e32 vcc, 0, v246
	v_fmamk_f32 v91, v91, 0x3e38aa3b, v249
	s_nop 0
	v_cndmask_b32_e32 v91, v77, v91, vcc
	v_subrev_u32_e32 v245, 32, v198
	v_min_u32_e32 v248, 0x7f, v245
	v_lshl_add_u32 v248, v248, 2, v80
	ds_read_b32 v248, v248
	v_subrev_u32_e32 v246, 33, v198
	v_min_u32_e32 v249, 0x7f, v246
	v_lshl_add_u32 v249, v249, 2, v80
	ds_read_b32 v249, v249
	s_waitcnt lgkmcnt(0)
	v_fmamk_f32 v248, v248, 0x3fb8aa3b, v200
	v_cmp_le_i32_e32 vcc, 0, v245
	v_fmamk_f32 v92, v92, 0x3e38aa3b, v248
	s_nop 0
	v_cndmask_b32_e32 v92, v77, v92, vcc
	v_fmamk_f32 v249, v249, 0x3fb8aa3b, v200
	v_cmp_le_i32_e32 vcc, 0, v246
	v_fmamk_f32 v93, v93, 0x3e38aa3b, v249
	s_nop 0
	v_cndmask_b32_e32 v93, v77, v93, vcc
	v_subrev_u32_e32 v245, 34, v198
	v_min_u32_e32 v248, 0x7f, v245
	v_lshl_add_u32 v248, v248, 2, v80
	ds_read_b32 v248, v248
	v_subrev_u32_e32 v246, 35, v198
	v_min_u32_e32 v249, 0x7f, v246
	v_lshl_add_u32 v249, v249, 2, v80
	ds_read_b32 v249, v249
	s_waitcnt lgkmcnt(0)
	v_fmamk_f32 v248, v248, 0x3fb8aa3b, v200
	v_cmp_le_i32_e32 vcc, 0, v245
	v_fmamk_f32 v94, v94, 0x3e38aa3b, v248
	s_nop 0
	v_cndmask_b32_e32 v94, v77, v94, vcc
	v_fmamk_f32 v249, v249, 0x3fb8aa3b, v200
	v_cmp_le_i32_e32 vcc, 0, v246
	v_fmamk_f32 v95, v95, 0x3e38aa3b, v249
	s_nop 0
	v_cndmask_b32_e32 v95, v77, v95, vcc
	v_subrev_u32_e32 v245, 48, v198
	v_min_u32_e32 v248, 0x7f, v245
	v_lshl_add_u32 v248, v248, 2, v80
	ds_read_b32 v248, v248
	v_subrev_u32_e32 v246, 49, v198
	v_min_u32_e32 v249, 0x7f, v246
	v_lshl_add_u32 v249, v249, 2, v80
	ds_read_b32 v249, v249
	s_waitcnt lgkmcnt(0)
	v_fmamk_f32 v248, v248, 0x3fb8aa3b, v200
	v_cmp_le_i32_e32 vcc, 0, v245
	v_fmamk_f32 v96, v96, 0x3e38aa3b, v248
	s_nop 0
	v_cndmask_b32_e32 v96, v77, v96, vcc
	v_fmamk_f32 v249, v249, 0x3fb8aa3b, v200
	v_cmp_le_i32_e32 vcc, 0, v246
	v_fmamk_f32 v97, v97, 0x3e38aa3b, v249
	s_nop 0
	v_cndmask_b32_e32 v97, v77, v97, vcc
	v_subrev_u32_e32 v245, 50, v198
	v_min_u32_e32 v248, 0x7f, v245
	v_lshl_add_u32 v248, v248, 2, v80
	ds_read_b32 v248, v248
	v_subrev_u32_e32 v246, 51, v198
	v_min_u32_e32 v249, 0x7f, v246
	v_lshl_add_u32 v249, v249, 2, v80
	ds_read_b32 v249, v249
	s_waitcnt lgkmcnt(0)
	v_fmamk_f32 v248, v248, 0x3fb8aa3b, v200
	v_cmp_le_i32_e32 vcc, 0, v245
	v_fmamk_f32 v98, v98, 0x3e38aa3b, v248
	s_nop 0
	v_cndmask_b32_e32 v98, v77, v98, vcc
	v_fmamk_f32 v249, v249, 0x3fb8aa3b, v200
	v_cmp_le_i32_e32 vcc, 0, v246
	v_fmamk_f32 v99, v99, 0x3e38aa3b, v249
	s_nop 0
	v_cndmask_b32_e32 v99, v77, v99, vcc
	s_branch .Lbm3_Ag0_max
.Lbm3_Ag0_skip:
	s_bfe_u32 s29, s48, 0x40004
	s_cmp_eq_u32 s29, 0
	s_cbranch_scc1 .Lbm3_Ag1_skip
	s_waitcnt vmcnt(12)
	v_mfma_f32_16x16x32_fp8_fp8 v[84:87], v[2:3], v[168:169], 0
	v_mfma_f32_16x16x32_fp8_fp8 v[88:91], v[6:7], v[168:169], 0
	v_mfma_f32_16x16x32_fp8_fp8 v[92:95], v[12:13], v[168:169], 0
	v_mfma_f32_16x16x32_fp8_fp8 v[96:99], v[16:17], v[168:169], 0
	v_mfma_f32_16x16x32_fp8_fp8 v[84:87], v[4:5], v[170:171], v[84:87]
	v_mfma_f32_16x16x32_fp8_fp8 v[88:91], v[8:9], v[170:171], v[88:91]
	v_mfma_f32_16x16x32_fp8_fp8 v[92:95], v[14:15], v[170:171], v[92:95]
	v_mfma_f32_16x16x32_fp8_fp8 v[96:99], v[18:19], v[170:171], v[96:99]
	v_and_b32_e32 v199, s29, v244
	s_cmp_eq_u32 s50, 1
	v_cmp_ne_u32_e32 vcc, 0, v199
	s_cbranch_scc1 .Lbm3_Ag1_near
	v_add_f32_e32 v200, v81, v191
	v_cndmask_b32_e32 v200, v77, v200, vcc
	v_pk_fma_f32 v[84:85], v[84:85], s[10:11], v[200:201] op_sel_hi:[1,1,0]
	v_pk_fma_f32 v[86:87], v[86:87], s[10:11], v[200:201] op_sel_hi:[1,1,0]
	v_pk_fma_f32 v[88:89], v[88:89], s[10:11], v[200:201] op_sel_hi:[1,1,0]
	v_pk_fma_f32 v[90:91], v[90:91], s[10:11], v[200:201] op_sel_hi:[1,1,0]
	v_pk_fma_f32 v[92:93], v[92:93], s[10:11], v[200:201] op_sel_hi:[1,1,0]
	v_pk_fma_f32 v[94:95], v[94:95], s[10:11], v[200:201] op_sel_hi:[1,1,0]
	v_pk_fma_f32 v[96:97], v[96:97], s[10:11], v[200:201] op_sel_hi:[1,1,0]
	v_pk_fma_f32 v[98:99], v[98:99], s[10:11], v[200:201] op_sel_hi:[1,1,0]

.Lbm3_Ag1_near:
	s_lshl_b32 s9, s38, 6
	s_sub_i32 s9, s47, s9
	s_add_i32 s9, s9, 4
	v_and_b32_e32 v245, 15, v181
	v_lshrrev_b32_e32 v246, 4, v181
	v_lshrrev_b32_e32 v245, 2, v245
	v_lshlrev_b32_e32 v246, 2, v246
	v_cndmask_b32_e32 v200, v77, v191, vcc
	v_sub_u32_e32 v245, v245, v246
	v_add_u32_e32 v198, s9, v245
	v_mov_b32_e32 v245, v198
	v_min_u32_e32 v248, 0x7f, v245
	v_lshl_add_u32 v248, v248, 2, v80
	ds_read_b32 v248, v248
	v_subrev_u32_e32 v246, 1, v198
	v_min_u32_e32 v249, 0x7f, v246
	v_lshl_add_u32 v249, v249, 2, v80
	ds_read_b32 v249, v249
	s_waitcnt lgkmcnt(0)
	v_fmamk_f32 v248, v248, 0x3fb8aa3b, v200
	v_cmp_le_i32_e32 vcc, 0, v245
	v_fmamk_f32 v84, v84, 0x3e38aa3b, v248
	s_nop 0
	v_cndmask_b32_e32 v84, v77, v84, vcc
	v_fmamk_f32 v249, v249, 0x3fb8aa3b, v200
	v_cmp_le_i32_e32 vcc, 0, v246
	v_fmamk_f32 v85, v85, 0x3e38aa3b, v249
	s_nop 0
	v_cndmask_b32_e32 v85, v77, v85, vcc
	v_subrev_u32_e32 v245, 2, v198
	v_min_u32_e32 v248, 0x7f, v245
	v_lshl_add_u32 v248, v248, 2, v80
	ds_read_b32 v248, v248
	v_subrev_u32_e32 v246, 3, v198
	v_min_u32_e32 v249, 0x7f, v246
	v_lshl_add_u32 v249, v249, 2, v80
	ds_read_b32 v249, v249
	s_waitcnt lgkmcnt(0)
	v_fmamk_f32 v248, v248, 0x3fb8aa3b, v200
	v_cmp_le_i32_e32 vcc, 0, v245
	v_fmamk_f32 v86, v86, 0x3e38aa3b, v248
	s_nop 0
	v_cndmask_b32_e32 v86, v77, v86, vcc
	v_fmamk_f32 v249, v249, 0x3fb8aa3b, v200
	v_cmp_le_i32_e32 vcc, 0, v246
	v_fmamk_f32 v87, v87, 0x3e38aa3b, v249
	s_nop 0
	v_cndmask_b32_e32 v87, v77, v87, vcc
	v_subrev_u32_e32 v245, 16, v198
	v_min_u32_e32 v248, 0x7f, v245
	v_lshl_add_u32 v248, v248, 2, v80
	ds_read_b32 v248, v248
	v_subrev_u32_e32 v246, 17, v198
	v_min_u32_e32 v249, 0x7f, v246
	v_lshl_add_u32 v249, v249, 2, v80
	ds_read_b32 v249, v249
	s_waitcnt lgkmcnt(0)
	v_fmamk_f32 v248, v248, 0x3fb8aa3b, v200
	v_cmp_le_i32_e32 vcc, 0, v245
	v_fmamk_f32 v88, v88, 0x3e38aa3b, v248
	s_nop 0
	v_cndmask_b32_e32 v88, v77, v88, vcc
	v_fmamk_f32 v249, v249, 0x3fb8aa3b, v200
	v_cmp_le_i32_e32 vcc, 0, v246
	v_fmamk_f32 v89, v89, 0x3e38aa3b, v249
	s_nop 0
	v_cndmask_b32_e32 v89, v77, v89, vcc
	v_subrev_u32_e32 v245, 18, v198
	v_min_u32_e32 v248, 0x7f, v245
	v_lshl_add_u32 v248, v248, 2, v80
	ds_read_b32 v248, v248
	v_subrev_u32_e32 v246, 19, v198
	v_min_u32_e32 v249, 0x7f, v246
	v_lshl_add_u32 v249, v249, 2, v80
	ds_read_b32 v249, v249
	s_waitcnt lgkmcnt(0)
	v_fmamk_f32 v248, v248, 0x3fb8aa3b, v200
	v_cmp_le_i32_e32 vcc, 0, v245
	v_fmamk_f32 v90, v90, 0x3e38aa3b, v248
	s_nop 0
	v_cndmask_b32_e32 v90, v77, v90, vcc
	v_fmamk_f32 v249, v249, 0x3fb8aa3b, v200
	v_cmp_le_i32_e32 vcc, 0, v246
	v_fmamk_f32 v91, v91, 0x3e38aa3b, v249
	s_nop 0
	v_cndmask_b32_e32 v91, v77, v91, vcc
	v_subrev_u32_e32 v245, 32, v198
	v_min_u32_e32 v248, 0x7f, v245
	v_lshl_add_u32 v248, v248, 2, v80
	ds_read_b32 v248, v248
	v_subrev_u32_e32 v246, 33, v198
	v_min_u32_e32 v249, 0x7f, v246
	v_lshl_add_u32 v249, v249, 2, v80
	ds_read_b32 v249, v249
	s_waitcnt lgkmcnt(0)
	v_fmamk_f32 v248, v248, 0x3fb8aa3b, v200
	v_cmp_le_i32_e32 vcc, 0, v245
	v_fmamk_f32 v92, v92, 0x3e38aa3b, v248
	s_nop 0
	v_cndmask_b32_e32 v92, v77, v92, vcc
	v_fmamk_f32 v249, v249, 0x3fb8aa3b, v200
	v_cmp_le_i32_e32 vcc, 0, v246
	v_fmamk_f32 v93, v93, 0x3e38aa3b, v249
	s_nop 0
	v_cndmask_b32_e32 v93, v77, v93, vcc
	v_subrev_u32_e32 v245, 34, v198
	v_min_u32_e32 v248, 0x7f, v245
	v_lshl_add_u32 v248, v248, 2, v80
	ds_read_b32 v248, v248
	v_subrev_u32_e32 v246, 35, v198
	v_min_u32_e32 v249, 0x7f, v246
	v_lshl_add_u32 v249, v249, 2, v80
	ds_read_b32 v249, v249
	s_waitcnt lgkmcnt(0)
	v_fmamk_f32 v248, v248, 0x3fb8aa3b, v200
	v_cmp_le_i32_e32 vcc, 0, v245
	v_fmamk_f32 v94, v94, 0x3e38aa3b, v248
	s_nop 0
	v_cndmask_b32_e32 v94, v77, v94, vcc
	v_fmamk_f32 v249, v249, 0x3fb8aa3b, v200
	v_cmp_le_i32_e32 vcc, 0, v246
	v_fmamk_f32 v95, v95, 0x3e38aa3b, v249
	s_nop 0
	v_cndmask_b32_e32 v95, v77, v95, vcc
	v_subrev_u32_e32 v245, 48, v198
	v_min_u32_e32 v248, 0x7f, v245
	v_lshl_add_u32 v248, v248, 2, v80
	ds_read_b32 v248, v248
	v_subrev_u32_e32 v246, 49, v198
	v_min_u32_e32 v249, 0x7f, v246
	v_lshl_add_u32 v249, v249, 2, v80
	ds_read_b32 v249, v249
	s_waitcnt lgkmcnt(0)
	v_fmamk_f32 v248, v248, 0x3fb8aa3b, v200
	v_cmp_le_i32_e32 vcc, 0, v245
	v_fmamk_f32 v96, v96, 0x3e38aa3b, v248
	s_nop 0
	v_cndmask_b32_e32 v96, v77, v96, vcc
	v_fmamk_f32 v249, v249, 0x3fb8aa3b, v200
	v_cmp_le_i32_e32 vcc, 0, v246
	v_fmamk_f32 v97, v97, 0x3e38aa3b, v249
	s_nop 0
	v_cndmask_b32_e32 v97, v77, v97, vcc
	v_subrev_u32_e32 v245, 50, v198
	v_min_u32_e32 v248, 0x7f, v245
	v_lshl_add_u32 v248, v248, 2, v80
	ds_read_b32 v248, v248
	v_subrev_u32_e32 v246, 51, v198
	v_min_u32_e32 v249, 0x7f, v246
	v_lshl_add_u32 v249, v249, 2, v80
	ds_read_b32 v249, v249
	s_waitcnt lgkmcnt(0)
	v_fmamk_f32 v248, v248, 0x3fb8aa3b, v200
	v_cmp_le_i32_e32 vcc, 0, v245
	v_fmamk_f32 v98, v98, 0x3e38aa3b, v248
	s_nop 0
	v_cndmask_b32_e32 v98, v77, v98, vcc
	v_fmamk_f32 v249, v249, 0x3fb8aa3b, v200
	v_cmp_le_i32_e32 vcc, 0, v246
	v_fmamk_f32 v99, v99, 0x3e38aa3b, v249
	s_nop 0
	v_cndmask_b32_e32 v99, v77, v99, vcc
	s_branch .Lbm3_Ag1_max
.Lbm3_Ag1_skip:
	s_bfe_u32 s29, s48, 0x40008
	s_cmp_eq_u32 s29, 0
	s_cbranch_scc1 .Lbm3_Ag2_skip
	s_waitcnt vmcnt(12)
	v_mfma_f32_16x16x32_fp8_fp8 v[84:87], v[2:3], v[182:183], 0
	v_mfma_f32_16x16x32_fp8_fp8 v[88:91], v[6:7], v[182:183], 0
	v_mfma_f32_16x16x32_fp8_fp8 v[92:95], v[12:13], v[182:183], 0
	v_mfma_f32_16x16x32_fp8_fp8 v[96:99], v[16:17], v[182:183], 0
	v_mfma_f32_16x16x32_fp8_fp8 v[84:87], v[4:5], v[184:185], v[84:87]
	v_mfma_f32_16x16x32_fp8_fp8 v[88:91], v[8:9], v[184:185], v[88:91]
	v_mfma_f32_16x16x32_fp8_fp8 v[92:95], v[14:15], v[184:185], v[92:95]
	v_mfma_f32_16x16x32_fp8_fp8 v[96:99], v[18:19], v[184:185], v[96:99]
	v_and_b32_e32 v199, s29, v244
	s_cmp_eq_u32 s50, 1
	v_cmp_ne_u32_e32 vcc, 0, v199
	s_cbranch_scc1 .Lbm3_Ag2_near
	v_add_f32_e32 v200, v81, v192
	v_cndmask_b32_e32 v200, v77, v200, vcc
	v_pk_fma_f32 v[84:85], v[84:85], s[10:11], v[200:201] op_sel_hi:[1,1,0]
	v_pk_fma_f32 v[86:87], v[86:87], s[10:11], v[200:201] op_sel_hi:[1,1,0]
	v_pk_fma_f32 v[88:89], v[88:89], s[10:11], v[200:201] op_sel_hi:[1,1,0]
	v_pk_fma_f32 v[90:91], v[90:91], s[10:11], v[200:201] op_sel_hi:[1,1,0]
	v_pk_fma_f32 v[92:93], v[92:93], s[10:11], v[200:201] op_sel_hi:[1,1,0]
	v_pk_fma_f32 v[94:95], v[94:95], s[10:11], v[200:201] op_sel_hi:[1,1,0]
	v_pk_fma_f32 v[96:97], v[96:97], s[10:11], v[200:201] op_sel_hi:[1,1,0]
	v_pk_fma_f32 v[98:99], v[98:99], s[10:11], v[200:201] op_sel_hi:[1,1,0]

.Lbm3_Ag2_near:
	s_lshl_b32 s9, s38, 6
	s_sub_i32 s9, s47, s9
	s_add_i32 s9, s9, 8
	v_and_b32_e32 v245, 15, v181
	v_lshrrev_b32_e32 v246, 4, v181
	v_lshrrev_b32_e32 v245, 2, v245
	v_lshlrev_b32_e32 v246, 2, v246
	v_cndmask_b32_e32 v200, v77, v192, vcc
	v_sub_u32_e32 v245, v245, v246
	v_add_u32_e32 v198, s9, v245
	v_mov_b32_e32 v245, v198
	v_min_u32_e32 v248, 0x7f, v245
	v_lshl_add_u32 v248, v248, 2, v80
	ds_read_b32 v248, v248
	v_subrev_u32_e32 v246, 1, v198
	v_min_u32_e32 v249, 0x7f, v246
	v_lshl_add_u32 v249, v249, 2, v80
	ds_read_b32 v249, v249
	s_waitcnt lgkmcnt(0)
	v_fmamk_f32 v248, v248, 0x3fb8aa3b, v200
	v_cmp_le_i32_e32 vcc, 0, v245
	v_fmamk_f32 v84, v84, 0x3e38aa3b, v248
	s_nop 0
	v_cndmask_b32_e32 v84, v77, v84, vcc
	v_fmamk_f32 v249, v249, 0x3fb8aa3b, v200
	v_cmp_le_i32_e32 vcc, 0, v246
	v_fmamk_f32 v85, v85, 0x3e38aa3b, v249
	s_nop 0
	v_cndmask_b32_e32 v85, v77, v85, vcc
	v_subrev_u32_e32 v245, 2, v198
	v_min_u32_e32 v248, 0x7f, v245
	v_lshl_add_u32 v248, v248, 2, v80
	ds_read_b32 v248, v248
	v_subrev_u32_e32 v246, 3, v198
	v_min_u32_e32 v249, 0x7f, v246
	v_lshl_add_u32 v249, v249, 2, v80
	ds_read_b32 v249, v249
	s_waitcnt lgkmcnt(0)
	v_fmamk_f32 v248, v248, 0x3fb8aa3b, v200
	v_cmp_le_i32_e32 vcc, 0, v245
	v_fmamk_f32 v86, v86, 0x3e38aa3b, v248
	s_nop 0
	v_cndmask_b32_e32 v86, v77, v86, vcc
	v_fmamk_f32 v249, v249, 0x3fb8aa3b, v200
	v_cmp_le_i32_e32 vcc, 0, v246
	v_fmamk_f32 v87, v87, 0x3e38aa3b, v249
	s_nop 0
	v_cndmask_b32_e32 v87, v77, v87, vcc
	v_subrev_u32_e32 v245, 16, v198
	v_min_u32_e32 v248, 0x7f, v245
	v_lshl_add_u32 v248, v248, 2, v80
	ds_read_b32 v248, v248
	v_subrev_u32_e32 v246, 17, v198
	v_min_u32_e32 v249, 0x7f, v246
	v_lshl_add_u32 v249, v249, 2, v80
	ds_read_b32 v249, v249
	s_waitcnt lgkmcnt(0)
	v_fmamk_f32 v248, v248, 0x3fb8aa3b, v200
	v_cmp_le_i32_e32 vcc, 0, v245
	v_fmamk_f32 v88, v88, 0x3e38aa3b, v248
	s_nop 0
	v_cndmask_b32_e32 v88, v77, v88, vcc
	v_fmamk_f32 v249, v249, 0x3fb8aa3b, v200
	v_cmp_le_i32_e32 vcc, 0, v246
	v_fmamk_f32 v89, v89, 0x3e38aa3b, v249
	s_nop 0
	v_cndmask_b32_e32 v89, v77, v89, vcc
	v_subrev_u32_e32 v245, 18, v198
	v_min_u32_e32 v248, 0x7f, v245
	v_lshl_add_u32 v248, v248, 2, v80
	ds_read_b32 v248, v248
	v_subrev_u32_e32 v246, 19, v198
	v_min_u32_e32 v249, 0x7f, v246
	v_lshl_add_u32 v249, v249, 2, v80
	ds_read_b32 v249, v249
	s_waitcnt lgkmcnt(0)
	v_fmamk_f32 v248, v248, 0x3fb8aa3b, v200
	v_cmp_le_i32_e32 vcc, 0, v245
	v_fmamk_f32 v90, v90, 0x3e38aa3b, v248
	s_nop 0
	v_cndmask_b32_e32 v90, v77, v90, vcc
	v_fmamk_f32 v249, v249, 0x3fb8aa3b, v200
	v_cmp_le_i32_e32 vcc, 0, v246
	v_fmamk_f32 v91, v91, 0x3e38aa3b, v249
	s_nop 0
	v_cndmask_b32_e32 v91, v77, v91, vcc
	v_subrev_u32_e32 v245, 32, v198
	v_min_u32_e32 v248, 0x7f, v245
	v_lshl_add_u32 v248, v248, 2, v80
	ds_read_b32 v248, v248
	v_subrev_u32_e32 v246, 33, v198
	v_min_u32_e32 v249, 0x7f, v246
	v_lshl_add_u32 v249, v249, 2, v80
	ds_read_b32 v249, v249
	s_waitcnt lgkmcnt(0)
	v_fmamk_f32 v248, v248, 0x3fb8aa3b, v200
	v_cmp_le_i32_e32 vcc, 0, v245
	v_fmamk_f32 v92, v92, 0x3e38aa3b, v248
	s_nop 0
	v_cndmask_b32_e32 v92, v77, v92, vcc
	v_fmamk_f32 v249, v249, 0x3fb8aa3b, v200
	v_cmp_le_i32_e32 vcc, 0, v246
	v_fmamk_f32 v93, v93, 0x3e38aa3b, v249
	s_nop 0
	v_cndmask_b32_e32 v93, v77, v93, vcc
	v_subrev_u32_e32 v245, 34, v198
	v_min_u32_e32 v248, 0x7f, v245
	v_lshl_add_u32 v248, v248, 2, v80
	ds_read_b32 v248, v248
	v_subrev_u32_e32 v246, 35, v198
	v_min_u32_e32 v249, 0x7f, v246
	v_lshl_add_u32 v249, v249, 2, v80
	ds_read_b32 v249, v249
	s_waitcnt lgkmcnt(0)
	v_fmamk_f32 v248, v248, 0x3fb8aa3b, v200
	v_cmp_le_i32_e32 vcc, 0, v245
	v_fmamk_f32 v94, v94, 0x3e38aa3b, v248
	s_nop 0
	v_cndmask_b32_e32 v94, v77, v94, vcc
	v_fmamk_f32 v249, v249, 0x3fb8aa3b, v200
	v_cmp_le_i32_e32 vcc, 0, v246
	v_fmamk_f32 v95, v95, 0x3e38aa3b, v249
	s_nop 0
	v_cndmask_b32_e32 v95, v77, v95, vcc
	v_subrev_u32_e32 v245, 48, v198
	v_min_u32_e32 v248, 0x7f, v245
	v_lshl_add_u32 v248, v248, 2, v80
	ds_read_b32 v248, v248
	v_subrev_u32_e32 v246, 49, v198
	v_min_u32_e32 v249, 0x7f, v246
	v_lshl_add_u32 v249, v249, 2, v80
	ds_read_b32 v249, v249
	s_waitcnt lgkmcnt(0)
	v_fmamk_f32 v248, v248, 0x3fb8aa3b, v200
	v_cmp_le_i32_e32 vcc, 0, v245
	v_fmamk_f32 v96, v96, 0x3e38aa3b, v248
	s_nop 0
	v_cndmask_b32_e32 v96, v77, v96, vcc
	v_fmamk_f32 v249, v249, 0x3fb8aa3b, v200
	v_cmp_le_i32_e32 vcc, 0, v246
	v_fmamk_f32 v97, v97, 0x3e38aa3b, v249
	s_nop 0
	v_cndmask_b32_e32 v97, v77, v97, vcc
	v_subrev_u32_e32 v245, 50, v198
	v_min_u32_e32 v248, 0x7f, v245
	v_lshl_add_u32 v248, v248, 2, v80
	ds_read_b32 v248, v248
	v_subrev_u32_e32 v246, 51, v198
	v_min_u32_e32 v249, 0x7f, v246
	v_lshl_add_u32 v249, v249, 2, v80
	ds_read_b32 v249, v249
	s_waitcnt lgkmcnt(0)
	v_fmamk_f32 v248, v248, 0x3fb8aa3b, v200
	v_cmp_le_i32_e32 vcc, 0, v245
	v_fmamk_f32 v98, v98, 0x3e38aa3b, v248
	s_nop 0
	v_cndmask_b32_e32 v98, v77, v98, vcc
	v_fmamk_f32 v249, v249, 0x3fb8aa3b, v200
	v_cmp_le_i32_e32 vcc, 0, v246
	v_fmamk_f32 v99, v99, 0x3e38aa3b, v249
	s_nop 0
	v_cndmask_b32_e32 v99, v77, v99, vcc
	s_branch .Lbm3_Ag2_max
.Lbm3_Ag2_skip:
	s_bfe_u32 s29, s48, 0x4000c
	s_cmp_eq_u32 s29, 0
	s_cbranch_scc1 .Lbm3_Ag3_skip
	s_waitcnt vmcnt(12)
	v_mfma_f32_16x16x32_fp8_fp8 v[84:87], v[2:3], v[186:187], 0
	v_mfma_f32_16x16x32_fp8_fp8 v[88:91], v[6:7], v[186:187], 0
	v_mfma_f32_16x16x32_fp8_fp8 v[92:95], v[12:13], v[186:187], 0
	v_mfma_f32_16x16x32_fp8_fp8 v[96:99], v[16:17], v[186:187], 0
	v_mfma_f32_16x16x32_fp8_fp8 v[84:87], v[4:5], v[188:189], v[84:87]
	v_mfma_f32_16x16x32_fp8_fp8 v[88:91], v[8:9], v[188:189], v[88:91]
	v_mfma_f32_16x16x32_fp8_fp8 v[92:95], v[14:15], v[188:189], v[92:95]
	v_mfma_f32_16x16x32_fp8_fp8 v[96:99], v[18:19], v[188:189], v[96:99]
	v_and_b32_e32 v199, s29, v244
	s_cmp_eq_u32 s50, 1
	v_cmp_ne_u32_e32 vcc, 0, v199
	s_cbranch_scc1 .Lbm3_Ag3_near
	v_add_f32_e32 v200, v81, v193
	v_cndmask_b32_e32 v200, v77, v200, vcc
	v_pk_fma_f32 v[84:85], v[84:85], s[10:11], v[200:201] op_sel_hi:[1,1,0]
	v_pk_fma_f32 v[86:87], v[86:87], s[10:11], v[200:201] op_sel_hi:[1,1,0]
	v_pk_fma_f32 v[88:89], v[88:89], s[10:11], v[200:201] op_sel_hi:[1,1,0]
	v_pk_fma_f32 v[90:91], v[90:91], s[10:11], v[200:201] op_sel_hi:[1,1,0]
	v_pk_fma_f32 v[92:93], v[92:93], s[10:11], v[200:201] op_sel_hi:[1,1,0]
	v_pk_fma_f32 v[94:95], v[94:95], s[10:11], v[200:201] op_sel_hi:[1,1,0]
	v_pk_fma_f32 v[96:97], v[96:97], s[10:11], v[200:201] op_sel_hi:[1,1,0]
	v_pk_fma_f32 v[98:99], v[98:99], s[10:11], v[200:201] op_sel_hi:[1,1,0]

.Lbm3_Ag3_near:
	s_lshl_b32 s9, s38, 6
	s_sub_i32 s9, s47, s9
	s_add_i32 s9, s9, 12
	v_and_b32_e32 v245, 15, v181
	v_lshrrev_b32_e32 v246, 4, v181
	v_lshrrev_b32_e32 v245, 2, v245
	v_lshlrev_b32_e32 v246, 2, v246
	v_cndmask_b32_e32 v200, v77, v193, vcc
	v_sub_u32_e32 v245, v245, v246
	v_add_u32_e32 v198, s9, v245
	v_mov_b32_e32 v245, v198
	v_min_u32_e32 v248, 0x7f, v245
	v_lshl_add_u32 v248, v248, 2, v80
	ds_read_b32 v248, v248
	v_subrev_u32_e32 v246, 1, v198
	v_min_u32_e32 v249, 0x7f, v246
	v_lshl_add_u32 v249, v249, 2, v80
	ds_read_b32 v249, v249
	s_waitcnt lgkmcnt(0)
	v_fmamk_f32 v248, v248, 0x3fb8aa3b, v200
	v_cmp_le_i32_e32 vcc, 0, v245
	v_fmamk_f32 v84, v84, 0x3e38aa3b, v248
	s_nop 0
	v_cndmask_b32_e32 v84, v77, v84, vcc
	v_fmamk_f32 v249, v249, 0x3fb8aa3b, v200
	v_cmp_le_i32_e32 vcc, 0, v246
	v_fmamk_f32 v85, v85, 0x3e38aa3b, v249
	s_nop 0
	v_cndmask_b32_e32 v85, v77, v85, vcc
	v_subrev_u32_e32 v245, 2, v198
	v_min_u32_e32 v248, 0x7f, v245
	v_lshl_add_u32 v248, v248, 2, v80
	ds_read_b32 v248, v248
	v_subrev_u32_e32 v246, 3, v198
	v_min_u32_e32 v249, 0x7f, v246
	v_lshl_add_u32 v249, v249, 2, v80
	ds_read_b32 v249, v249
	s_waitcnt lgkmcnt(0)
	v_fmamk_f32 v248, v248, 0x3fb8aa3b, v200
	v_cmp_le_i32_e32 vcc, 0, v245
	v_fmamk_f32 v86, v86, 0x3e38aa3b, v248
	s_nop 0
	v_cndmask_b32_e32 v86, v77, v86, vcc
	v_fmamk_f32 v249, v249, 0x3fb8aa3b, v200
	v_cmp_le_i32_e32 vcc, 0, v246
	v_fmamk_f32 v87, v87, 0x3e38aa3b, v249
	s_nop 0
	v_cndmask_b32_e32 v87, v77, v87, vcc
	v_subrev_u32_e32 v245, 16, v198
	v_min_u32_e32 v248, 0x7f, v245
	v_lshl_add_u32 v248, v248, 2, v80
	ds_read_b32 v248, v248
	v_subrev_u32_e32 v246, 17, v198
	v_min_u32_e32 v249, 0x7f, v246
	v_lshl_add_u32 v249, v249, 2, v80
	ds_read_b32 v249, v249
	s_waitcnt lgkmcnt(0)
	v_fmamk_f32 v248, v248, 0x3fb8aa3b, v200
	v_cmp_le_i32_e32 vcc, 0, v245
	v_fmamk_f32 v88, v88, 0x3e38aa3b, v248
	s_nop 0
	v_cndmask_b32_e32 v88, v77, v88, vcc
	v_fmamk_f32 v249, v249, 0x3fb8aa3b, v200
	v_cmp_le_i32_e32 vcc, 0, v246
	v_fmamk_f32 v89, v89, 0x3e38aa3b, v249
	s_nop 0
	v_cndmask_b32_e32 v89, v77, v89, vcc
	v_subrev_u32_e32 v245, 18, v198
	v_min_u32_e32 v248, 0x7f, v245
	v_lshl_add_u32 v248, v248, 2, v80
	ds_read_b32 v248, v248
	v_subrev_u32_e32 v246, 19, v198
	v_min_u32_e32 v249, 0x7f, v246
	v_lshl_add_u32 v249, v249, 2, v80
	ds_read_b32 v249, v249
	s_waitcnt lgkmcnt(0)
	v_fmamk_f32 v248, v248, 0x3fb8aa3b, v200
	v_cmp_le_i32_e32 vcc, 0, v245
	v_fmamk_f32 v90, v90, 0x3e38aa3b, v248
	s_nop 0
	v_cndmask_b32_e32 v90, v77, v90, vcc
	v_fmamk_f32 v249, v249, 0x3fb8aa3b, v200
	v_cmp_le_i32_e32 vcc, 0, v246
	v_fmamk_f32 v91, v91, 0x3e38aa3b, v249
	s_nop 0
	v_cndmask_b32_e32 v91, v77, v91, vcc
	v_subrev_u32_e32 v245, 32, v198
	v_min_u32_e32 v248, 0x7f, v245
	v_lshl_add_u32 v248, v248, 2, v80
	ds_read_b32 v248, v248
	v_subrev_u32_e32 v246, 33, v198
	v_min_u32_e32 v249, 0x7f, v246
	v_lshl_add_u32 v249, v249, 2, v80
	ds_read_b32 v249, v249
	s_waitcnt lgkmcnt(0)
	v_fmamk_f32 v248, v248, 0x3fb8aa3b, v200
	v_cmp_le_i32_e32 vcc, 0, v245
	v_fmamk_f32 v92, v92, 0x3e38aa3b, v248
	s_nop 0
	v_cndmask_b32_e32 v92, v77, v92, vcc
	v_fmamk_f32 v249, v249, 0x3fb8aa3b, v200
	v_cmp_le_i32_e32 vcc, 0, v246
	v_fmamk_f32 v93, v93, 0x3e38aa3b, v249
	s_nop 0
	v_cndmask_b32_e32 v93, v77, v93, vcc
	v_subrev_u32_e32 v245, 34, v198
	v_min_u32_e32 v248, 0x7f, v245
	v_lshl_add_u32 v248, v248, 2, v80
	ds_read_b32 v248, v248
	v_subrev_u32_e32 v246, 35, v198
	v_min_u32_e32 v249, 0x7f, v246
	v_lshl_add_u32 v249, v249, 2, v80
	ds_read_b32 v249, v249
	s_waitcnt lgkmcnt(0)
	v_fmamk_f32 v248, v248, 0x3fb8aa3b, v200
	v_cmp_le_i32_e32 vcc, 0, v245
	v_fmamk_f32 v94, v94, 0x3e38aa3b, v248
	s_nop 0
	v_cndmask_b32_e32 v94, v77, v94, vcc
	v_fmamk_f32 v249, v249, 0x3fb8aa3b, v200
	v_cmp_le_i32_e32 vcc, 0, v246
	v_fmamk_f32 v95, v95, 0x3e38aa3b, v249
	s_nop 0
	v_cndmask_b32_e32 v95, v77, v95, vcc
	v_subrev_u32_e32 v245, 48, v198
	v_min_u32_e32 v248, 0x7f, v245
	v_lshl_add_u32 v248, v248, 2, v80
	ds_read_b32 v248, v248
	v_subrev_u32_e32 v246, 49, v198
	v_min_u32_e32 v249, 0x7f, v246
	v_lshl_add_u32 v249, v249, 2, v80
	ds_read_b32 v249, v249
	s_waitcnt lgkmcnt(0)
	v_fmamk_f32 v248, v248, 0x3fb8aa3b, v200
	v_cmp_le_i32_e32 vcc, 0, v245
	v_fmamk_f32 v96, v96, 0x3e38aa3b, v248
	s_nop 0
	v_cndmask_b32_e32 v96, v77, v96, vcc
	v_fmamk_f32 v249, v249, 0x3fb8aa3b, v200
	v_cmp_le_i32_e32 vcc, 0, v246
	v_fmamk_f32 v97, v97, 0x3e38aa3b, v249
	s_nop 0
	v_cndmask_b32_e32 v97, v77, v97, vcc
	v_subrev_u32_e32 v245, 50, v198
	v_min_u32_e32 v248, 0x7f, v245
	v_lshl_add_u32 v248, v248, 2, v80
	ds_read_b32 v248, v248
	v_subrev_u32_e32 v246, 51, v198
	v_min_u32_e32 v249, 0x7f, v246
	v_lshl_add_u32 v249, v249, 2, v80
	ds_read_b32 v249, v249
	s_waitcnt lgkmcnt(0)
	v_fmamk_f32 v248, v248, 0x3fb8aa3b, v200
	v_cmp_le_i32_e32 vcc, 0, v245
	v_fmamk_f32 v98, v98, 0x3e38aa3b, v248
	s_nop 0
	v_cndmask_b32_e32 v98, v77, v98, vcc
	v_fmamk_f32 v249, v249, 0x3fb8aa3b, v200
	v_cmp_le_i32_e32 vcc, 0, v246
	v_fmamk_f32 v99, v99, 0x3e38aa3b, v249
	s_nop 0
	v_cndmask_b32_e32 v99, v77, v99, vcc
	s_branch .Lbm3_Ag3_max
.Lbm3_Ag3_skip:
	v_mov_b32_e32 v78, 0
	s_mov_b32 s38, s27
	s_mov_b32 s48, s8
	s_waitcnt lgkmcnt(0)
	v_readfirstlane_b32 s9, v76
	s_add_i32 s35, s35, 1
	s_and_b32 s27, s9, 0xffff
	s_lshr_b32 s8, s9, 16
	s_cmp_lt_i32 s35, s25
	s_cbranch_scc1 .Lbm3_blkB
	s_branch .Lbm3_done
.Lbm3_blkB:
	s_lshl_b32 s29, s27, 12
	s_add_u32 s30, s40, s29
	s_addc_u32 s31, s41, 0
	global_load_dwordx4 v[2:5], v79, s[30:31]
	global_load_dwordx4 v[6:9], v79, s[30:31] offset:1024
	global_load_dwordx4 v[12:15], v79, s[30:31] offset:2048
	global_load_dwordx4 v[16:19], v79, s[30:31] offset:3072
	s_lshl_b32 s29, s27, 12
	s_add_u32 s30, s62, s29
	s_addc_u32 s31, s63, 0
	global_load_dwordx4 v[36:39], v79, s[30:31]
	global_load_dwordx4 v[40:43], v79, s[30:31] offset:1024
	global_load_dwordx4 v[44:47], v79, s[30:31] offset:2048
	global_load_dwordx4 v[48:51], v79, s[30:31] offset:3072
	s_add_i32 s50, s35, 2
	s_add_i32 s9, s25, -1
	s_min_i32 s50, s50, s9
	s_lshl_b32 s9, s50, 2
	s_add_i32 s9, s9, s46
	v_mov_b32_e32 v76, s9
	ds_read_b32 v76, v76 offset:16384
	s_cmp_ge_i32 s38, s21
	s_cselect_b32 s50, 1, 0
	s_bfe_u32 s29, s48, 0x40000
	s_cmp_eq_u32 s29, 0
	s_cbranch_scc1 .Lbm3_Bg0_skip
	s_waitcnt vmcnt(12)
	v_mfma_f32_16x16x32_fp8_fp8 v[84:87], v[20:21], v[164:165], 0
	v_mfma_f32_16x16x32_fp8_fp8 v[88:91], v[24:25], v[164:165], 0
	v_mfma_f32_16x16x32_fp8_fp8 v[92:95], v[28:29], v[164:165], 0
	v_mfma_f32_16x16x32_fp8_fp8 v[96:99], v[32:33], v[164:165], 0
	v_mfma_f32_16x16x32_fp8_fp8 v[84:87], v[22:23], v[166:167], v[84:87]
	v_mfma_f32_16x16x32_fp8_fp8 v[88:91], v[26:27], v[166:167], v[88:91]
	v_mfma_f32_16x16x32_fp8_fp8 v[92:95], v[30:31], v[166:167], v[92:95]
	v_mfma_f32_16x16x32_fp8_fp8 v[96:99], v[34:35], v[166:167], v[96:99]
	v_and_b32_e32 v199, s29, v244
	s_cmp_eq_u32 s50, 1
	v_cmp_ne_u32_e32 vcc, 0, v199
	s_cbranch_scc1 .Lbm3_Bg0_near
	v_add_f32_e32 v200, v81, v190
	v_cndmask_b32_e32 v200, v77, v200, vcc
	v_pk_fma_f32 v[84:85], v[84:85], s[10:11], v[200:201] op_sel_hi:[1,1,0]
	v_pk_fma_f32 v[86:87], v[86:87], s[10:11], v[200:201] op_sel_hi:[1,1,0]
	v_pk_fma_f32 v[88:89], v[88:89], s[10:11], v[200:201] op_sel_hi:[1,1,0]
	v_pk_fma_f32 v[90:91], v[90:91], s[10:11], v[200:201] op_sel_hi:[1,1,0]
	v_pk_fma_f32 v[92:93], v[92:93], s[10:11], v[200:201] op_sel_hi:[1,1,0]
	v_pk_fma_f32 v[94:95], v[94:95], s[10:11], v[200:201] op_sel_hi:[1,1,0]
	v_pk_fma_f32 v[96:97], v[96:97], s[10:11], v[200:201] op_sel_hi:[1,1,0]
	v_pk_fma_f32 v[98:99], v[98:99], s[10:11], v[200:201] op_sel_hi:[1,1,0]

.Lbm3_Bg0_skip:
	s_bfe_u32 s29, s48, 0x40004
	s_cmp_eq_u32 s29, 0
	s_cbranch_scc1 .Lbm3_Bg1_skip
	s_waitcnt vmcnt(12)
	v_mfma_f32_16x16x32_fp8_fp8 v[84:87], v[20:21], v[168:169], 0
	v_mfma_f32_16x16x32_fp8_fp8 v[88:91], v[24:25], v[168:169], 0
	v_mfma_f32_16x16x32_fp8_fp8 v[92:95], v[28:29], v[168:169], 0
	v_mfma_f32_16x16x32_fp8_fp8 v[96:99], v[32:33], v[168:169], 0
	v_mfma_f32_16x16x32_fp8_fp8 v[84:87], v[22:23], v[170:171], v[84:87]
	v_mfma_f32_16x16x32_fp8_fp8 v[88:91], v[26:27], v[170:171], v[88:91]
	v_mfma_f32_16x16x32_fp8_fp8 v[92:95], v[30:31], v[170:171], v[92:95]
	v_mfma_f32_16x16x32_fp8_fp8 v[96:99], v[34:35], v[170:171], v[96:99]
	v_and_b32_e32 v199, s29, v244
	s_cmp_eq_u32 s50, 1
	v_cmp_ne_u32_e32 vcc, 0, v199
	s_cbranch_scc1 .Lbm3_Bg1_near
	v_add_f32_e32 v200, v81, v191
	v_cndmask_b32_e32 v200, v77, v200, vcc
	v_pk_fma_f32 v[84:85], v[84:85], s[10:11], v[200:201] op_sel_hi:[1,1,0]
	v_pk_fma_f32 v[86:87], v[86:87], s[10:11], v[200:201] op_sel_hi:[1,1,0]
	v_pk_fma_f32 v[88:89], v[88:89], s[10:11], v[200:201] op_sel_hi:[1,1,0]
	v_pk_fma_f32 v[90:91], v[90:91], s[10:11], v[200:201] op_sel_hi:[1,1,0]
	v_pk_fma_f32 v[92:93], v[92:93], s[10:11], v[200:201] op_sel_hi:[1,1,0]
	v_pk_fma_f32 v[94:95], v[94:95], s[10:11], v[200:201] op_sel_hi:[1,1,0]
	v_pk_fma_f32 v[96:97], v[96:97], s[10:11], v[200:201] op_sel_hi:[1,1,0]
	v_pk_fma_f32 v[98:99], v[98:99], s[10:11], v[200:201] op_sel_hi:[1,1,0]

.Lbm3_Bg1_skip:
	s_bfe_u32 s29, s48, 0x40008
	s_cmp_eq_u32 s29, 0
	s_cbranch_scc1 .Lbm3_Bg2_skip
	s_waitcnt vmcnt(12)
	v_mfma_f32_16x16x32_fp8_fp8 v[84:87], v[20:21], v[182:183], 0
	v_mfma_f32_16x16x32_fp8_fp8 v[88:91], v[24:25], v[182:183], 0
	v_mfma_f32_16x16x32_fp8_fp8 v[92:95], v[28:29], v[182:183], 0
	v_mfma_f32_16x16x32_fp8_fp8 v[96:99], v[32:33], v[182:183], 0
	v_mfma_f32_16x16x32_fp8_fp8 v[84:87], v[22:23], v[184:185], v[84:87]
	v_mfma_f32_16x16x32_fp8_fp8 v[88:91], v[26:27], v[184:185], v[88:91]
	v_mfma_f32_16x16x32_fp8_fp8 v[92:95], v[30:31], v[184:185], v[92:95]
	v_mfma_f32_16x16x32_fp8_fp8 v[96:99], v[34:35], v[184:185], v[96:99]
	v_and_b32_e32 v199, s29, v244
	s_cmp_eq_u32 s50, 1
	v_cmp_ne_u32_e32 vcc, 0, v199
	s_cbranch_scc1 .Lbm3_Bg2_near
	v_add_f32_e32 v200, v81, v192
	v_cndmask_b32_e32 v200, v77, v200, vcc
	v_pk_fma_f32 v[84:85], v[84:85], s[10:11], v[200:201] op_sel_hi:[1,1,0]
	v_pk_fma_f32 v[86:87], v[86:87], s[10:11], v[200:201] op_sel_hi:[1,1,0]
	v_pk_fma_f32 v[88:89], v[88:89], s[10:11], v[200:201] op_sel_hi:[1,1,0]
	v_pk_fma_f32 v[90:91], v[90:91], s[10:11], v[200:201] op_sel_hi:[1,1,0]
	v_pk_fma_f32 v[92:93], v[92:93], s[10:11], v[200:201] op_sel_hi:[1,1,0]
	v_pk_fma_f32 v[94:95], v[94:95], s[10:11], v[200:201] op_sel_hi:[1,1,0]
	v_pk_fma_f32 v[96:97], v[96:97], s[10:11], v[200:201] op_sel_hi:[1,1,0]
	v_pk_fma_f32 v[98:99], v[98:99], s[10:11], v[200:201] op_sel_hi:[1,1,0]

.Lbm3_Bg2_skip:
	s_bfe_u32 s29, s48, 0x4000c
	s_cmp_eq_u32 s29, 0
	s_cbranch_scc1 .Lbm3_Bg3_skip
	s_waitcnt vmcnt(12)
	v_mfma_f32_16x16x32_fp8_fp8 v[84:87], v[20:21], v[186:187], 0
	v_mfma_f32_16x16x32_fp8_fp8 v[88:91], v[24:25], v[186:187], 0
	v_mfma_f32_16x16x32_fp8_fp8 v[92:95], v[28:29], v[186:187], 0
	v_mfma_f32_16x16x32_fp8_fp8 v[96:99], v[32:33], v[186:187], 0
	v_mfma_f32_16x16x32_fp8_fp8 v[84:87], v[22:23], v[188:189], v[84:87]
	v_mfma_f32_16x16x32_fp8_fp8 v[88:91], v[26:27], v[188:189], v[88:91]
	v_mfma_f32_16x16x32_fp8_fp8 v[92:95], v[30:31], v[188:189], v[92:95]
	v_mfma_f32_16x16x32_fp8_fp8 v[96:99], v[34:35], v[188:189], v[96:99]
	v_and_b32_e32 v199, s29, v244
	s_cmp_eq_u32 s50, 1
	v_cmp_ne_u32_e32 vcc, 0, v199
	s_cbranch_scc1 .Lbm3_Bg3_near
	v_add_f32_e32 v200, v81, v193
	v_cndmask_b32_e32 v200, v77, v200, vcc
	v_pk_fma_f32 v[84:85], v[84:85], s[10:11], v[200:201] op_sel_hi:[1,1,0]
	v_pk_fma_f32 v[86:87], v[86:87], s[10:11], v[200:201] op_sel_hi:[1,1,0]
	v_pk_fma_f32 v[88:89], v[88:89], s[10:11], v[200:201] op_sel_hi:[1,1,0]
	v_pk_fma_f32 v[90:91], v[90:91], s[10:11], v[200:201] op_sel_hi:[1,1,0]
	v_pk_fma_f32 v[92:93], v[92:93], s[10:11], v[200:201] op_sel_hi:[1,1,0]
	v_pk_fma_f32 v[94:95], v[94:95], s[10:11], v[200:201] op_sel_hi:[1,1,0]
	v_pk_fma_f32 v[96:97], v[96:97], s[10:11], v[200:201] op_sel_hi:[1,1,0]
	v_pk_fma_f32 v[98:99], v[98:99], s[10:11], v[200:201] op_sel_hi:[1,1,0]

.Lbm3_done:
	s_waitcnt vmcnt(0)
	v_and_b32_e32 v245, 15, v181
	v_lshrrev_b32_e32 v246, 4, v181
	v_lshrrev_b32_e32 v247, 2, v245
	v_add_u32_e32 v247, s23, v247
	v_lshlrev_b32_e32 v245, 8, v245
	v_lshl_add_u32 v245, v246, 4, v245
	v_add_u32_e32 v200, s46, v245
	v_mad_u64_u32 v[250:251], s[6:7], v247, v213, v[74:75]
	global_load_dword v252, v[250:251], off offset:4
	v_add_u32_e32 v246, 4, v247
	v_mad_u64_u32 v[250:251], s[6:7], v246, v213, v[74:75]
	global_load_dword v253, v[250:251], off offset:4
	v_add_u32_e32 v246, 8, v247
	v_mad_u64_u32 v[250:251], s[6:7], v246, v213, v[74:75]
	global_load_dword v254, v[250:251], off offset:4
	v_add_u32_e32 v246, 12, v247
	v_mad_u64_u32 v[250:251], s[6:7], v246, v213, v[74:75]
	global_load_dword v255, v[250:251], off offset:4
	v_mov_b32_e32 v199, v194
	s_nop 1
	v_permlane16_swap_b32_e32 v194, v199
	s_nop 0
	v_add_f32_e32 v194, v194, v199
	v_mov_b32_e32 v199, v194
	s_nop 1
	v_permlane32_swap_b32_e32 v194, v199
	s_nop 0
	v_add_f32_e32 v194, v194, v199
	v_max_f32_e32 v194, 0xda24260, v194
	v_mov_b32_e32 v199, v195
	s_nop 1
	v_permlane16_swap_b32_e32 v195, v199
	s_nop 0
	v_add_f32_e32 v195, v195, v199
	v_mov_b32_e32 v199, v195
	s_nop 1
	v_permlane32_swap_b32_e32 v195, v199
	s_nop 0
	v_add_f32_e32 v195, v195, v199
	v_max_f32_e32 v195, 0xda24260, v195
	v_mov_b32_e32 v199, v196
	s_nop 1
	v_permlane16_swap_b32_e32 v196, v199
	s_nop 0
	v_add_f32_e32 v196, v196, v199
	v_mov_b32_e32 v199, v196
	s_nop 1
	v_permlane32_swap_b32_e32 v196, v199
	s_nop 0
	v_add_f32_e32 v196, v196, v199
	v_max_f32_e32 v196, 0xda24260, v196
	v_mov_b32_e32 v199, v197
	s_nop 1
	v_permlane16_swap_b32_e32 v197, v199
	s_nop 0
	v_add_f32_e32 v197, v197, v199
	v_mov_b32_e32 v199, v197
	s_nop 1
	v_permlane32_swap_b32_e32 v197, v199
	s_nop 0
	v_add_f32_e32 v197, v197, v199
	v_max_f32_e32 v197, 0xda24260, v197
	s_waitcnt vmcnt(0)
	v_div_scale_f32 v2, s[6:7], v194, v194, v252
	v_rcp_f32_e32 v3, v2
	s_nop 0
	v_fma_f32 v4, -v2, v3, 1.0
	v_fmac_f32_e32 v3, v4, v3
	v_div_scale_f32 v4, vcc, v252, v194, v252
	v_mul_f32_e32 v5, v4, v3
	v_fma_f32 v6, -v2, v5, v4
	v_fmac_f32_e32 v5, v6, v3
	v_fma_f32 v2, -v2, v5, v4
	v_div_fmas_f32 v2, v2, v3, v5
	v_div_fixup_f32 v248, v2, v194, v252
	ds_read_b128 v[16:19], v200 offset:0
	s_waitcnt lgkmcnt(0)
	v_pk_fma_f32 v[100:101], v[100:101], v[248:249], v[16:17] op_sel_hi:[1,0,1]
	v_pk_fma_f32 v[102:103], v[102:103], v[248:249], v[18:19] op_sel_hi:[1,0,1]
	ds_write_b128 v200, v[100:103] offset:0
	ds_read_b128 v[16:19], v200 offset:64
	s_waitcnt lgkmcnt(0)
	v_pk_fma_f32 v[104:105], v[104:105], v[248:249], v[16:17] op_sel_hi:[1,0,1]
	v_pk_fma_f32 v[106:107], v[106:107], v[248:249], v[18:19] op_sel_hi:[1,0,1]
	ds_write_b128 v200, v[104:107] offset:64
	ds_read_b128 v[16:19], v200 offset:128
	s_waitcnt lgkmcnt(0)
	v_pk_fma_f32 v[108:109], v[108:109], v[248:249], v[16:17] op_sel_hi:[1,0,1]
	v_pk_fma_f32 v[110:111], v[110:111], v[248:249], v[18:19] op_sel_hi:[1,0,1]
	ds_write_b128 v200, v[108:111] offset:128
	ds_read_b128 v[16:19], v200 offset:192
	s_waitcnt lgkmcnt(0)
	v_pk_fma_f32 v[112:113], v[112:113], v[248:249], v[16:17] op_sel_hi:[1,0,1]
	v_pk_fma_f32 v[114:115], v[114:115], v[248:249], v[18:19] op_sel_hi:[1,0,1]
	ds_write_b128 v200, v[112:115] offset:192
	v_div_scale_f32 v2, s[6:7], v195, v195, v253
	v_rcp_f32_e32 v3, v2
	s_nop 0
	v_fma_f32 v4, -v2, v3, 1.0
	v_fmac_f32_e32 v3, v4, v3
	v_div_scale_f32 v4, vcc, v253, v195, v253
	v_mul_f32_e32 v5, v4, v3
	v_fma_f32 v6, -v2, v5, v4
	v_fmac_f32_e32 v5, v6, v3
	v_fma_f32 v2, -v2, v5, v4
	v_div_fmas_f32 v2, v2, v3, v5
	v_div_fixup_f32 v248, v2, v195, v253
	ds_read_b128 v[16:19], v200 offset:4096
	s_waitcnt lgkmcnt(0)
	v_pk_fma_f32 v[116:117], v[116:117], v[248:249], v[16:17] op_sel_hi:[1,0,1]
	v_pk_fma_f32 v[118:119], v[118:119], v[248:249], v[18:19] op_sel_hi:[1,0,1]
	ds_write_b128 v200, v[116:119] offset:4096
	ds_read_b128 v[16:19], v200 offset:4160
	s_waitcnt lgkmcnt(0)
	v_pk_fma_f32 v[120:121], v[120:121], v[248:249], v[16:17] op_sel_hi:[1,0,1]
	v_pk_fma_f32 v[122:123], v[122:123], v[248:249], v[18:19] op_sel_hi:[1,0,1]
	ds_write_b128 v200, v[120:123] offset:4160
	ds_read_b128 v[16:19], v200 offset:4224
	s_waitcnt lgkmcnt(0)
	v_pk_fma_f32 v[124:125], v[124:125], v[248:249], v[16:17] op_sel_hi:[1,0,1]
	v_pk_fma_f32 v[126:127], v[126:127], v[248:249], v[18:19] op_sel_hi:[1,0,1]
	ds_write_b128 v200, v[124:127] offset:4224
	ds_read_b128 v[16:19], v200 offset:4288
	s_waitcnt lgkmcnt(0)
	v_pk_fma_f32 v[128:129], v[128:129], v[248:249], v[16:17] op_sel_hi:[1,0,1]
	v_pk_fma_f32 v[130:131], v[130:131], v[248:249], v[18:19] op_sel_hi:[1,0,1]
	ds_write_b128 v200, v[128:131] offset:4288
	v_div_scale_f32 v2, s[6:7], v196, v196, v254
	v_rcp_f32_e32 v3, v2
	s_nop 0
	v_fma_f32 v4, -v2, v3, 1.0
	v_fmac_f32_e32 v3, v4, v3
	v_div_scale_f32 v4, vcc, v254, v196, v254
	v_mul_f32_e32 v5, v4, v3
	v_fma_f32 v6, -v2, v5, v4
	v_fmac_f32_e32 v5, v6, v3
	v_fma_f32 v2, -v2, v5, v4
	v_div_fmas_f32 v2, v2, v3, v5
	v_div_fixup_f32 v248, v2, v196, v254
	ds_read_b128 v[16:19], v200 offset:8192
	s_waitcnt lgkmcnt(0)
	v_pk_fma_f32 v[132:133], v[132:133], v[248:249], v[16:17] op_sel_hi:[1,0,1]
	v_pk_fma_f32 v[134:135], v[134:135], v[248:249], v[18:19] op_sel_hi:[1,0,1]
	ds_write_b128 v200, v[132:135] offset:8192
	ds_read_b128 v[16:19], v200 offset:8256
	s_waitcnt lgkmcnt(0)
	v_pk_fma_f32 v[136:137], v[136:137], v[248:249], v[16:17] op_sel_hi:[1,0,1]
	v_pk_fma_f32 v[138:139], v[138:139], v[248:249], v[18:19] op_sel_hi:[1,0,1]
	ds_write_b128 v200, v[136:139] offset:8256
	ds_read_b128 v[16:19], v200 offset:8320
	s_waitcnt lgkmcnt(0)
	v_pk_fma_f32 v[140:141], v[140:141], v[248:249], v[16:17] op_sel_hi:[1,0,1]
	v_pk_fma_f32 v[142:143], v[142:143], v[248:249], v[18:19] op_sel_hi:[1,0,1]
	ds_write_b128 v200, v[140:143] offset:8320
	ds_read_b128 v[16:19], v200 offset:8384
	s_waitcnt lgkmcnt(0)
	v_pk_fma_f32 v[144:145], v[144:145], v[248:249], v[16:17] op_sel_hi:[1,0,1]
	v_pk_fma_f32 v[146:147], v[146:147], v[248:249], v[18:19] op_sel_hi:[1,0,1]
	ds_write_b128 v200, v[144:147] offset:8384
	v_div_scale_f32 v2, s[6:7], v197, v197, v255
	v_rcp_f32_e32 v3, v2
	s_nop 0
	v_fma_f32 v4, -v2, v3, 1.0
	v_fmac_f32_e32 v3, v4, v3
	v_div_scale_f32 v4, vcc, v255, v197, v255
	v_mul_f32_e32 v5, v4, v3
	v_fma_f32 v6, -v2, v5, v4
	v_fmac_f32_e32 v5, v6, v3
	v_fma_f32 v2, -v2, v5, v4
	v_div_fmas_f32 v2, v2, v3, v5
	v_div_fixup_f32 v248, v2, v197, v255
	ds_read_b128 v[16:19], v200 offset:12288
	s_waitcnt lgkmcnt(0)
	v_pk_fma_f32 v[148:149], v[148:149], v[248:249], v[16:17] op_sel_hi:[1,0,1]
	v_pk_fma_f32 v[150:151], v[150:151], v[248:249], v[18:19] op_sel_hi:[1,0,1]
	ds_write_b128 v200, v[148:151] offset:12288
	ds_read_b128 v[16:19], v200 offset:12352
	s_waitcnt lgkmcnt(0)
	v_pk_fma_f32 v[152:153], v[152:153], v[248:249], v[16:17] op_sel_hi:[1,0,1]
	v_pk_fma_f32 v[154:155], v[154:155], v[248:249], v[18:19] op_sel_hi:[1,0,1]
	ds_write_b128 v200, v[152:155] offset:12352
	ds_read_b128 v[16:19], v200 offset:12416
	s_waitcnt lgkmcnt(0)
	v_pk_fma_f32 v[156:157], v[156:157], v[248:249], v[16:17] op_sel_hi:[1,0,1]
	v_pk_fma_f32 v[158:159], v[158:159], v[248:249], v[18:19] op_sel_hi:[1,0,1]
	ds_write_b128 v200, v[156:159] offset:12416
	ds_read_b128 v[16:19], v200 offset:12480
	s_waitcnt lgkmcnt(0)
	v_pk_fma_f32 v[160:161], v[160:161], v[248:249], v[16:17] op_sel_hi:[1,0,1]
	v_pk_fma_f32 v[162:163], v[162:163], v[248:249], v[18:19] op_sel_hi:[1,0,1]
	ds_write_b128 v200, v[160:163] offset:12480
	s_waitcnt lgkmcnt(0)
	s_branch .LBB0_2088
